# v24 + GEMM K-loops: counter update and exit compare moved above the closing barrier into the MFMA shadow (strategy 7.11 back-edge rotation, 6 loops)
# speedup vs baseline: 1.0076x; 1.0004x over previous
; #define LDA(dst, b, h) for (int m = 0; m < 4; ++m) for (int k = 0; k < 2; ++k) \
;     dst[m][k] = *reinterpret_cast<const bf16x8*>((char*)SA(b, h) + lds_byte(wr * 64 + m * 16 + fr, k * 32 + fq * 8))
; #define LDB(dst, b, h) for (int n = 0; n < 2; ++n) for (int k = 0; k < 2; ++k) \
;     dst[n][k] = *reinterpret_cast<const bf16x8*>((char*)SB(b, h) + lds_byte(wc * 32 + n * 16 + fr, k * 32 + fq * 8))
; #define MMA(ai, bj, At, Bt_) do { __builtin_amdgcn_s_setprio(1); \
;     for (int m = 0; m < 4; ++m) for (int n = 0; n < 2; ++n) for (int k = 0; k < 2; ++k) \
;       acc[ai][bj][m][n] = __builtin_amdgcn_mfma_f32_16x16x32_bf16(Bt_[n][k], At[m][k], acc[ai][bj][m][n], 0, 0, 0); \
;     __builtin_amdgcn_s_setprio(0); } while (0)
; #define WAIT_V(n) asm volatile("s_waitcnt vmcnt(" #n ")" ::: "memory")
; #define WAIT_L(n) asm volatile("s_waitcnt lgkmcnt(" #n ")" ::: "memory")
; #define BAR __builtin_amdgcn_s_barrier()
; #define SCHED __builtin_amdgcn_sched_barrier(0)
; template <int MODE>
; DI void gemm_phase(const bf16_t* __restrict__ A, const bf16_t* __restrict__ Bt, int M, int N, int K, const Epi& ep) {
;     ...
;             LDB(B0, 0, 0); LDB(B1, 0, 1); SCHED; LDA(At, 0, 0); STAGE(SA(1, 1), rsA, brow + HALF, t + 1);
;             WAIT_V(8); WAIT_L(0); BAR; MMA(0, 0, At, B0); MMA(0, 1, At, B1); BAR; SCHED;
;             LDA(At, 0, 1); STAGE(SB(0, 0), rsB, bcol, t + 2); STAGE(SB(0, 1), rsB, bcol + HALF, t + 2); STAGE(SA(0, 0), rsA, brow, t + 2);
.LBB0_91:
	ds_read_b128 v[156:159], v146
	ds_read_b128 v[160:163], v146 offset:1024
	ds_read_b128 v[164:167], v146 offset:2048
	ds_read_b128 v[168:171], v146 offset:3072
	ds_read_b128 v[172:175], v147
	ds_read_b128 v[176:179], v147 offset:1024
	ds_read_b128 v[180:183], v147 offset:2048
	ds_read_b128 v[184:187], v147 offset:3072
	s_add_i32 s41, s0, s40
	v_readfirstlane_b32 s7, v144
	s_add_i32 s6, s41, 0x40080
	s_mov_b32 m0, s7
	v_readfirstlane_b32 s7, v145
	ds_read_b128 v[188:191], v148
	ds_read_b128 v[192:195], v148 offset:1024
	ds_read_b128 v[196:199], v149
	ds_read_b128 v[200:203], v149 offset:1024
	ds_read_b128 v[204:207], v150
	ds_read_b128 v[208:211], v150 offset:1024
	ds_read_b128 v[214:217], v151
	ds_read_b128 v[218:221], v151 offset:1024
	buffer_load_dwordx4 v128, s[8:11], s6 offen lds
	s_mov_b32 m0, s7
	s_nop 0
	buffer_load_dwordx4 v129, s[8:11], s6 offen lds
	s_waitcnt vmcnt(8)
	s_waitcnt lgkmcnt(0)
	s_barrier
	s_setprio 1
	s_waitcnt lgkmcnt(7)
	v_mfma_f32_16x16x32_bf16 v[124:127], v[156:159], v[188:191], v[124:127]
	v_mfma_f32_16x16x32_bf16 v[120:123], v[164:167], v[188:191], v[120:123]
	s_waitcnt lgkmcnt(5)
	v_mfma_f32_16x16x32_bf16 v[116:119], v[156:159], v[196:199], v[116:119]
	v_mfma_f32_16x16x32_bf16 v[112:115], v[164:167], v[196:199], v[112:115]
	s_waitcnt lgkmcnt(3)
	v_mfma_f32_16x16x32_bf16 v[108:111], v[156:159], v[204:207], v[108:111]
	v_mfma_f32_16x16x32_bf16 v[104:107], v[164:167], v[204:207], v[104:107]
	s_waitcnt lgkmcnt(1)
	v_mfma_f32_16x16x32_bf16 v[100:103], v[156:159], v[214:217], v[100:103]
	v_mfma_f32_16x16x32_bf16 v[96:99], v[164:167], v[214:217], v[96:99]
	v_mfma_f32_16x16x32_bf16 v[124:127], v[160:163], v[192:195], v[124:127]
	v_mfma_f32_16x16x32_bf16 v[120:123], v[168:171], v[192:195], v[120:123]
	v_mfma_f32_16x16x32_bf16 v[116:119], v[160:163], v[200:203], v[116:119]
	v_mfma_f32_16x16x32_bf16 v[112:115], v[168:171], v[200:203], v[112:115]
	v_mfma_f32_16x16x32_bf16 v[108:111], v[160:163], v[208:211], v[108:111]
	v_mfma_f32_16x16x32_bf16 v[104:107], v[168:171], v[208:211], v[104:107]
	s_waitcnt lgkmcnt(0)
	v_mfma_f32_16x16x32_bf16 v[100:103], v[160:163], v[218:221], v[100:103]
	v_mfma_f32_16x16x32_bf16 v[96:99], v[168:171], v[218:221], v[96:99]
	s_setprio 0
	s_setprio 1
	v_mfma_f32_16x16x32_bf16 v[92:95], v[172:175], v[188:191], v[92:95]
	v_mfma_f32_16x16x32_bf16 v[88:91], v[180:183], v[188:191], v[88:91]
	v_mfma_f32_16x16x32_bf16 v[84:87], v[172:175], v[196:199], v[84:87]
	v_mfma_f32_16x16x32_bf16 v[80:83], v[180:183], v[196:199], v[80:83]
	v_mfma_f32_16x16x32_bf16 v[76:79], v[172:175], v[204:207], v[76:79]
	v_mfma_f32_16x16x32_bf16 v[72:75], v[180:183], v[204:207], v[72:75]
	v_mfma_f32_16x16x32_bf16 v[68:71], v[172:175], v[214:217], v[68:71]
	v_mfma_f32_16x16x32_bf16 v[64:67], v[180:183], v[214:217], v[64:67]
	v_mfma_f32_16x16x32_bf16 v[92:95], v[176:179], v[192:195], v[92:95]
	v_mfma_f32_16x16x32_bf16 v[88:91], v[184:187], v[192:195], v[88:91]
	v_mfma_f32_16x16x32_bf16 v[84:87], v[176:179], v[200:203], v[84:87]
	v_mfma_f32_16x16x32_bf16 v[80:83], v[184:187], v[200:203], v[80:83]
	v_mfma_f32_16x16x32_bf16 v[76:79], v[176:179], v[208:211], v[76:79]
	v_mfma_f32_16x16x32_bf16 v[72:75], v[184:187], v[208:211], v[72:75]
	v_mfma_f32_16x16x32_bf16 v[68:71], v[176:179], v[218:221], v[68:71]
	v_mfma_f32_16x16x32_bf16 v[64:67], v[184:187], v[218:221], v[64:67]
	s_setprio 0
	s_barrier
	s_add_i32 s42, s1, s40
	v_readfirstlane_b32 s44, v130
	s_add_i32 s43, s42, 0x100
	s_mov_b32 s6, s10
	s_mov_b32 s7, s11
	s_mov_b32 m0, s44
	v_readfirstlane_b32 s44, v131
	ds_read_b128 v[188:191], v148 offset:16384
	ds_read_b128 v[192:195], v148 offset:17408
	ds_read_b128 v[196:199], v149 offset:16384
	ds_read_b128 v[200:203], v149 offset:17408
	ds_read_b128 v[204:207], v150 offset:16384
	ds_read_b128 v[208:211], v150 offset:17408
	ds_read_b128 v[214:217], v151 offset:16384
	ds_read_b128 v[218:221], v151 offset:17408
	buffer_load_dwordx4 v128, s[4:7], s43 offen lds
	s_mov_b32 m0, s44
	v_readfirstlane_b32 s44, v132
	buffer_load_dwordx4 v129, s[4:7], s43 offen lds
	s_add_i32 s43, s42, 0x40100
	s_mov_b32 m0, s44
	v_readfirstlane_b32 s44, v133
	buffer_load_dwordx4 v128, s[4:7], s43 offen lds
	s_mov_b32 m0, s44
	v_readfirstlane_b32 s44, v134
	buffer_load_dwordx4 v129, s[4:7], s43 offen lds
	s_add_i32 s43, s41, 0x100
	s_mov_b32 m0, s44
	v_readfirstlane_b32 s44, v135
	buffer_load_dwordx4 v128, s[8:11], s43 offen lds
	s_mov_b32 m0, s44
	s_nop 0
	buffer_load_dwordx4 v129, s[8:11], s43 offen lds
	s_waitcnt vmcnt(8)
	s_waitcnt lgkmcnt(0)
	s_barrier
; #define LDA(dst, b, h) for (int m = 0; m < 4; ++m) for (int k = 0; k < 2; ++k) \
;     dst[m][k] = *reinterpret_cast<const bf16x8*>((char*)SA(b, h) + lds_byte(wr * 64 + m * 16 + fr, k * 32 + fq * 8))
; #define LDB(dst, b, h) for (int n = 0; n < 2; ++n) for (int k = 0; k < 2; ++k) \
;     dst[n][k] = *reinterpret_cast<const bf16x8*>((char*)SB(b, h) + lds_byte(wc * 32 + n * 16 + fr, k * 32 + fq * 8))
; #define MMA(ai, bj, At, Bt_) do { __builtin_amdgcn_s_setprio(1); \
;     for (int m = 0; m < 4; ++m) for (int n = 0; n < 2; ++n) for (int k = 0; k < 2; ++k) \
;       acc[ai][bj][m][n] = __builtin_amdgcn_mfma_f32_16x16x32_bf16(Bt_[n][k], At[m][k], acc[ai][bj][m][n], 0, 0, 0); \
;     __builtin_amdgcn_s_setprio(0); } while (0)
; #define WAIT_V(n) asm volatile("s_waitcnt vmcnt(" #n ")" ::: "memory")
; #define WAIT_L(n) asm volatile("s_waitcnt lgkmcnt(" #n ")" ::: "memory")
; #define BAR __builtin_amdgcn_s_barrier()
; #define SCHED __builtin_amdgcn_sched_barrier(0)
; template <int MODE>
; DI void gemm_phase(const bf16_t* __restrict__ A, const bf16_t* __restrict__ Bt, int M, int N, int K, const Epi& ep) {
;     ...
;             WAIT_V(8); WAIT_L(0); BAR; MMA(1, 0, At, B0); MMA(1, 1, At, B1); BAR; SCHED;
;             LDB(B0, 1, 0); LDB(B1, 1, 1); SCHED; LDA(At, 1, 0); STAGE(SA(0, 1), rsA, brow + HALF, t + 2);
;             WAIT_V(8); WAIT_L(0); BAR; MMA(0, 0, At, B0); MMA(0, 1, At, B1); BAR; SCHED;
	s_setprio 1
	s_waitcnt lgkmcnt(7)
	v_mfma_f32_16x16x32_bf16 v[60:63], v[156:159], v[188:191], v[60:63]
	v_mfma_f32_16x16x32_bf16 v[56:59], v[164:167], v[188:191], v[56:59]
	s_waitcnt lgkmcnt(5)
	v_mfma_f32_16x16x32_bf16 v[52:55], v[156:159], v[196:199], v[52:55]
	v_mfma_f32_16x16x32_bf16 v[48:51], v[164:167], v[196:199], v[48:51]
	s_waitcnt lgkmcnt(3)
	v_mfma_f32_16x16x32_bf16 v[44:47], v[156:159], v[204:207], v[44:47]
	v_mfma_f32_16x16x32_bf16 v[40:43], v[164:167], v[204:207], v[40:43]
	s_waitcnt lgkmcnt(1)
	v_mfma_f32_16x16x32_bf16 v[36:39], v[156:159], v[214:217], v[36:39]
	v_mfma_f32_16x16x32_bf16 v[32:35], v[164:167], v[214:217], v[32:35]
	v_mfma_f32_16x16x32_bf16 v[60:63], v[160:163], v[192:195], v[60:63]
	v_mfma_f32_16x16x32_bf16 v[56:59], v[168:171], v[192:195], v[56:59]
	v_mfma_f32_16x16x32_bf16 v[52:55], v[160:163], v[200:203], v[52:55]
	v_mfma_f32_16x16x32_bf16 v[48:51], v[168:171], v[200:203], v[48:51]
	v_mfma_f32_16x16x32_bf16 v[44:47], v[160:163], v[208:211], v[44:47]
	v_mfma_f32_16x16x32_bf16 v[40:43], v[168:171], v[208:211], v[40:43]
	s_waitcnt lgkmcnt(0)
	v_mfma_f32_16x16x32_bf16 v[36:39], v[160:163], v[218:221], v[36:39]
	v_mfma_f32_16x16x32_bf16 v[32:35], v[168:171], v[218:221], v[32:35]
	s_setprio 0
	s_setprio 1
	v_mfma_f32_16x16x32_bf16 v[28:31], v[172:175], v[188:191], v[28:31]
	v_mfma_f32_16x16x32_bf16 v[24:27], v[180:183], v[188:191], v[24:27]
	v_mfma_f32_16x16x32_bf16 v[20:23], v[172:175], v[196:199], v[20:23]
	v_mfma_f32_16x16x32_bf16 v[16:19], v[180:183], v[196:199], v[16:19]
	v_mfma_f32_16x16x32_bf16 v[12:15], v[172:175], v[204:207], v[12:15]
	v_mfma_f32_16x16x32_bf16 v[8:11], v[180:183], v[204:207], v[8:11]
	v_mfma_f32_16x16x32_bf16 v[4:7], v[172:175], v[214:217], v[4:7]
	v_mfma_f32_16x16x32_bf16 v[0:3], v[180:183], v[214:217], v[0:3]
	v_mfma_f32_16x16x32_bf16 v[28:31], v[176:179], v[192:195], v[28:31]
	v_mfma_f32_16x16x32_bf16 v[24:27], v[184:187], v[192:195], v[24:27]
	v_mfma_f32_16x16x32_bf16 v[20:23], v[176:179], v[200:203], v[20:23]
	v_mfma_f32_16x16x32_bf16 v[16:19], v[184:187], v[200:203], v[16:19]
	v_mfma_f32_16x16x32_bf16 v[12:15], v[176:179], v[208:211], v[12:15]
	v_mfma_f32_16x16x32_bf16 v[8:11], v[184:187], v[208:211], v[8:11]
	v_mfma_f32_16x16x32_bf16 v[4:7], v[176:179], v[218:221], v[4:7]
	v_mfma_f32_16x16x32_bf16 v[0:3], v[184:187], v[218:221], v[0:3]
	s_setprio 0
	s_barrier
	ds_read_b128 v[156:159], v152
	ds_read_b128 v[160:163], v152 offset:1024
	ds_read_b128 v[164:167], v152 offset:2048
	ds_read_b128 v[168:171], v152 offset:3072
	ds_read_b128 v[172:175], v153
	ds_read_b128 v[176:179], v153 offset:1024
	ds_read_b128 v[180:183], v153 offset:2048
	ds_read_b128 v[184:187], v153 offset:3072
	v_readfirstlane_b32 s44, v136
	s_add_i32 s43, s41, 0x40100
	s_mov_b32 m0, s44
	v_readfirstlane_b32 s44, v137
	ds_read_b128 v[188:191], v148 offset:32768
	ds_read_b128 v[192:195], v148 offset:33792
	ds_read_b128 v[196:199], v149 offset:32768
	ds_read_b128 v[200:203], v149 offset:33792
	ds_read_b128 v[204:207], v150 offset:32768
	ds_read_b128 v[208:211], v150 offset:33792
	ds_read_b128 v[214:217], v151 offset:32768
	ds_read_b128 v[218:221], v151 offset:33792
	buffer_load_dwordx4 v128, s[8:11], s43 offen lds
	s_mov_b32 m0, s44
	s_nop 0
	buffer_load_dwordx4 v129, s[8:11], s43 offen lds
	s_waitcnt vmcnt(8)
	s_waitcnt lgkmcnt(0)
	s_barrier
	s_setprio 1
	s_waitcnt lgkmcnt(7)
	v_mfma_f32_16x16x32_bf16 v[124:127], v[156:159], v[188:191], v[124:127]
	v_mfma_f32_16x16x32_bf16 v[120:123], v[164:167], v[188:191], v[120:123]
	s_waitcnt lgkmcnt(5)
	v_mfma_f32_16x16x32_bf16 v[116:119], v[156:159], v[196:199], v[116:119]
	v_mfma_f32_16x16x32_bf16 v[112:115], v[164:167], v[196:199], v[112:115]
	s_waitcnt lgkmcnt(3)
	v_mfma_f32_16x16x32_bf16 v[108:111], v[156:159], v[204:207], v[108:111]
	v_mfma_f32_16x16x32_bf16 v[104:107], v[164:167], v[204:207], v[104:107]
	s_waitcnt lgkmcnt(1)
	v_mfma_f32_16x16x32_bf16 v[100:103], v[156:159], v[214:217], v[100:103]
	v_mfma_f32_16x16x32_bf16 v[96:99], v[164:167], v[214:217], v[96:99]
	v_mfma_f32_16x16x32_bf16 v[124:127], v[160:163], v[192:195], v[124:127]
	v_mfma_f32_16x16x32_bf16 v[120:123], v[168:171], v[192:195], v[120:123]
	v_mfma_f32_16x16x32_bf16 v[116:119], v[160:163], v[200:203], v[116:119]
	v_mfma_f32_16x16x32_bf16 v[112:115], v[168:171], v[200:203], v[112:115]
	v_mfma_f32_16x16x32_bf16 v[108:111], v[160:163], v[208:211], v[108:111]
	v_mfma_f32_16x16x32_bf16 v[104:107], v[168:171], v[208:211], v[104:107]
	s_waitcnt lgkmcnt(0)
	v_mfma_f32_16x16x32_bf16 v[100:103], v[160:163], v[218:221], v[100:103]
	v_mfma_f32_16x16x32_bf16 v[96:99], v[168:171], v[218:221], v[96:99]
	s_setprio 0
	s_setprio 1
	v_mfma_f32_16x16x32_bf16 v[92:95], v[172:175], v[188:191], v[92:95]
	v_mfma_f32_16x16x32_bf16 v[88:91], v[180:183], v[188:191], v[88:91]
	v_mfma_f32_16x16x32_bf16 v[84:87], v[172:175], v[196:199], v[84:87]
	v_mfma_f32_16x16x32_bf16 v[80:83], v[180:183], v[196:199], v[80:83]
	v_mfma_f32_16x16x32_bf16 v[76:79], v[172:175], v[204:207], v[76:79]
	v_mfma_f32_16x16x32_bf16 v[72:75], v[180:183], v[204:207], v[72:75]
	v_mfma_f32_16x16x32_bf16 v[68:71], v[172:175], v[214:217], v[68:71]
	v_mfma_f32_16x16x32_bf16 v[64:67], v[180:183], v[214:217], v[64:67]
	v_mfma_f32_16x16x32_bf16 v[92:95], v[176:179], v[192:195], v[92:95]
	v_mfma_f32_16x16x32_bf16 v[88:91], v[184:187], v[192:195], v[88:91]
	v_mfma_f32_16x16x32_bf16 v[84:87], v[176:179], v[200:203], v[84:87]
	v_mfma_f32_16x16x32_bf16 v[80:83], v[184:187], v[200:203], v[80:83]
	v_mfma_f32_16x16x32_bf16 v[76:79], v[176:179], v[208:211], v[76:79]
	v_mfma_f32_16x16x32_bf16 v[72:75], v[184:187], v[208:211], v[72:75]
	v_mfma_f32_16x16x32_bf16 v[68:71], v[176:179], v[218:221], v[68:71]
	v_mfma_f32_16x16x32_bf16 v[64:67], v[184:187], v[218:221], v[64:67]
	s_setprio 0
	s_barrier
; #define LDA(dst, b, h) for (int m = 0; m < 4; ++m) for (int k = 0; k < 2; ++k) \
;     dst[m][k] = *reinterpret_cast<const bf16x8*>((char*)SA(b, h) + lds_byte(wr * 64 + m * 16 + fr, k * 32 + fq * 8))
; #define LDB(dst, b, h) for (int n = 0; n < 2; ++n) for (int k = 0; k < 2; ++k) \
;     dst[n][k] = *reinterpret_cast<const bf16x8*>((char*)SB(b, h) + lds_byte(wc * 32 + n * 16 + fr, k * 32 + fq * 8))
; #define MMA(ai, bj, At, Bt_) do { __builtin_amdgcn_s_setprio(1); \
;     for (int m = 0; m < 4; ++m) for (int n = 0; n < 2; ++n) for (int k = 0; k < 2; ++k) \
;       acc[ai][bj][m][n] = __builtin_amdgcn_mfma_f32_16x16x32_bf16(Bt_[n][k], At[m][k], acc[ai][bj][m][n], 0, 0, 0); \
;     __builtin_amdgcn_s_setprio(0); } while (0)
; #define WAIT_V(n) asm volatile("s_waitcnt vmcnt(" #n ")" ::: "memory")
; #define WAIT_L(n) asm volatile("s_waitcnt lgkmcnt(" #n ")" ::: "memory")
; #define BAR __builtin_amdgcn_s_barrier()
; #define SCHED __builtin_amdgcn_sched_barrier(0)
; template <int MODE>
; DI void gemm_phase(const bf16_t* __restrict__ A, const bf16_t* __restrict__ Bt, int M, int N, int K, const Epi& ep) {
;     ...
;             LDA(At, 1, 1); STAGE(SB(1, 0), rsB, bcol, t + 3); STAGE(SB(1, 1), rsB, bcol + HALF, t + 3); STAGE(SA(1, 0), rsA, brow, t + 3);
;             WAIT_V(8); WAIT_L(0); BAR; MMA(1, 0, At, B0); MMA(1, 1, At, B1); BAR; SCHED;
;         }
;         {
;             LDB(B0, 0, 0); LDB(B1, 0, 1); SCHED; LDA(At, 0, 0); STAGE(SA(1, 1), rsA, brow + HALF, nt - 1);
;             WAIT_V(8); WAIT_L(0); BAR; MMA(0, 0, At, B0); MMA(0, 1, At, B1); BAR; SCHED;
	v_readfirstlane_b32 s44, v138
	s_add_i32 s43, s42, 0x180
	s_mov_b32 m0, s44
	v_readfirstlane_b32 s44, v139
	ds_read_b128 v[188:191], v148 offset:49152
	ds_read_b128 v[192:195], v148 offset:50176
	ds_read_b128 v[196:199], v149 offset:49152
	ds_read_b128 v[200:203], v149 offset:50176
	ds_read_b128 v[204:207], v150 offset:49152
	ds_read_b128 v[208:211], v150 offset:50176
	ds_read_b128 v[214:217], v151 offset:49152
	ds_read_b128 v[218:221], v151 offset:50176
	buffer_load_dwordx4 v128, s[4:7], s43 offen lds
	s_mov_b32 m0, s44
	s_add_i32 s42, s42, 0x40180
	buffer_load_dwordx4 v129, s[4:7], s43 offen lds
	v_readfirstlane_b32 s43, v142
	s_mov_b32 m0, s43
	v_readfirstlane_b32 s43, v143
	buffer_load_dwordx4 v128, s[4:7], s42 offen lds
	s_mov_b32 m0, s43
	s_addk_i32 s41, 0x180
	buffer_load_dwordx4 v129, s[4:7], s42 offen lds
	v_readfirstlane_b32 s6, v140
	s_mov_b32 m0, s6
	v_readfirstlane_b32 s6, v141
	buffer_load_dwordx4 v128, s[8:11], s41 offen lds
	s_mov_b32 m0, s6
	s_nop 0
	buffer_load_dwordx4 v129, s[8:11], s41 offen lds
	s_waitcnt vmcnt(8)
	s_waitcnt lgkmcnt(0)
	s_barrier
	s_setprio 1
	s_waitcnt lgkmcnt(7)
	v_mfma_f32_16x16x32_bf16 v[60:63], v[156:159], v[188:191], v[60:63]
	v_mfma_f32_16x16x32_bf16 v[56:59], v[164:167], v[188:191], v[56:59]
	s_waitcnt lgkmcnt(5)
	v_mfma_f32_16x16x32_bf16 v[52:55], v[156:159], v[196:199], v[52:55]
	v_mfma_f32_16x16x32_bf16 v[48:51], v[164:167], v[196:199], v[48:51]
	s_waitcnt lgkmcnt(3)
	v_mfma_f32_16x16x32_bf16 v[44:47], v[156:159], v[204:207], v[44:47]
	v_mfma_f32_16x16x32_bf16 v[40:43], v[164:167], v[204:207], v[40:43]
	s_waitcnt lgkmcnt(1)
	v_mfma_f32_16x16x32_bf16 v[36:39], v[156:159], v[214:217], v[36:39]
	v_mfma_f32_16x16x32_bf16 v[32:35], v[164:167], v[214:217], v[32:35]
	v_mfma_f32_16x16x32_bf16 v[60:63], v[160:163], v[192:195], v[60:63]
	v_mfma_f32_16x16x32_bf16 v[56:59], v[168:171], v[192:195], v[56:59]
	v_mfma_f32_16x16x32_bf16 v[52:55], v[160:163], v[200:203], v[52:55]
	v_mfma_f32_16x16x32_bf16 v[48:51], v[168:171], v[200:203], v[48:51]
	v_mfma_f32_16x16x32_bf16 v[44:47], v[160:163], v[208:211], v[44:47]
	v_mfma_f32_16x16x32_bf16 v[40:43], v[168:171], v[208:211], v[40:43]
	s_waitcnt lgkmcnt(0)
	v_mfma_f32_16x16x32_bf16 v[36:39], v[160:163], v[218:221], v[36:39]
	v_mfma_f32_16x16x32_bf16 v[32:35], v[168:171], v[218:221], v[32:35]
	s_setprio 0
	s_setprio 1
	v_mfma_f32_16x16x32_bf16 v[28:31], v[172:175], v[188:191], v[28:31]
	v_mfma_f32_16x16x32_bf16 v[24:27], v[180:183], v[188:191], v[24:27]
	v_mfma_f32_16x16x32_bf16 v[20:23], v[172:175], v[196:199], v[20:23]
	v_mfma_f32_16x16x32_bf16 v[16:19], v[180:183], v[196:199], v[16:19]
	v_mfma_f32_16x16x32_bf16 v[12:15], v[172:175], v[204:207], v[12:15]
	v_mfma_f32_16x16x32_bf16 v[8:11], v[180:183], v[204:207], v[8:11]
	v_mfma_f32_16x16x32_bf16 v[4:7], v[172:175], v[214:217], v[4:7]
	v_mfma_f32_16x16x32_bf16 v[0:3], v[180:183], v[214:217], v[0:3]
	v_mfma_f32_16x16x32_bf16 v[28:31], v[176:179], v[192:195], v[28:31]
	v_mfma_f32_16x16x32_bf16 v[24:27], v[184:187], v[192:195], v[24:27]
	v_mfma_f32_16x16x32_bf16 v[20:23], v[176:179], v[200:203], v[20:23]
	v_mfma_f32_16x16x32_bf16 v[16:19], v[184:187], v[200:203], v[16:19]
	v_mfma_f32_16x16x32_bf16 v[12:15], v[176:179], v[208:211], v[12:15]
	v_mfma_f32_16x16x32_bf16 v[8:11], v[184:187], v[208:211], v[8:11]
	v_mfma_f32_16x16x32_bf16 v[4:7], v[176:179], v[218:221], v[4:7]
	v_mfma_f32_16x16x32_bf16 v[0:3], v[184:187], v[218:221], v[0:3]
	s_add_i32 s31, s31, 2
	s_addk_i32 s40, 0x100
	s_cmp_lt_u32 s31, 12
	s_setprio 0
	s_barrier
	s_cbranch_scc1 .LBB0_91
	ds_read_b128 v[156:159], v146
	ds_read_b128 v[160:163], v146 offset:1024
	ds_read_b128 v[164:167], v146 offset:2048
	ds_read_b128 v[168:171], v146 offset:3072
	ds_read_b128 v[172:175], v147
	ds_read_b128 v[176:179], v147 offset:1024
	ds_read_b128 v[180:183], v147 offset:2048
	ds_read_b128 v[184:187], v147 offset:3072
	v_readfirstlane_b32 s1, v144
	s_or_b32 s0, s30, 0x40780
	s_mov_b32 m0, s1
	v_readfirstlane_b32 s1, v145
	ds_read_b128 v[188:191], v148
	ds_read_b128 v[192:195], v148 offset:1024
	ds_read_b128 v[196:199], v149
	ds_read_b128 v[200:203], v149 offset:1024
	ds_read_b128 v[204:207], v150
	ds_read_b128 v[208:211], v150 offset:1024
	ds_read_b128 v[214:217], v151
	ds_read_b128 v[218:221], v151 offset:1024
	buffer_load_dwordx4 v128, s[8:11], s0 offen lds
	s_mov_b32 m0, s1
	s_nop 0
	buffer_load_dwordx4 v129, s[8:11], s0 offen lds
	s_waitcnt vmcnt(8)
	s_waitcnt lgkmcnt(0)
	s_barrier
; #define LDA(dst, b, h) for (int m = 0; m < 4; ++m) for (int k = 0; k < 2; ++k) \
;     dst[m][k] = *reinterpret_cast<const bf16x8*>((char*)SA(b, h) + lds_byte(wr * 64 + m * 16 + fr, k * 32 + fq * 8))
; #define MMA(ai, bj, At, Bt_) do { __builtin_amdgcn_s_setprio(1); \
;     for (int m = 0; m < 4; ++m) for (int n = 0; n < 2; ++n) for (int k = 0; k < 2; ++k) \
;       acc[ai][bj][m][n] = __builtin_amdgcn_mfma_f32_16x16x32_bf16(Bt_[n][k], At[m][k], acc[ai][bj][m][n], 0, 0, 0); \
;     __builtin_amdgcn_s_setprio(0); } while (0)
; #define WAIT_V(n) asm volatile("s_waitcnt vmcnt(" #n ")" ::: "memory")
; #define WAIT_L(n) asm volatile("s_waitcnt lgkmcnt(" #n ")" ::: "memory")
; #define BAR __builtin_amdgcn_s_barrier()
; #define SCHED __builtin_amdgcn_sched_barrier(0)
; template <int MODE>
; DI void gemm_phase(const bf16_t* __restrict__ A, const bf16_t* __restrict__ Bt, int M, int N, int K, const Epi& ep) {
;     ...
;             WAIT_V(8); WAIT_L(0); BAR; MMA(0, 0, At, B0); MMA(0, 1, At, B1); BAR; SCHED;
;             LDA(At, 0, 1);
;             WAIT_V(2); WAIT_L(0); BAR; MMA(1, 0, At, B0); MMA(1, 1, At, B1); BAR; SCHED;
	s_setprio 1
	s_waitcnt lgkmcnt(7)
	v_mfma_f32_16x16x32_bf16 v[124:127], v[156:159], v[188:191], v[124:127]
	v_mfma_f32_16x16x32_bf16 v[120:123], v[164:167], v[188:191], v[120:123]
	s_waitcnt lgkmcnt(5)
	v_mfma_f32_16x16x32_bf16 v[116:119], v[156:159], v[196:199], v[116:119]
	v_mfma_f32_16x16x32_bf16 v[112:115], v[164:167], v[196:199], v[112:115]
	s_waitcnt lgkmcnt(3)
	v_mfma_f32_16x16x32_bf16 v[108:111], v[156:159], v[204:207], v[108:111]
	v_mfma_f32_16x16x32_bf16 v[124:127], v[160:163], v[192:195], v[124:127]
	v_mfma_f32_16x16x32_bf16 v[120:123], v[168:171], v[192:195], v[120:123]
	v_mfma_f32_16x16x32_bf16 v[116:119], v[160:163], v[200:203], v[116:119]
	v_mfma_f32_16x16x32_bf16 v[112:115], v[168:171], v[200:203], v[112:115]
	s_waitcnt lgkmcnt(2)
	v_mfma_f32_16x16x32_bf16 v[222:225], v[160:163], v[208:211], v[108:111]
	v_mfma_f32_16x16x32_bf16 v[104:107], v[164:167], v[204:207], v[104:107]
	s_waitcnt lgkmcnt(1)
	v_mfma_f32_16x16x32_bf16 v[100:103], v[156:159], v[214:217], v[100:103]
	v_mfma_f32_16x16x32_bf16 v[96:99], v[164:167], v[214:217], v[96:99]
	v_mfma_f32_16x16x32_bf16 v[226:229], v[168:171], v[208:211], v[104:107]
	s_waitcnt lgkmcnt(0)
	v_mfma_f32_16x16x32_bf16 v[230:233], v[160:163], v[218:221], v[100:103]
	v_mfma_f32_16x16x32_bf16 v[234:237], v[168:171], v[218:221], v[96:99]
	s_setprio 0
	s_setprio 1
	v_mfma_f32_16x16x32_bf16 v[92:95], v[172:175], v[188:191], v[92:95]
	v_mfma_f32_16x16x32_bf16 v[88:91], v[180:183], v[188:191], v[88:91]
	v_mfma_f32_16x16x32_bf16 v[84:87], v[172:175], v[196:199], v[84:87]
	v_mfma_f32_16x16x32_bf16 v[80:83], v[180:183], v[196:199], v[80:83]
	v_mfma_f32_16x16x32_bf16 v[92:95], v[176:179], v[192:195], v[92:95]
	v_mfma_f32_16x16x32_bf16 v[88:91], v[184:187], v[192:195], v[88:91]
	v_mfma_f32_16x16x32_bf16 v[84:87], v[176:179], v[200:203], v[84:87]
	v_mfma_f32_16x16x32_bf16 v[80:83], v[184:187], v[200:203], v[80:83]
	v_mfma_f32_16x16x32_bf16 v[76:79], v[172:175], v[204:207], v[76:79]
	v_mfma_f32_16x16x32_bf16 v[72:75], v[180:183], v[204:207], v[72:75]
	v_mfma_f32_16x16x32_bf16 v[68:71], v[172:175], v[214:217], v[68:71]
	v_mfma_f32_16x16x32_bf16 v[64:67], v[180:183], v[214:217], v[64:67]
	v_mfma_f32_16x16x32_bf16 v[188:191], v[176:179], v[208:211], v[76:79]
	v_mfma_f32_16x16x32_bf16 v[192:195], v[184:187], v[208:211], v[72:75]
	v_mfma_f32_16x16x32_bf16 v[196:199], v[176:179], v[218:221], v[68:71]
	v_mfma_f32_16x16x32_bf16 v[200:203], v[184:187], v[218:221], v[64:67]
	s_setprio 0
	s_barrier
	s_nop 1
	ds_read_b128 v[64:67], v148 offset:16384
	ds_read_b128 v[68:71], v148 offset:17408
	ds_read_b128 v[72:75], v149 offset:16384
	ds_read_b128 v[76:79], v149 offset:17408
	ds_read_b128 v[96:99], v150 offset:16384
	ds_read_b128 v[100:103], v150 offset:17408
	ds_read_b128 v[104:107], v151 offset:16384
	ds_read_b128 v[108:111], v151 offset:17408
	s_waitcnt vmcnt(2)
	s_waitcnt lgkmcnt(0)
	s_barrier
	s_setprio 1
	s_waitcnt lgkmcnt(7)
	v_mfma_f32_16x16x32_bf16 v[60:63], v[156:159], v[64:67], v[60:63]
	v_mfma_f32_16x16x32_bf16 v[56:59], v[164:167], v[64:67], v[56:59]
	s_waitcnt lgkmcnt(5)
	v_mfma_f32_16x16x32_bf16 v[52:55], v[156:159], v[72:75], v[52:55]
	v_mfma_f32_16x16x32_bf16 v[48:51], v[164:167], v[72:75], v[48:51]
	v_mfma_f32_16x16x32_bf16 v[60:63], v[160:163], v[68:71], v[60:63]
	v_mfma_f32_16x16x32_bf16 v[56:59], v[168:171], v[68:71], v[56:59]
	s_waitcnt lgkmcnt(4)
	v_mfma_f32_16x16x32_bf16 v[52:55], v[160:163], v[76:79], v[52:55]
	v_mfma_f32_16x16x32_bf16 v[48:51], v[168:171], v[76:79], v[48:51]
	s_waitcnt lgkmcnt(3)
	v_mfma_f32_16x16x32_bf16 v[44:47], v[156:159], v[96:99], v[44:47]
	v_mfma_f32_16x16x32_bf16 v[40:43], v[164:167], v[96:99], v[40:43]
	s_waitcnt lgkmcnt(1)
	v_mfma_f32_16x16x32_bf16 v[36:39], v[156:159], v[104:107], v[36:39]
	v_mfma_f32_16x16x32_bf16 v[32:35], v[164:167], v[104:107], v[32:35]
	v_mfma_f32_16x16x32_bf16 v[204:207], v[160:163], v[100:103], v[44:47]
	v_mfma_f32_16x16x32_bf16 v[208:211], v[168:171], v[100:103], v[40:43]
	s_waitcnt lgkmcnt(0)
	v_mfma_f32_16x16x32_bf16 v[156:159], v[160:163], v[108:111], v[36:39]
	v_mfma_f32_16x16x32_bf16 v[160:163], v[168:171], v[108:111], v[32:35]
	s_setprio 0
	s_setprio 1
	v_mfma_f32_16x16x32_bf16 v[28:31], v[172:175], v[64:67], v[28:31]
	v_mfma_f32_16x16x32_bf16 v[24:27], v[180:183], v[64:67], v[24:27]
	v_mfma_f32_16x16x32_bf16 v[20:23], v[172:175], v[72:75], v[20:23]
	v_mfma_f32_16x16x32_bf16 v[16:19], v[180:183], v[72:75], v[16:19]
	v_mfma_f32_16x16x32_bf16 v[28:31], v[176:179], v[68:71], v[28:31]
	v_mfma_f32_16x16x32_bf16 v[24:27], v[184:187], v[68:71], v[24:27]
	v_mfma_f32_16x16x32_bf16 v[20:23], v[176:179], v[76:79], v[20:23]
	v_mfma_f32_16x16x32_bf16 v[16:19], v[184:187], v[76:79], v[16:19]
	v_mfma_f32_16x16x32_bf16 v[12:15], v[172:175], v[96:99], v[12:15]
	v_mfma_f32_16x16x32_bf16 v[8:11], v[180:183], v[96:99], v[8:11]
	v_mfma_f32_16x16x32_bf16 v[4:7], v[172:175], v[104:107], v[4:7]
	v_mfma_f32_16x16x32_bf16 v[0:3], v[180:183], v[104:107], v[0:3]
	v_mfma_f32_16x16x32_bf16 v[164:167], v[176:179], v[100:103], v[12:15]
	v_mfma_f32_16x16x32_bf16 v[168:171], v[184:187], v[100:103], v[8:11]
	v_mfma_f32_16x16x32_bf16 v[172:175], v[176:179], v[108:111], v[4:7]
	v_mfma_f32_16x16x32_bf16 v[176:179], v[184:187], v[108:111], v[0:3]
	s_setprio 0
	s_barrier
; #define LDA(dst, b, h) for (int m = 0; m < 4; ++m) for (int k = 0; k < 2; ++k) \
;     dst[m][k] = *reinterpret_cast<const bf16x8*>((char*)SA(b, h) + lds_byte(wr * 64 + m * 16 + fr, k * 32 + fq * 8))
; #define LDB(dst, b, h) for (int n = 0; n < 2; ++n) for (int k = 0; k < 2; ++k) \
;     dst[n][k] = *reinterpret_cast<const bf16x8*>((char*)SB(b, h) + lds_byte(wc * 32 + n * 16 + fr, k * 32 + fq * 8))
; #define MMA(ai, bj, At, Bt_) do { __builtin_amdgcn_s_setprio(1); \
;     for (int m = 0; m < 4; ++m) for (int n = 0; n < 2; ++n) for (int k = 0; k < 2; ++k) \
;       acc[ai][bj][m][n] = __builtin_amdgcn_mfma_f32_16x16x32_bf16(Bt_[n][k], At[m][k], acc[ai][bj][m][n], 0, 0, 0); \
;     __builtin_amdgcn_s_setprio(0); } while (0)
; #define WAIT_V(n) asm volatile("s_waitcnt vmcnt(" #n ")" ::: "memory")
; #define WAIT_L(n) asm volatile("s_waitcnt lgkmcnt(" #n ")" ::: "memory")
; #define BAR __builtin_amdgcn_s_barrier()
; #define SCHED __builtin_amdgcn_sched_barrier(0)
; template <int MODE>
; DI void gemm_phase(const bf16_t* __restrict__ A, const bf16_t* __restrict__ Bt, int M, int N, int K, const Epi& ep) {
;     ...
;             LDB(B0, 1, 0); LDB(B1, 1, 1); SCHED; LDA(At, 1, 0);
;             WAIT_V(0); WAIT_L(0); BAR; MMA(0, 0, At, B0); MMA(0, 1, At, B1); BAR; SCHED;
;             LDA(At, 1, 1);
;             WAIT_L(0); BAR; MMA(1, 0, At, B0); MMA(1, 1, At, B1); BAR; SCHED;
;         }
;         if (wr == 0) BAR;
	s_nop 1
	ds_read_b128 v[0:3], v152
	ds_read_b128 v[4:7], v152 offset:1024
	ds_read_b128 v[8:11], v152 offset:2048
	ds_read_b128 v[12:15], v152 offset:3072
	ds_read_b128 v[180:183], v153
	ds_read_b128 v[184:187], v153 offset:1024
	ds_read_b128 v[214:217], v153 offset:2048
	ds_read_b128 v[218:221], v153 offset:3072
	ds_read_b128 v[32:35], v148 offset:32768
	ds_read_b128 v[36:39], v148 offset:33792
	ds_read_b128 v[40:43], v149 offset:32768
	ds_read_b128 v[44:47], v149 offset:33792
	ds_read_b128 v[238:241], v150 offset:32768
	ds_read_b128 v[242:245], v150 offset:33792
	ds_read_b128 v[246:249], v151 offset:32768
	ds_read_b128 v[64:67], v151 offset:33792
	s_waitcnt vmcnt(0)
	s_waitcnt lgkmcnt(0)
	s_barrier
	s_setprio 1
	s_waitcnt lgkmcnt(7)
	v_mfma_f32_16x16x32_bf16 v[68:71], v[0:3], v[32:35], v[124:127]
	s_waitcnt lgkmcnt(6)
	v_mfma_f32_16x16x32_bf16 v[96:99], v[4:7], v[36:39], v[68:71]
	v_mfma_f32_16x16x32_bf16 v[68:71], v[8:11], v[32:35], v[120:123]
	v_mfma_f32_16x16x32_bf16 v[100:103], v[12:15], v[36:39], v[68:71]
	s_waitcnt lgkmcnt(5)
	v_mfma_f32_16x16x32_bf16 v[68:71], v[0:3], v[40:43], v[116:119]
	s_waitcnt lgkmcnt(4)
	v_mfma_f32_16x16x32_bf16 v[104:107], v[4:7], v[44:47], v[68:71]
	v_mfma_f32_16x16x32_bf16 v[68:71], v[8:11], v[40:43], v[112:115]
	v_mfma_f32_16x16x32_bf16 v[108:111], v[12:15], v[44:47], v[68:71]
	s_waitcnt lgkmcnt(3)
	v_mfma_f32_16x16x32_bf16 v[68:71], v[0:3], v[238:241], v[222:225]
	s_waitcnt lgkmcnt(2)
	v_mfma_f32_16x16x32_bf16 v[112:115], v[4:7], v[242:245], v[68:71]
	v_mfma_f32_16x16x32_bf16 v[68:71], v[8:11], v[238:241], v[226:229]
	v_mfma_f32_16x16x32_bf16 v[116:119], v[12:15], v[242:245], v[68:71]
	s_waitcnt lgkmcnt(1)
	v_mfma_f32_16x16x32_bf16 v[68:71], v[0:3], v[246:249], v[230:233]
	s_waitcnt lgkmcnt(0)
	v_mfma_f32_16x16x32_bf16 v[120:123], v[4:7], v[64:67], v[68:71]
	v_mfma_f32_16x16x32_bf16 v[68:71], v[8:11], v[246:249], v[234:237]
	v_mfma_f32_16x16x32_bf16 v[124:127], v[12:15], v[64:67], v[68:71]
	s_setprio 0
	s_setprio 1
	v_mfma_f32_16x16x32_bf16 v[68:71], v[180:183], v[32:35], v[92:95]
	v_mfma_f32_16x16x32_bf16 v[32:35], v[214:217], v[32:35], v[88:91]
	v_mfma_f32_16x16x32_bf16 v[222:225], v[184:187], v[36:39], v[68:71]
	v_mfma_f32_16x16x32_bf16 v[68:71], v[218:221], v[36:39], v[32:35]
	v_mfma_f32_16x16x32_bf16 v[32:35], v[180:183], v[40:43], v[84:87]
	v_mfma_f32_16x16x32_bf16 v[72:75], v[184:187], v[44:47], v[32:35]
	v_mfma_f32_16x16x32_bf16 v[32:35], v[214:217], v[40:43], v[80:83]
	v_mfma_f32_16x16x32_bf16 v[76:79], v[218:221], v[44:47], v[32:35]
	v_mfma_f32_16x16x32_bf16 v[32:35], v[180:183], v[238:241], v[188:191]
	v_mfma_f32_16x16x32_bf16 v[80:83], v[184:187], v[242:245], v[32:35]
	v_mfma_f32_16x16x32_bf16 v[32:35], v[214:217], v[238:241], v[192:195]
	v_mfma_f32_16x16x32_bf16 v[84:87], v[218:221], v[242:245], v[32:35]
	v_mfma_f32_16x16x32_bf16 v[32:35], v[180:183], v[246:249], v[196:199]
	v_mfma_f32_16x16x32_bf16 v[88:91], v[184:187], v[64:67], v[32:35]
	v_mfma_f32_16x16x32_bf16 v[32:35], v[214:217], v[246:249], v[200:203]
	v_mfma_f32_16x16x32_bf16 v[92:95], v[218:221], v[64:67], v[32:35]
	s_setprio 0
	s_barrier
	ds_read_b128 v[64:67], v148 offset:49152
	ds_read_b128 v[188:191], v148 offset:50176
	ds_read_b128 v[192:195], v149 offset:49152
	ds_read_b128 v[196:199], v149 offset:50176
	ds_read_b128 v[200:203], v150 offset:49152
	ds_read_b128 v[226:229], v150 offset:50176
	ds_read_b128 v[230:233], v151 offset:49152
	ds_read_b128 v[234:237], v151 offset:50176
	s_waitcnt lgkmcnt(0)
	s_barrier
	s_setprio 1
	s_waitcnt lgkmcnt(7)
	v_mfma_f32_16x16x32_bf16 v[32:35], v[0:3], v[64:67], v[60:63]
	s_waitcnt lgkmcnt(5)
	v_mfma_f32_16x16x32_bf16 v[40:43], v[0:3], v[192:195], v[52:55]
	v_mfma_f32_16x16x32_bf16 v[44:47], v[8:11], v[192:195], v[48:51]
	s_waitcnt lgkmcnt(3)
	v_mfma_f32_16x16x32_bf16 v[48:51], v[0:3], v[200:203], v[204:207]
	s_waitcnt lgkmcnt(1)
	v_mfma_f32_16x16x32_bf16 v[0:3], v[0:3], v[230:233], v[156:159]
	v_mfma_f32_16x16x32_bf16 v[36:39], v[8:11], v[64:67], v[56:59]
	v_mfma_f32_16x16x32_bf16 v[52:55], v[8:11], v[200:203], v[208:211]
	s_waitcnt lgkmcnt(0)
	v_mfma_f32_16x16x32_bf16 v[56:59], v[4:7], v[234:237], v[0:3]
	v_mfma_f32_16x16x32_bf16 v[0:3], v[8:11], v[230:233], v[160:163]
	v_mfma_f32_16x16x32_bf16 v[32:35], v[4:7], v[188:191], v[32:35]
	v_mfma_f32_16x16x32_bf16 v[36:39], v[12:15], v[188:191], v[36:39]
	v_mfma_f32_16x16x32_bf16 v[40:43], v[4:7], v[196:199], v[40:43]
	v_mfma_f32_16x16x32_bf16 v[44:47], v[12:15], v[196:199], v[44:47]
	v_mfma_f32_16x16x32_bf16 v[48:51], v[4:7], v[226:229], v[48:51]
	v_mfma_f32_16x16x32_bf16 v[52:55], v[12:15], v[226:229], v[52:55]
	v_mfma_f32_16x16x32_bf16 v[60:63], v[12:15], v[234:237], v[0:3]
	s_setprio 0
	s_setprio 1
	v_mfma_f32_16x16x32_bf16 v[0:3], v[180:183], v[64:67], v[28:31]
	v_mfma_f32_16x16x32_bf16 v[4:7], v[214:217], v[64:67], v[24:27]
	v_mfma_f32_16x16x32_bf16 v[8:11], v[180:183], v[192:195], v[20:23]
	v_mfma_f32_16x16x32_bf16 v[12:15], v[214:217], v[192:195], v[16:19]
	v_mfma_f32_16x16x32_bf16 v[16:19], v[180:183], v[200:203], v[164:167]
	v_mfma_f32_16x16x32_bf16 v[20:23], v[214:217], v[200:203], v[168:171]
	v_mfma_f32_16x16x32_bf16 v[24:27], v[180:183], v[230:233], v[172:175]
	v_mfma_f32_16x16x32_bf16 v[28:31], v[214:217], v[230:233], v[176:179]
	v_mfma_f32_16x16x32_bf16 v[0:3], v[184:187], v[188:191], v[0:3]
	v_mfma_f32_16x16x32_bf16 v[4:7], v[218:221], v[188:191], v[4:7]
	v_mfma_f32_16x16x32_bf16 v[8:11], v[184:187], v[196:199], v[8:11]
	v_mfma_f32_16x16x32_bf16 v[12:15], v[218:221], v[196:199], v[12:15]
	v_mfma_f32_16x16x32_bf16 v[16:19], v[184:187], v[226:229], v[16:19]
	v_mfma_f32_16x16x32_bf16 v[20:23], v[218:221], v[226:229], v[20:23]
	v_mfma_f32_16x16x32_bf16 v[24:27], v[184:187], v[234:237], v[24:27]
	v_mfma_f32_16x16x32_bf16 v[28:31], v[218:221], v[234:237], v[28:31]
	s_setprio 0
	s_barrier
	s_and_saveexec_b64 s[0:1], s[38:39]
	s_cbranch_execz .LBB0_94
	s_barrier

; #define LDA(dst, b, h) for (int m = 0; m < 4; ++m) for (int k = 0; k < 2; ++k) \
;     dst[m][k] = *reinterpret_cast<const bf16x8*>((char*)SA(b, h) + lds_byte(wr * 64 + m * 16 + fr, k * 32 + fq * 8))
; #define LDB(dst, b, h) for (int n = 0; n < 2; ++n) for (int k = 0; k < 2; ++k) \
;     dst[n][k] = *reinterpret_cast<const bf16x8*>((char*)SB(b, h) + lds_byte(wc * 32 + n * 16 + fr, k * 32 + fq * 8))
; #define MMA(ai, bj, At, Bt_) do { __builtin_amdgcn_s_setprio(1); \
;     for (int m = 0; m < 4; ++m) for (int n = 0; n < 2; ++n) for (int k = 0; k < 2; ++k) \
;       acc[ai][bj][m][n] = __builtin_amdgcn_mfma_f32_16x16x32_bf16(Bt_[n][k], At[m][k], acc[ai][bj][m][n], 0, 0, 0); \
;     __builtin_amdgcn_s_setprio(0); } while (0)
; #define WAIT_V(n) asm volatile("s_waitcnt vmcnt(" #n ")" ::: "memory")
; #define WAIT_L(n) asm volatile("s_waitcnt lgkmcnt(" #n ")" ::: "memory")
; #define BAR __builtin_amdgcn_s_barrier()
; #define SCHED __builtin_amdgcn_sched_barrier(0)
; template <int MODE>
; DI void gemm_phase(const bf16_t* __restrict__ A, const bf16_t* __restrict__ Bt, int M, int N, int K, const Epi& ep) {
;     ...
;             LDB(B0, 0, 0); LDB(B1, 0, 1); SCHED; LDA(At, 0, 0); STAGE(SA(1, 1), rsA, brow + HALF, t + 1);
;             WAIT_V(8); WAIT_L(0); BAR; MMA(0, 0, At, B0); MMA(0, 1, At, B1); BAR; SCHED;
;             LDA(At, 0, 1); STAGE(SB(0, 0), rsB, bcol, t + 2); STAGE(SB(0, 1), rsB, bcol + HALF, t + 2); STAGE(SA(0, 0), rsA, brow, t + 2);
.LBB0_488:
	ds_read_b128 v[156:159], v147
	ds_read_b128 v[160:163], v147 offset:1024
	ds_read_b128 v[164:167], v147 offset:2048
	ds_read_b128 v[168:171], v147 offset:3072
	ds_read_b128 v[172:175], v148
	ds_read_b128 v[176:179], v148 offset:1024
	ds_read_b128 v[180:183], v148 offset:2048
	ds_read_b128 v[184:187], v148 offset:3072
	s_add_i32 s42, s27, s41
	v_readfirstlane_b32 s15, v144
	s_add_i32 s14, s42, 0x40080
	s_mov_b32 s30, s10
	s_mov_b32 s31, s11
	s_mov_b32 m0, s15
	v_readfirstlane_b32 s15, v145
	ds_read_b128 v[188:191], v149
	ds_read_b128 v[192:195], v149 offset:1024
	ds_read_b128 v[196:199], v150
	ds_read_b128 v[200:203], v150 offset:1024
	ds_read_b128 v[204:207], v151
	ds_read_b128 v[208:211], v151 offset:1024
	ds_read_b128 v[214:217], v152
	ds_read_b128 v[218:221], v152 offset:1024
	buffer_load_dwordx4 v128, s[28:31], s14 offen lds
	s_mov_b32 m0, s15
	s_nop 0
	buffer_load_dwordx4 v129, s[28:31], s14 offen lds
	s_waitcnt vmcnt(8)
	s_waitcnt lgkmcnt(0)
	s_barrier
	s_setprio 1
	s_waitcnt lgkmcnt(7)
	v_mfma_f32_16x16x32_bf16 v[124:127], v[156:159], v[188:191], v[124:127]
	v_mfma_f32_16x16x32_bf16 v[120:123], v[164:167], v[188:191], v[120:123]
	s_waitcnt lgkmcnt(5)
	v_mfma_f32_16x16x32_bf16 v[116:119], v[156:159], v[196:199], v[116:119]
	v_mfma_f32_16x16x32_bf16 v[112:115], v[164:167], v[196:199], v[112:115]
	s_waitcnt lgkmcnt(3)
	v_mfma_f32_16x16x32_bf16 v[108:111], v[156:159], v[204:207], v[108:111]
	v_mfma_f32_16x16x32_bf16 v[104:107], v[164:167], v[204:207], v[104:107]
	s_waitcnt lgkmcnt(1)
	v_mfma_f32_16x16x32_bf16 v[100:103], v[156:159], v[214:217], v[100:103]
	v_mfma_f32_16x16x32_bf16 v[96:99], v[164:167], v[214:217], v[96:99]
	v_mfma_f32_16x16x32_bf16 v[124:127], v[160:163], v[192:195], v[124:127]
	v_mfma_f32_16x16x32_bf16 v[120:123], v[168:171], v[192:195], v[120:123]
	v_mfma_f32_16x16x32_bf16 v[116:119], v[160:163], v[200:203], v[116:119]
	v_mfma_f32_16x16x32_bf16 v[112:115], v[168:171], v[200:203], v[112:115]
	v_mfma_f32_16x16x32_bf16 v[108:111], v[160:163], v[208:211], v[108:111]
	v_mfma_f32_16x16x32_bf16 v[104:107], v[168:171], v[208:211], v[104:107]
	s_waitcnt lgkmcnt(0)
	v_mfma_f32_16x16x32_bf16 v[100:103], v[160:163], v[218:221], v[100:103]
	v_mfma_f32_16x16x32_bf16 v[96:99], v[168:171], v[218:221], v[96:99]
	s_setprio 0
	s_setprio 1
	v_mfma_f32_16x16x32_bf16 v[92:95], v[172:175], v[188:191], v[92:95]
	v_mfma_f32_16x16x32_bf16 v[88:91], v[180:183], v[188:191], v[88:91]
	v_mfma_f32_16x16x32_bf16 v[84:87], v[172:175], v[196:199], v[84:87]
	v_mfma_f32_16x16x32_bf16 v[80:83], v[180:183], v[196:199], v[80:83]
	v_mfma_f32_16x16x32_bf16 v[76:79], v[172:175], v[204:207], v[76:79]
	v_mfma_f32_16x16x32_bf16 v[72:75], v[180:183], v[204:207], v[72:75]
	v_mfma_f32_16x16x32_bf16 v[68:71], v[172:175], v[214:217], v[68:71]
	v_mfma_f32_16x16x32_bf16 v[64:67], v[180:183], v[214:217], v[64:67]
	v_mfma_f32_16x16x32_bf16 v[92:95], v[176:179], v[192:195], v[92:95]
	v_mfma_f32_16x16x32_bf16 v[88:91], v[184:187], v[192:195], v[88:91]
	v_mfma_f32_16x16x32_bf16 v[84:87], v[176:179], v[200:203], v[84:87]
	v_mfma_f32_16x16x32_bf16 v[80:83], v[184:187], v[200:203], v[80:83]
	v_mfma_f32_16x16x32_bf16 v[76:79], v[176:179], v[208:211], v[76:79]
	v_mfma_f32_16x16x32_bf16 v[72:75], v[184:187], v[208:211], v[72:75]
	v_mfma_f32_16x16x32_bf16 v[68:71], v[176:179], v[218:221], v[68:71]
	v_mfma_f32_16x16x32_bf16 v[64:67], v[184:187], v[218:221], v[64:67]
	s_setprio 0
	s_barrier
	s_add_i32 s43, s6, s41
	v_readfirstlane_b32 s45, v130
	s_add_i32 s44, s43, 0x100
	s_mov_b32 s14, s10
	s_mov_b32 s15, s11
	s_mov_b32 m0, s45
	v_readfirstlane_b32 s45, v131
	ds_read_b128 v[188:191], v149 offset:16384
	ds_read_b128 v[192:195], v149 offset:17408
	ds_read_b128 v[196:199], v150 offset:16384
	ds_read_b128 v[200:203], v150 offset:17408
	ds_read_b128 v[204:207], v151 offset:16384
	ds_read_b128 v[208:211], v151 offset:17408
	ds_read_b128 v[214:217], v152 offset:16384
	ds_read_b128 v[218:221], v152 offset:17408
	buffer_load_dwordx4 v128, s[12:15], s44 offen lds
	s_mov_b32 m0, s45
	v_readfirstlane_b32 s45, v132
	buffer_load_dwordx4 v129, s[12:15], s44 offen lds
	s_add_i32 s44, s43, 0x40100
	s_mov_b32 m0, s45
	v_readfirstlane_b32 s45, v133
	buffer_load_dwordx4 v128, s[12:15], s44 offen lds
	s_mov_b32 m0, s45
	v_readfirstlane_b32 s45, v134
	buffer_load_dwordx4 v129, s[12:15], s44 offen lds
	s_add_i32 s44, s42, 0x100
	s_mov_b32 m0, s45
	v_readfirstlane_b32 s45, v135
	buffer_load_dwordx4 v128, s[28:31], s44 offen lds
	s_mov_b32 m0, s45
	s_nop 0
	buffer_load_dwordx4 v129, s[28:31], s44 offen lds
	s_waitcnt vmcnt(8)
	s_waitcnt lgkmcnt(0)
	s_barrier
; #define LDA(dst, b, h) for (int m = 0; m < 4; ++m) for (int k = 0; k < 2; ++k) \
;     dst[m][k] = *reinterpret_cast<const bf16x8*>((char*)SA(b, h) + lds_byte(wr * 64 + m * 16 + fr, k * 32 + fq * 8))
; #define LDB(dst, b, h) for (int n = 0; n < 2; ++n) for (int k = 0; k < 2; ++k) \
;     dst[n][k] = *reinterpret_cast<const bf16x8*>((char*)SB(b, h) + lds_byte(wc * 32 + n * 16 + fr, k * 32 + fq * 8))
; #define MMA(ai, bj, At, Bt_) do { __builtin_amdgcn_s_setprio(1); \
;     for (int m = 0; m < 4; ++m) for (int n = 0; n < 2; ++n) for (int k = 0; k < 2; ++k) \
;       acc[ai][bj][m][n] = __builtin_amdgcn_mfma_f32_16x16x32_bf16(Bt_[n][k], At[m][k], acc[ai][bj][m][n], 0, 0, 0); \
;     __builtin_amdgcn_s_setprio(0); } while (0)
; #define WAIT_V(n) asm volatile("s_waitcnt vmcnt(" #n ")" ::: "memory")
; #define WAIT_L(n) asm volatile("s_waitcnt lgkmcnt(" #n ")" ::: "memory")
; #define BAR __builtin_amdgcn_s_barrier()
; #define SCHED __builtin_amdgcn_sched_barrier(0)
; template <int MODE>
; DI void gemm_phase(const bf16_t* __restrict__ A, const bf16_t* __restrict__ Bt, int M, int N, int K, const Epi& ep) {
;     ...
;             WAIT_V(8); WAIT_L(0); BAR; MMA(1, 0, At, B0); MMA(1, 1, At, B1); BAR; SCHED;
;             LDB(B0, 1, 0); LDB(B1, 1, 1); SCHED; LDA(At, 1, 0); STAGE(SA(0, 1), rsA, brow + HALF, t + 2);
;             WAIT_V(8); WAIT_L(0); BAR; MMA(0, 0, At, B0); MMA(0, 1, At, B1); BAR; SCHED;
	s_setprio 1
	s_waitcnt lgkmcnt(7)
	v_mfma_f32_16x16x32_bf16 v[60:63], v[156:159], v[188:191], v[60:63]
	v_mfma_f32_16x16x32_bf16 v[56:59], v[164:167], v[188:191], v[56:59]
	s_waitcnt lgkmcnt(5)
	v_mfma_f32_16x16x32_bf16 v[52:55], v[156:159], v[196:199], v[52:55]
	v_mfma_f32_16x16x32_bf16 v[48:51], v[164:167], v[196:199], v[48:51]
	s_waitcnt lgkmcnt(3)
	v_mfma_f32_16x16x32_bf16 v[44:47], v[156:159], v[204:207], v[44:47]
	v_mfma_f32_16x16x32_bf16 v[40:43], v[164:167], v[204:207], v[40:43]
	s_waitcnt lgkmcnt(1)
	v_mfma_f32_16x16x32_bf16 v[36:39], v[156:159], v[214:217], v[36:39]
	v_mfma_f32_16x16x32_bf16 v[32:35], v[164:167], v[214:217], v[32:35]
	v_mfma_f32_16x16x32_bf16 v[60:63], v[160:163], v[192:195], v[60:63]
	v_mfma_f32_16x16x32_bf16 v[56:59], v[168:171], v[192:195], v[56:59]
	v_mfma_f32_16x16x32_bf16 v[52:55], v[160:163], v[200:203], v[52:55]
	v_mfma_f32_16x16x32_bf16 v[48:51], v[168:171], v[200:203], v[48:51]
	v_mfma_f32_16x16x32_bf16 v[44:47], v[160:163], v[208:211], v[44:47]
	v_mfma_f32_16x16x32_bf16 v[40:43], v[168:171], v[208:211], v[40:43]
	s_waitcnt lgkmcnt(0)
	v_mfma_f32_16x16x32_bf16 v[36:39], v[160:163], v[218:221], v[36:39]
	v_mfma_f32_16x16x32_bf16 v[32:35], v[168:171], v[218:221], v[32:35]
	s_setprio 0
	s_setprio 1
	v_mfma_f32_16x16x32_bf16 v[28:31], v[172:175], v[188:191], v[28:31]
	v_mfma_f32_16x16x32_bf16 v[24:27], v[180:183], v[188:191], v[24:27]
	v_mfma_f32_16x16x32_bf16 v[20:23], v[172:175], v[196:199], v[20:23]
	v_mfma_f32_16x16x32_bf16 v[16:19], v[180:183], v[196:199], v[16:19]
	v_mfma_f32_16x16x32_bf16 v[12:15], v[172:175], v[204:207], v[12:15]
	v_mfma_f32_16x16x32_bf16 v[8:11], v[180:183], v[204:207], v[8:11]
	v_mfma_f32_16x16x32_bf16 v[4:7], v[172:175], v[214:217], v[4:7]
	v_mfma_f32_16x16x32_bf16 v[0:3], v[180:183], v[214:217], v[0:3]
	v_mfma_f32_16x16x32_bf16 v[28:31], v[176:179], v[192:195], v[28:31]
	v_mfma_f32_16x16x32_bf16 v[24:27], v[184:187], v[192:195], v[24:27]
	v_mfma_f32_16x16x32_bf16 v[20:23], v[176:179], v[200:203], v[20:23]
	v_mfma_f32_16x16x32_bf16 v[16:19], v[184:187], v[200:203], v[16:19]
	v_mfma_f32_16x16x32_bf16 v[12:15], v[176:179], v[208:211], v[12:15]
	v_mfma_f32_16x16x32_bf16 v[8:11], v[184:187], v[208:211], v[8:11]
	v_mfma_f32_16x16x32_bf16 v[4:7], v[176:179], v[218:221], v[4:7]
	v_mfma_f32_16x16x32_bf16 v[0:3], v[184:187], v[218:221], v[0:3]
	s_setprio 0
	s_barrier
	ds_read_b128 v[156:159], v153
	ds_read_b128 v[160:163], v153 offset:1024
	ds_read_b128 v[164:167], v153 offset:2048
	ds_read_b128 v[168:171], v153 offset:3072
	ds_read_b128 v[172:175], v154
	ds_read_b128 v[176:179], v154 offset:1024
	ds_read_b128 v[180:183], v154 offset:2048
	ds_read_b128 v[184:187], v154 offset:3072
	v_readfirstlane_b32 s45, v136
	s_add_i32 s44, s42, 0x40100
	s_mov_b32 m0, s45
	v_readfirstlane_b32 s45, v137
	ds_read_b128 v[188:191], v149 offset:32768
	ds_read_b128 v[192:195], v149 offset:33792
	ds_read_b128 v[196:199], v150 offset:32768
	ds_read_b128 v[200:203], v150 offset:33792
	ds_read_b128 v[204:207], v151 offset:32768
	ds_read_b128 v[208:211], v151 offset:33792
	ds_read_b128 v[214:217], v152 offset:32768
	ds_read_b128 v[218:221], v152 offset:33792
	buffer_load_dwordx4 v128, s[28:31], s44 offen lds
	s_mov_b32 m0, s45
	s_nop 0
	buffer_load_dwordx4 v129, s[28:31], s44 offen lds
	s_waitcnt vmcnt(8)
	s_waitcnt lgkmcnt(0)
	s_barrier
	s_setprio 1
	s_waitcnt lgkmcnt(7)
	v_mfma_f32_16x16x32_bf16 v[124:127], v[156:159], v[188:191], v[124:127]
	v_mfma_f32_16x16x32_bf16 v[120:123], v[164:167], v[188:191], v[120:123]
	s_waitcnt lgkmcnt(5)
	v_mfma_f32_16x16x32_bf16 v[116:119], v[156:159], v[196:199], v[116:119]
	v_mfma_f32_16x16x32_bf16 v[112:115], v[164:167], v[196:199], v[112:115]
	s_waitcnt lgkmcnt(3)
	v_mfma_f32_16x16x32_bf16 v[108:111], v[156:159], v[204:207], v[108:111]
	v_mfma_f32_16x16x32_bf16 v[104:107], v[164:167], v[204:207], v[104:107]
	s_waitcnt lgkmcnt(1)
	v_mfma_f32_16x16x32_bf16 v[100:103], v[156:159], v[214:217], v[100:103]
	v_mfma_f32_16x16x32_bf16 v[96:99], v[164:167], v[214:217], v[96:99]
	v_mfma_f32_16x16x32_bf16 v[124:127], v[160:163], v[192:195], v[124:127]
	v_mfma_f32_16x16x32_bf16 v[120:123], v[168:171], v[192:195], v[120:123]
	v_mfma_f32_16x16x32_bf16 v[116:119], v[160:163], v[200:203], v[116:119]
	v_mfma_f32_16x16x32_bf16 v[112:115], v[168:171], v[200:203], v[112:115]
	v_mfma_f32_16x16x32_bf16 v[108:111], v[160:163], v[208:211], v[108:111]
	v_mfma_f32_16x16x32_bf16 v[104:107], v[168:171], v[208:211], v[104:107]
	s_waitcnt lgkmcnt(0)
	v_mfma_f32_16x16x32_bf16 v[100:103], v[160:163], v[218:221], v[100:103]
	v_mfma_f32_16x16x32_bf16 v[96:99], v[168:171], v[218:221], v[96:99]
	s_setprio 0
	s_setprio 1
	v_mfma_f32_16x16x32_bf16 v[92:95], v[172:175], v[188:191], v[92:95]
	v_mfma_f32_16x16x32_bf16 v[88:91], v[180:183], v[188:191], v[88:91]
	v_mfma_f32_16x16x32_bf16 v[84:87], v[172:175], v[196:199], v[84:87]
	v_mfma_f32_16x16x32_bf16 v[80:83], v[180:183], v[196:199], v[80:83]
	v_mfma_f32_16x16x32_bf16 v[76:79], v[172:175], v[204:207], v[76:79]
	v_mfma_f32_16x16x32_bf16 v[72:75], v[180:183], v[204:207], v[72:75]
	v_mfma_f32_16x16x32_bf16 v[68:71], v[172:175], v[214:217], v[68:71]
	v_mfma_f32_16x16x32_bf16 v[64:67], v[180:183], v[214:217], v[64:67]
	v_mfma_f32_16x16x32_bf16 v[92:95], v[176:179], v[192:195], v[92:95]
	v_mfma_f32_16x16x32_bf16 v[88:91], v[184:187], v[192:195], v[88:91]
	v_mfma_f32_16x16x32_bf16 v[84:87], v[176:179], v[200:203], v[84:87]
	v_mfma_f32_16x16x32_bf16 v[80:83], v[184:187], v[200:203], v[80:83]
	v_mfma_f32_16x16x32_bf16 v[76:79], v[176:179], v[208:211], v[76:79]
	v_mfma_f32_16x16x32_bf16 v[72:75], v[184:187], v[208:211], v[72:75]
	v_mfma_f32_16x16x32_bf16 v[68:71], v[176:179], v[218:221], v[68:71]
	v_mfma_f32_16x16x32_bf16 v[64:67], v[184:187], v[218:221], v[64:67]
	s_setprio 0
	s_barrier
; #define LDA(dst, b, h) for (int m = 0; m < 4; ++m) for (int k = 0; k < 2; ++k) \
;     dst[m][k] = *reinterpret_cast<const bf16x8*>((char*)SA(b, h) + lds_byte(wr * 64 + m * 16 + fr, k * 32 + fq * 8))
; #define LDB(dst, b, h) for (int n = 0; n < 2; ++n) for (int k = 0; k < 2; ++k) \
;     dst[n][k] = *reinterpret_cast<const bf16x8*>((char*)SB(b, h) + lds_byte(wc * 32 + n * 16 + fr, k * 32 + fq * 8))
; #define MMA(ai, bj, At, Bt_) do { __builtin_amdgcn_s_setprio(1); \
;     for (int m = 0; m < 4; ++m) for (int n = 0; n < 2; ++n) for (int k = 0; k < 2; ++k) \
;       acc[ai][bj][m][n] = __builtin_amdgcn_mfma_f32_16x16x32_bf16(Bt_[n][k], At[m][k], acc[ai][bj][m][n], 0, 0, 0); \
;     __builtin_amdgcn_s_setprio(0); } while (0)
; #define WAIT_V(n) asm volatile("s_waitcnt vmcnt(" #n ")" ::: "memory")
; #define WAIT_L(n) asm volatile("s_waitcnt lgkmcnt(" #n ")" ::: "memory")
; #define BAR __builtin_amdgcn_s_barrier()
; #define SCHED __builtin_amdgcn_sched_barrier(0)
; template <int MODE>
; DI void gemm_phase(const bf16_t* __restrict__ A, const bf16_t* __restrict__ Bt, int M, int N, int K, const Epi& ep) {
;     ...
;             LDA(At, 1, 1); STAGE(SB(1, 0), rsB, bcol, t + 3); STAGE(SB(1, 1), rsB, bcol + HALF, t + 3); STAGE(SA(1, 0), rsA, brow, t + 3);
;             WAIT_V(8); WAIT_L(0); BAR; MMA(1, 0, At, B0); MMA(1, 1, At, B1); BAR; SCHED;
;         }
;         {
;             LDB(B0, 0, 0); LDB(B1, 0, 1); SCHED; LDA(At, 0, 0); STAGE(SA(1, 1), rsA, brow + HALF, nt - 1);
;             WAIT_V(8); WAIT_L(0); BAR; MMA(0, 0, At, B0); MMA(0, 1, At, B1); BAR; SCHED;
	v_readfirstlane_b32 s45, v138
	s_add_i32 s44, s43, 0x180
	s_mov_b32 m0, s45
	v_readfirstlane_b32 s45, v139
	ds_read_b128 v[188:191], v149 offset:49152
	ds_read_b128 v[192:195], v149 offset:50176
	ds_read_b128 v[196:199], v150 offset:49152
	ds_read_b128 v[200:203], v150 offset:50176
	ds_read_b128 v[204:207], v151 offset:49152
	ds_read_b128 v[208:211], v151 offset:50176
	ds_read_b128 v[214:217], v152 offset:49152
	ds_read_b128 v[218:221], v152 offset:50176
	buffer_load_dwordx4 v128, s[12:15], s44 offen lds
	s_mov_b32 m0, s45
	s_add_i32 s43, s43, 0x40180
	buffer_load_dwordx4 v129, s[12:15], s44 offen lds
	v_readfirstlane_b32 s44, v142
	s_mov_b32 m0, s44
	v_readfirstlane_b32 s44, v143
	buffer_load_dwordx4 v128, s[12:15], s43 offen lds
	s_mov_b32 m0, s44
	s_addk_i32 s42, 0x180
	buffer_load_dwordx4 v129, s[12:15], s43 offen lds
	v_readfirstlane_b32 s14, v140
	s_mov_b32 m0, s14
	v_readfirstlane_b32 s14, v141
	buffer_load_dwordx4 v128, s[28:31], s42 offen lds
	s_mov_b32 m0, s14
	s_nop 0
	buffer_load_dwordx4 v129, s[28:31], s42 offen lds
	s_waitcnt vmcnt(8)
	s_waitcnt lgkmcnt(0)
	s_barrier
	s_setprio 1
	s_waitcnt lgkmcnt(7)
	v_mfma_f32_16x16x32_bf16 v[60:63], v[156:159], v[188:191], v[60:63]
	v_mfma_f32_16x16x32_bf16 v[56:59], v[164:167], v[188:191], v[56:59]
	s_waitcnt lgkmcnt(5)
	v_mfma_f32_16x16x32_bf16 v[52:55], v[156:159], v[196:199], v[52:55]
	v_mfma_f32_16x16x32_bf16 v[48:51], v[164:167], v[196:199], v[48:51]
	s_waitcnt lgkmcnt(3)
	v_mfma_f32_16x16x32_bf16 v[44:47], v[156:159], v[204:207], v[44:47]
	v_mfma_f32_16x16x32_bf16 v[40:43], v[164:167], v[204:207], v[40:43]
	s_waitcnt lgkmcnt(1)
	v_mfma_f32_16x16x32_bf16 v[36:39], v[156:159], v[214:217], v[36:39]
	v_mfma_f32_16x16x32_bf16 v[32:35], v[164:167], v[214:217], v[32:35]
	v_mfma_f32_16x16x32_bf16 v[60:63], v[160:163], v[192:195], v[60:63]
	v_mfma_f32_16x16x32_bf16 v[56:59], v[168:171], v[192:195], v[56:59]
	v_mfma_f32_16x16x32_bf16 v[52:55], v[160:163], v[200:203], v[52:55]
	v_mfma_f32_16x16x32_bf16 v[48:51], v[168:171], v[200:203], v[48:51]
	v_mfma_f32_16x16x32_bf16 v[44:47], v[160:163], v[208:211], v[44:47]
	v_mfma_f32_16x16x32_bf16 v[40:43], v[168:171], v[208:211], v[40:43]
	s_waitcnt lgkmcnt(0)
	v_mfma_f32_16x16x32_bf16 v[36:39], v[160:163], v[218:221], v[36:39]
	v_mfma_f32_16x16x32_bf16 v[32:35], v[168:171], v[218:221], v[32:35]
	s_setprio 0
	s_setprio 1
	v_mfma_f32_16x16x32_bf16 v[28:31], v[172:175], v[188:191], v[28:31]
	v_mfma_f32_16x16x32_bf16 v[24:27], v[180:183], v[188:191], v[24:27]
	v_mfma_f32_16x16x32_bf16 v[20:23], v[172:175], v[196:199], v[20:23]
	v_mfma_f32_16x16x32_bf16 v[16:19], v[180:183], v[196:199], v[16:19]
	v_mfma_f32_16x16x32_bf16 v[12:15], v[172:175], v[204:207], v[12:15]
	v_mfma_f32_16x16x32_bf16 v[8:11], v[180:183], v[204:207], v[8:11]
	v_mfma_f32_16x16x32_bf16 v[4:7], v[172:175], v[214:217], v[4:7]
	v_mfma_f32_16x16x32_bf16 v[0:3], v[180:183], v[214:217], v[0:3]
	v_mfma_f32_16x16x32_bf16 v[28:31], v[176:179], v[192:195], v[28:31]
	v_mfma_f32_16x16x32_bf16 v[24:27], v[184:187], v[192:195], v[24:27]
	v_mfma_f32_16x16x32_bf16 v[20:23], v[176:179], v[200:203], v[20:23]
	v_mfma_f32_16x16x32_bf16 v[16:19], v[184:187], v[200:203], v[16:19]
	v_mfma_f32_16x16x32_bf16 v[12:15], v[176:179], v[208:211], v[12:15]
	v_mfma_f32_16x16x32_bf16 v[8:11], v[184:187], v[208:211], v[8:11]
	v_mfma_f32_16x16x32_bf16 v[4:7], v[176:179], v[218:221], v[4:7]
	v_mfma_f32_16x16x32_bf16 v[0:3], v[184:187], v[218:221], v[0:3]
	s_add_i32 s40, s40, 2
	s_addk_i32 s41, 0x100
	s_cmp_gt_u32 s40, 11
	s_setprio 0
	s_barrier
	s_cbranch_scc0 .LBB0_488
	ds_read_b128 v[156:159], v147
	ds_read_b128 v[160:163], v147 offset:1024
	ds_read_b128 v[164:167], v147 offset:2048
	ds_read_b128 v[168:171], v147 offset:3072
	ds_read_b128 v[172:175], v148
	ds_read_b128 v[176:179], v148 offset:1024
	ds_read_b128 v[180:183], v148 offset:2048
	ds_read_b128 v[184:187], v148 offset:3072
	s_or_b32 s6, s7, 0x780
	v_readfirstlane_b32 s7, v144
	s_mov_b32 m0, s7
	v_readfirstlane_b32 s7, v145
	ds_read_b128 v[188:191], v149
	ds_read_b128 v[192:195], v149 offset:1024
	ds_read_b128 v[196:199], v150
	ds_read_b128 v[200:203], v150 offset:1024
	ds_read_b128 v[204:207], v151
	ds_read_b128 v[208:211], v151 offset:1024
	ds_read_b128 v[214:217], v152
	ds_read_b128 v[218:221], v152 offset:1024
	buffer_load_dwordx4 v128, s[28:31], s6 offen lds
	s_mov_b32 m0, s7
	s_nop 0
	buffer_load_dwordx4 v129, s[28:31], s6 offen lds
	s_waitcnt vmcnt(8)
	s_waitcnt lgkmcnt(0)
	s_barrier
; #define LDA(dst, b, h) for (int m = 0; m < 4; ++m) for (int k = 0; k < 2; ++k) \
;     dst[m][k] = *reinterpret_cast<const bf16x8*>((char*)SA(b, h) + lds_byte(wr * 64 + m * 16 + fr, k * 32 + fq * 8))
; #define MMA(ai, bj, At, Bt_) do { __builtin_amdgcn_s_setprio(1); \
;     for (int m = 0; m < 4; ++m) for (int n = 0; n < 2; ++n) for (int k = 0; k < 2; ++k) \
;       acc[ai][bj][m][n] = __builtin_amdgcn_mfma_f32_16x16x32_bf16(Bt_[n][k], At[m][k], acc[ai][bj][m][n], 0, 0, 0); \
;     __builtin_amdgcn_s_setprio(0); } while (0)
; #define WAIT_V(n) asm volatile("s_waitcnt vmcnt(" #n ")" ::: "memory")
; #define WAIT_L(n) asm volatile("s_waitcnt lgkmcnt(" #n ")" ::: "memory")
; #define BAR __builtin_amdgcn_s_barrier()
; #define SCHED __builtin_amdgcn_sched_barrier(0)
; template <int MODE>
; DI void gemm_phase(const bf16_t* __restrict__ A, const bf16_t* __restrict__ Bt, int M, int N, int K, const Epi& ep) {
;     ...
;             WAIT_V(8); WAIT_L(0); BAR; MMA(0, 0, At, B0); MMA(0, 1, At, B1); BAR; SCHED;
;             LDA(At, 0, 1);
;             WAIT_V(2); WAIT_L(0); BAR; MMA(1, 0, At, B0); MMA(1, 1, At, B1); BAR; SCHED;
	s_setprio 1
	s_waitcnt lgkmcnt(7)
	v_mfma_f32_16x16x32_bf16 v[124:127], v[156:159], v[188:191], v[124:127]
	v_mfma_f32_16x16x32_bf16 v[120:123], v[164:167], v[188:191], v[120:123]
	s_waitcnt lgkmcnt(5)
	v_mfma_f32_16x16x32_bf16 v[116:119], v[156:159], v[196:199], v[116:119]
	v_mfma_f32_16x16x32_bf16 v[112:115], v[164:167], v[196:199], v[112:115]
	s_waitcnt lgkmcnt(3)
	v_mfma_f32_16x16x32_bf16 v[108:111], v[156:159], v[204:207], v[108:111]
	v_mfma_f32_16x16x32_bf16 v[124:127], v[160:163], v[192:195], v[124:127]
	v_mfma_f32_16x16x32_bf16 v[120:123], v[168:171], v[192:195], v[120:123]
	v_mfma_f32_16x16x32_bf16 v[116:119], v[160:163], v[200:203], v[116:119]
	v_mfma_f32_16x16x32_bf16 v[112:115], v[168:171], v[200:203], v[112:115]
	s_waitcnt lgkmcnt(2)
	v_mfma_f32_16x16x32_bf16 v[222:225], v[160:163], v[208:211], v[108:111]
	v_mfma_f32_16x16x32_bf16 v[104:107], v[164:167], v[204:207], v[104:107]
	s_waitcnt lgkmcnt(1)
	v_mfma_f32_16x16x32_bf16 v[100:103], v[156:159], v[214:217], v[100:103]
	v_mfma_f32_16x16x32_bf16 v[96:99], v[164:167], v[214:217], v[96:99]
	v_mfma_f32_16x16x32_bf16 v[226:229], v[168:171], v[208:211], v[104:107]
	s_waitcnt lgkmcnt(0)
	v_mfma_f32_16x16x32_bf16 v[230:233], v[160:163], v[218:221], v[100:103]
	v_mfma_f32_16x16x32_bf16 v[234:237], v[168:171], v[218:221], v[96:99]
	s_setprio 0
	s_setprio 1
	v_mfma_f32_16x16x32_bf16 v[92:95], v[172:175], v[188:191], v[92:95]
	v_mfma_f32_16x16x32_bf16 v[88:91], v[180:183], v[188:191], v[88:91]
	v_mfma_f32_16x16x32_bf16 v[84:87], v[172:175], v[196:199], v[84:87]
	v_mfma_f32_16x16x32_bf16 v[80:83], v[180:183], v[196:199], v[80:83]
	v_mfma_f32_16x16x32_bf16 v[92:95], v[176:179], v[192:195], v[92:95]
	v_mfma_f32_16x16x32_bf16 v[88:91], v[184:187], v[192:195], v[88:91]
	v_mfma_f32_16x16x32_bf16 v[84:87], v[176:179], v[200:203], v[84:87]
	v_mfma_f32_16x16x32_bf16 v[80:83], v[184:187], v[200:203], v[80:83]
	v_mfma_f32_16x16x32_bf16 v[76:79], v[172:175], v[204:207], v[76:79]
	v_mfma_f32_16x16x32_bf16 v[72:75], v[180:183], v[204:207], v[72:75]
	v_mfma_f32_16x16x32_bf16 v[68:71], v[172:175], v[214:217], v[68:71]
	v_mfma_f32_16x16x32_bf16 v[64:67], v[180:183], v[214:217], v[64:67]
	v_mfma_f32_16x16x32_bf16 v[188:191], v[176:179], v[208:211], v[76:79]
	v_mfma_f32_16x16x32_bf16 v[192:195], v[184:187], v[208:211], v[72:75]
	v_mfma_f32_16x16x32_bf16 v[196:199], v[176:179], v[218:221], v[68:71]
	v_mfma_f32_16x16x32_bf16 v[200:203], v[184:187], v[218:221], v[64:67]
	s_setprio 0
	s_barrier
	s_nop 1
	ds_read_b128 v[64:67], v149 offset:16384
	ds_read_b128 v[68:71], v149 offset:17408
	ds_read_b128 v[72:75], v150 offset:16384
	ds_read_b128 v[76:79], v150 offset:17408
	ds_read_b128 v[96:99], v151 offset:16384
	ds_read_b128 v[100:103], v151 offset:17408
	ds_read_b128 v[104:107], v152 offset:16384
	ds_read_b128 v[108:111], v152 offset:17408
	s_waitcnt vmcnt(2)
	s_waitcnt lgkmcnt(0)
	s_barrier
	s_setprio 1
	s_waitcnt lgkmcnt(7)
	v_mfma_f32_16x16x32_bf16 v[60:63], v[156:159], v[64:67], v[60:63]
	v_mfma_f32_16x16x32_bf16 v[56:59], v[164:167], v[64:67], v[56:59]
	s_waitcnt lgkmcnt(5)
	v_mfma_f32_16x16x32_bf16 v[52:55], v[156:159], v[72:75], v[52:55]
	v_mfma_f32_16x16x32_bf16 v[48:51], v[164:167], v[72:75], v[48:51]
	v_mfma_f32_16x16x32_bf16 v[60:63], v[160:163], v[68:71], v[60:63]
	v_mfma_f32_16x16x32_bf16 v[56:59], v[168:171], v[68:71], v[56:59]
	s_waitcnt lgkmcnt(4)
	v_mfma_f32_16x16x32_bf16 v[52:55], v[160:163], v[76:79], v[52:55]
	v_mfma_f32_16x16x32_bf16 v[48:51], v[168:171], v[76:79], v[48:51]
	s_waitcnt lgkmcnt(3)
	v_mfma_f32_16x16x32_bf16 v[44:47], v[156:159], v[96:99], v[44:47]
	v_mfma_f32_16x16x32_bf16 v[40:43], v[164:167], v[96:99], v[40:43]
	s_waitcnt lgkmcnt(1)
	v_mfma_f32_16x16x32_bf16 v[36:39], v[156:159], v[104:107], v[36:39]
	v_mfma_f32_16x16x32_bf16 v[32:35], v[164:167], v[104:107], v[32:35]
	v_mfma_f32_16x16x32_bf16 v[204:207], v[160:163], v[100:103], v[44:47]
	v_mfma_f32_16x16x32_bf16 v[208:211], v[168:171], v[100:103], v[40:43]
	s_waitcnt lgkmcnt(0)
	v_mfma_f32_16x16x32_bf16 v[156:159], v[160:163], v[108:111], v[36:39]
	v_mfma_f32_16x16x32_bf16 v[160:163], v[168:171], v[108:111], v[32:35]
	s_setprio 0
	s_setprio 1
	v_mfma_f32_16x16x32_bf16 v[28:31], v[172:175], v[64:67], v[28:31]
	v_mfma_f32_16x16x32_bf16 v[24:27], v[180:183], v[64:67], v[24:27]
	v_mfma_f32_16x16x32_bf16 v[20:23], v[172:175], v[72:75], v[20:23]
	v_mfma_f32_16x16x32_bf16 v[16:19], v[180:183], v[72:75], v[16:19]
	v_mfma_f32_16x16x32_bf16 v[28:31], v[176:179], v[68:71], v[28:31]
	v_mfma_f32_16x16x32_bf16 v[24:27], v[184:187], v[68:71], v[24:27]
	v_mfma_f32_16x16x32_bf16 v[20:23], v[176:179], v[76:79], v[20:23]
	v_mfma_f32_16x16x32_bf16 v[16:19], v[184:187], v[76:79], v[16:19]
	v_mfma_f32_16x16x32_bf16 v[12:15], v[172:175], v[96:99], v[12:15]
	v_mfma_f32_16x16x32_bf16 v[8:11], v[180:183], v[96:99], v[8:11]
	v_mfma_f32_16x16x32_bf16 v[4:7], v[172:175], v[104:107], v[4:7]
	v_mfma_f32_16x16x32_bf16 v[0:3], v[180:183], v[104:107], v[0:3]
	v_mfma_f32_16x16x32_bf16 v[164:167], v[176:179], v[100:103], v[12:15]
	v_mfma_f32_16x16x32_bf16 v[168:171], v[184:187], v[100:103], v[8:11]
	v_mfma_f32_16x16x32_bf16 v[172:175], v[176:179], v[108:111], v[4:7]
	v_mfma_f32_16x16x32_bf16 v[176:179], v[184:187], v[108:111], v[0:3]
	s_setprio 0
	s_barrier
; #define LDA(dst, b, h) for (int m = 0; m < 4; ++m) for (int k = 0; k < 2; ++k) \
;     dst[m][k] = *reinterpret_cast<const bf16x8*>((char*)SA(b, h) + lds_byte(wr * 64 + m * 16 + fr, k * 32 + fq * 8))
; #define LDB(dst, b, h) for (int n = 0; n < 2; ++n) for (int k = 0; k < 2; ++k) \
;     dst[n][k] = *reinterpret_cast<const bf16x8*>((char*)SB(b, h) + lds_byte(wc * 32 + n * 16 + fr, k * 32 + fq * 8))
; #define MMA(ai, bj, At, Bt_) do { __builtin_amdgcn_s_setprio(1); \
;     for (int m = 0; m < 4; ++m) for (int n = 0; n < 2; ++n) for (int k = 0; k < 2; ++k) \
;       acc[ai][bj][m][n] = __builtin_amdgcn_mfma_f32_16x16x32_bf16(Bt_[n][k], At[m][k], acc[ai][bj][m][n], 0, 0, 0); \
;     __builtin_amdgcn_s_setprio(0); } while (0)
; #define WAIT_V(n) asm volatile("s_waitcnt vmcnt(" #n ")" ::: "memory")
; #define WAIT_L(n) asm volatile("s_waitcnt lgkmcnt(" #n ")" ::: "memory")
; #define BAR __builtin_amdgcn_s_barrier()
; #define SCHED __builtin_amdgcn_sched_barrier(0)
; template <int MODE>
; DI void gemm_phase(const bf16_t* __restrict__ A, const bf16_t* __restrict__ Bt, int M, int N, int K, const Epi& ep) {
;     ...
;             LDB(B0, 1, 0); LDB(B1, 1, 1); SCHED; LDA(At, 1, 0);
;             WAIT_V(0); WAIT_L(0); BAR; MMA(0, 0, At, B0); MMA(0, 1, At, B1); BAR; SCHED;
;             LDA(At, 1, 1);
;             WAIT_L(0); BAR; MMA(1, 0, At, B0); MMA(1, 1, At, B1); BAR; SCHED;
;         }
;         if (wr == 0) BAR;
	s_nop 1
	ds_read_b128 v[0:3], v153
	ds_read_b128 v[4:7], v153 offset:1024
	ds_read_b128 v[8:11], v153 offset:2048
	ds_read_b128 v[12:15], v153 offset:3072
	ds_read_b128 v[180:183], v154
	ds_read_b128 v[184:187], v154 offset:1024
	ds_read_b128 v[214:217], v154 offset:2048
	ds_read_b128 v[218:221], v154 offset:3072
	ds_read_b128 v[32:35], v149 offset:32768
	ds_read_b128 v[36:39], v149 offset:33792
	ds_read_b128 v[40:43], v150 offset:32768
	ds_read_b128 v[44:47], v150 offset:33792
	ds_read_b128 v[238:241], v151 offset:32768
	ds_read_b128 v[242:245], v151 offset:33792
	ds_read_b128 v[246:249], v152 offset:32768
	ds_read_b128 v[64:67], v152 offset:33792
	s_waitcnt vmcnt(0)
	s_waitcnt lgkmcnt(0)
	s_barrier
	s_setprio 1
	s_waitcnt lgkmcnt(7)
	v_mfma_f32_16x16x32_bf16 v[68:71], v[0:3], v[32:35], v[124:127]
	s_waitcnt lgkmcnt(6)
	v_mfma_f32_16x16x32_bf16 v[96:99], v[4:7], v[36:39], v[68:71]
	v_mfma_f32_16x16x32_bf16 v[68:71], v[8:11], v[32:35], v[120:123]
	v_mfma_f32_16x16x32_bf16 v[100:103], v[12:15], v[36:39], v[68:71]
	s_waitcnt lgkmcnt(5)
	v_mfma_f32_16x16x32_bf16 v[68:71], v[0:3], v[40:43], v[116:119]
	s_waitcnt lgkmcnt(4)
	v_mfma_f32_16x16x32_bf16 v[104:107], v[4:7], v[44:47], v[68:71]
	v_mfma_f32_16x16x32_bf16 v[68:71], v[8:11], v[40:43], v[112:115]
	v_mfma_f32_16x16x32_bf16 v[108:111], v[12:15], v[44:47], v[68:71]
	s_waitcnt lgkmcnt(3)
	v_mfma_f32_16x16x32_bf16 v[68:71], v[0:3], v[238:241], v[222:225]
	s_waitcnt lgkmcnt(2)
	v_mfma_f32_16x16x32_bf16 v[112:115], v[4:7], v[242:245], v[68:71]
	v_mfma_f32_16x16x32_bf16 v[68:71], v[8:11], v[238:241], v[226:229]
	v_mfma_f32_16x16x32_bf16 v[116:119], v[12:15], v[242:245], v[68:71]
	s_waitcnt lgkmcnt(1)
	v_mfma_f32_16x16x32_bf16 v[68:71], v[0:3], v[246:249], v[230:233]
	s_waitcnt lgkmcnt(0)
	v_mfma_f32_16x16x32_bf16 v[120:123], v[4:7], v[64:67], v[68:71]
	v_mfma_f32_16x16x32_bf16 v[68:71], v[8:11], v[246:249], v[234:237]
	v_mfma_f32_16x16x32_bf16 v[124:127], v[12:15], v[64:67], v[68:71]
	s_setprio 0
	s_setprio 1
	v_mfma_f32_16x16x32_bf16 v[68:71], v[180:183], v[32:35], v[92:95]
	v_mfma_f32_16x16x32_bf16 v[32:35], v[214:217], v[32:35], v[88:91]
	v_mfma_f32_16x16x32_bf16 v[222:225], v[184:187], v[36:39], v[68:71]
	v_mfma_f32_16x16x32_bf16 v[68:71], v[218:221], v[36:39], v[32:35]
	v_mfma_f32_16x16x32_bf16 v[32:35], v[180:183], v[40:43], v[84:87]
	v_mfma_f32_16x16x32_bf16 v[72:75], v[184:187], v[44:47], v[32:35]
	v_mfma_f32_16x16x32_bf16 v[32:35], v[214:217], v[40:43], v[80:83]
	v_mfma_f32_16x16x32_bf16 v[76:79], v[218:221], v[44:47], v[32:35]
	v_mfma_f32_16x16x32_bf16 v[32:35], v[180:183], v[238:241], v[188:191]
	v_mfma_f32_16x16x32_bf16 v[80:83], v[184:187], v[242:245], v[32:35]
	v_mfma_f32_16x16x32_bf16 v[32:35], v[214:217], v[238:241], v[192:195]
	v_mfma_f32_16x16x32_bf16 v[84:87], v[218:221], v[242:245], v[32:35]
	v_mfma_f32_16x16x32_bf16 v[32:35], v[180:183], v[246:249], v[196:199]
	v_mfma_f32_16x16x32_bf16 v[88:91], v[184:187], v[64:67], v[32:35]
	v_mfma_f32_16x16x32_bf16 v[32:35], v[214:217], v[246:249], v[200:203]
	v_mfma_f32_16x16x32_bf16 v[92:95], v[218:221], v[64:67], v[32:35]
	s_setprio 0
	s_barrier
	ds_read_b128 v[64:67], v149 offset:49152
	ds_read_b128 v[188:191], v149 offset:50176
	ds_read_b128 v[192:195], v150 offset:49152
	ds_read_b128 v[196:199], v150 offset:50176
	ds_read_b128 v[200:203], v151 offset:49152
	ds_read_b128 v[226:229], v151 offset:50176
	ds_read_b128 v[230:233], v152 offset:49152
	ds_read_b128 v[234:237], v152 offset:50176
	s_waitcnt lgkmcnt(0)
	s_barrier
	s_setprio 1
	s_waitcnt lgkmcnt(7)
	v_mfma_f32_16x16x32_bf16 v[32:35], v[0:3], v[64:67], v[60:63]
	s_waitcnt lgkmcnt(5)
	v_mfma_f32_16x16x32_bf16 v[40:43], v[0:3], v[192:195], v[52:55]
	v_mfma_f32_16x16x32_bf16 v[44:47], v[8:11], v[192:195], v[48:51]
	s_waitcnt lgkmcnt(3)
	v_mfma_f32_16x16x32_bf16 v[48:51], v[0:3], v[200:203], v[204:207]
	s_waitcnt lgkmcnt(1)
	v_mfma_f32_16x16x32_bf16 v[0:3], v[0:3], v[230:233], v[156:159]
	v_mfma_f32_16x16x32_bf16 v[36:39], v[8:11], v[64:67], v[56:59]
	v_mfma_f32_16x16x32_bf16 v[52:55], v[8:11], v[200:203], v[208:211]
	s_waitcnt lgkmcnt(0)
	v_mfma_f32_16x16x32_bf16 v[56:59], v[4:7], v[234:237], v[0:3]
	v_mfma_f32_16x16x32_bf16 v[0:3], v[8:11], v[230:233], v[160:163]
	v_mfma_f32_16x16x32_bf16 v[32:35], v[4:7], v[188:191], v[32:35]
	v_mfma_f32_16x16x32_bf16 v[36:39], v[12:15], v[188:191], v[36:39]
	v_mfma_f32_16x16x32_bf16 v[40:43], v[4:7], v[196:199], v[40:43]
	v_mfma_f32_16x16x32_bf16 v[44:47], v[12:15], v[196:199], v[44:47]
	v_mfma_f32_16x16x32_bf16 v[48:51], v[4:7], v[226:229], v[48:51]
	v_mfma_f32_16x16x32_bf16 v[52:55], v[12:15], v[226:229], v[52:55]
	v_mfma_f32_16x16x32_bf16 v[60:63], v[12:15], v[234:237], v[0:3]
	s_setprio 0
	s_setprio 1
	v_mfma_f32_16x16x32_bf16 v[0:3], v[180:183], v[64:67], v[28:31]
	v_mfma_f32_16x16x32_bf16 v[4:7], v[214:217], v[64:67], v[24:27]
	v_mfma_f32_16x16x32_bf16 v[8:11], v[180:183], v[192:195], v[20:23]
	v_mfma_f32_16x16x32_bf16 v[12:15], v[214:217], v[192:195], v[16:19]
	v_mfma_f32_16x16x32_bf16 v[16:19], v[180:183], v[200:203], v[164:167]
	v_mfma_f32_16x16x32_bf16 v[20:23], v[214:217], v[200:203], v[168:171]
	v_mfma_f32_16x16x32_bf16 v[24:27], v[180:183], v[230:233], v[172:175]
	v_mfma_f32_16x16x32_bf16 v[28:31], v[214:217], v[230:233], v[176:179]
	v_mfma_f32_16x16x32_bf16 v[0:3], v[184:187], v[188:191], v[0:3]
	v_mfma_f32_16x16x32_bf16 v[4:7], v[218:221], v[188:191], v[4:7]
	v_mfma_f32_16x16x32_bf16 v[8:11], v[184:187], v[196:199], v[8:11]
	v_mfma_f32_16x16x32_bf16 v[12:15], v[218:221], v[196:199], v[12:15]
	v_mfma_f32_16x16x32_bf16 v[16:19], v[184:187], v[226:229], v[16:19]
	v_mfma_f32_16x16x32_bf16 v[20:23], v[218:221], v[226:229], v[20:23]
	v_mfma_f32_16x16x32_bf16 v[24:27], v[184:187], v[234:237], v[24:27]
	v_mfma_f32_16x16x32_bf16 v[28:31], v[218:221], v[234:237], v[28:31]
	s_setprio 0
	s_barrier
	s_and_saveexec_b64 s[6:7], s[38:39]
	s_cbranch_execz .LBB0_480
	s_barrier
	s_branch .LBB0_480

; #define LDA(dst, b, h) for (int m = 0; m < 4; ++m) for (int k = 0; k < 2; ++k) \
;     dst[m][k] = *reinterpret_cast<const bf16x8*>((char*)SA(b, h) + lds_byte(wr * 64 + m * 16 + fr, k * 32 + fq * 8))
; #define LDB(dst, b, h) for (int n = 0; n < 2; ++n) for (int k = 0; k < 2; ++k) \
;     dst[n][k] = *reinterpret_cast<const bf16x8*>((char*)SB(b, h) + lds_byte(wc * 32 + n * 16 + fr, k * 32 + fq * 8))
; #define MMA(ai, bj, At, Bt_) do { __builtin_amdgcn_s_setprio(1); \
;     for (int m = 0; m < 4; ++m) for (int n = 0; n < 2; ++n) for (int k = 0; k < 2; ++k) \
;       acc[ai][bj][m][n] = __builtin_amdgcn_mfma_f32_16x16x32_bf16(Bt_[n][k], At[m][k], acc[ai][bj][m][n], 0, 0, 0); \
;     __builtin_amdgcn_s_setprio(0); } while (0)
; #define WAIT_V(n) asm volatile("s_waitcnt vmcnt(" #n ")" ::: "memory")
; #define WAIT_L(n) asm volatile("s_waitcnt lgkmcnt(" #n ")" ::: "memory")
; #define BAR __builtin_amdgcn_s_barrier()
; #define SCHED __builtin_amdgcn_sched_barrier(0)
; template <int MODE>
; DI void gemm_phase(const bf16_t* __restrict__ A, const bf16_t* __restrict__ Bt, int M, int N, int K, const Epi& ep) {
;     ...
;             LDB(B0, 0, 0); LDB(B1, 0, 1); SCHED; LDA(At, 0, 0); STAGE(SA(1, 1), rsA, brow + HALF, t + 1);
;             WAIT_V(8); WAIT_L(0); BAR; MMA(0, 0, At, B0); MMA(0, 1, At, B1); BAR; SCHED;
;             LDA(At, 0, 1); STAGE(SB(0, 0), rsB, bcol, t + 2); STAGE(SB(0, 1), rsB, bcol + HALF, t + 2); STAGE(SA(0, 0), rsA, brow, t + 2);
.LBB0_558:
	ds_read_b128 v[156:159], v147
	ds_read_b128 v[160:163], v147 offset:1024
	ds_read_b128 v[164:167], v147 offset:2048
	ds_read_b128 v[168:171], v147 offset:3072
	ds_read_b128 v[172:175], v148
	ds_read_b128 v[176:179], v148 offset:1024
	ds_read_b128 v[180:183], v148 offset:2048
	ds_read_b128 v[184:187], v148 offset:3072
	s_add_i32 s40, s27, s31
	v_readfirstlane_b32 s7, v144
	s_add_i32 s6, s40, 0x40080
	s_mov_b32 m0, s7
	v_readfirstlane_b32 s7, v145
	ds_read_b128 v[188:191], v149
	ds_read_b128 v[192:195], v149 offset:1024
	ds_read_b128 v[196:199], v150
	ds_read_b128 v[200:203], v150 offset:1024
	ds_read_b128 v[204:207], v151
	ds_read_b128 v[208:211], v151 offset:1024
	ds_read_b128 v[214:217], v152
	ds_read_b128 v[218:221], v152 offset:1024
	buffer_load_dwordx4 v128, s[8:11], s6 offen lds
	s_mov_b32 m0, s7
	s_nop 0
	buffer_load_dwordx4 v129, s[8:11], s6 offen lds
	s_waitcnt vmcnt(8)
	s_waitcnt lgkmcnt(0)
	s_barrier
	s_setprio 1
	s_waitcnt lgkmcnt(7)
	v_mfma_f32_16x16x32_bf16 v[124:127], v[156:159], v[188:191], v[124:127]
	v_mfma_f32_16x16x32_bf16 v[120:123], v[164:167], v[188:191], v[120:123]
	s_waitcnt lgkmcnt(5)
	v_mfma_f32_16x16x32_bf16 v[116:119], v[156:159], v[196:199], v[116:119]
	v_mfma_f32_16x16x32_bf16 v[112:115], v[164:167], v[196:199], v[112:115]
	s_waitcnt lgkmcnt(3)
	v_mfma_f32_16x16x32_bf16 v[108:111], v[156:159], v[204:207], v[108:111]
	v_mfma_f32_16x16x32_bf16 v[104:107], v[164:167], v[204:207], v[104:107]
	s_waitcnt lgkmcnt(1)
	v_mfma_f32_16x16x32_bf16 v[100:103], v[156:159], v[214:217], v[100:103]
	v_mfma_f32_16x16x32_bf16 v[96:99], v[164:167], v[214:217], v[96:99]
	v_mfma_f32_16x16x32_bf16 v[124:127], v[160:163], v[192:195], v[124:127]
	v_mfma_f32_16x16x32_bf16 v[120:123], v[168:171], v[192:195], v[120:123]
	v_mfma_f32_16x16x32_bf16 v[116:119], v[160:163], v[200:203], v[116:119]
	v_mfma_f32_16x16x32_bf16 v[112:115], v[168:171], v[200:203], v[112:115]
	v_mfma_f32_16x16x32_bf16 v[108:111], v[160:163], v[208:211], v[108:111]
	v_mfma_f32_16x16x32_bf16 v[104:107], v[168:171], v[208:211], v[104:107]
	s_waitcnt lgkmcnt(0)
	v_mfma_f32_16x16x32_bf16 v[100:103], v[160:163], v[218:221], v[100:103]
	v_mfma_f32_16x16x32_bf16 v[96:99], v[168:171], v[218:221], v[96:99]
	s_setprio 0
	s_setprio 1
	v_mfma_f32_16x16x32_bf16 v[92:95], v[172:175], v[188:191], v[92:95]
	v_mfma_f32_16x16x32_bf16 v[88:91], v[180:183], v[188:191], v[88:91]
	v_mfma_f32_16x16x32_bf16 v[84:87], v[172:175], v[196:199], v[84:87]
	v_mfma_f32_16x16x32_bf16 v[80:83], v[180:183], v[196:199], v[80:83]
	v_mfma_f32_16x16x32_bf16 v[76:79], v[172:175], v[204:207], v[76:79]
	v_mfma_f32_16x16x32_bf16 v[72:75], v[180:183], v[204:207], v[72:75]
	v_mfma_f32_16x16x32_bf16 v[68:71], v[172:175], v[214:217], v[68:71]
	v_mfma_f32_16x16x32_bf16 v[64:67], v[180:183], v[214:217], v[64:67]
	v_mfma_f32_16x16x32_bf16 v[92:95], v[176:179], v[192:195], v[92:95]
	v_mfma_f32_16x16x32_bf16 v[88:91], v[184:187], v[192:195], v[88:91]
	v_mfma_f32_16x16x32_bf16 v[84:87], v[176:179], v[200:203], v[84:87]
	v_mfma_f32_16x16x32_bf16 v[80:83], v[184:187], v[200:203], v[80:83]
	v_mfma_f32_16x16x32_bf16 v[76:79], v[176:179], v[208:211], v[76:79]
	v_mfma_f32_16x16x32_bf16 v[72:75], v[184:187], v[208:211], v[72:75]
	v_mfma_f32_16x16x32_bf16 v[68:71], v[176:179], v[218:221], v[68:71]
	v_mfma_f32_16x16x32_bf16 v[64:67], v[184:187], v[218:221], v[64:67]
	s_setprio 0
	s_barrier
	s_add_i32 s41, s23, s31
	v_readfirstlane_b32 s43, v130
	s_add_i32 s42, s41, 0x100
	s_mov_b32 s6, s10
	s_mov_b32 s7, s11
	s_mov_b32 m0, s43
	v_readfirstlane_b32 s43, v131
	ds_read_b128 v[188:191], v149 offset:16384
	ds_read_b128 v[192:195], v149 offset:17408
	ds_read_b128 v[196:199], v150 offset:16384
	ds_read_b128 v[200:203], v150 offset:17408
	ds_read_b128 v[204:207], v151 offset:16384
	ds_read_b128 v[208:211], v151 offset:17408
	ds_read_b128 v[214:217], v152 offset:16384
	ds_read_b128 v[218:221], v152 offset:17408
	buffer_load_dwordx4 v128, s[4:7], s42 offen lds
	s_mov_b32 m0, s43
	v_readfirstlane_b32 s43, v132
	buffer_load_dwordx4 v129, s[4:7], s42 offen lds
	s_add_i32 s42, s41, 0x40100
	s_mov_b32 m0, s43
	v_readfirstlane_b32 s43, v133
	buffer_load_dwordx4 v128, s[4:7], s42 offen lds
	s_mov_b32 m0, s43
	v_readfirstlane_b32 s43, v134
	buffer_load_dwordx4 v129, s[4:7], s42 offen lds
	s_add_i32 s42, s40, 0x100
	s_mov_b32 m0, s43
	v_readfirstlane_b32 s43, v135
	buffer_load_dwordx4 v128, s[8:11], s42 offen lds
	s_mov_b32 m0, s43
	s_nop 0
	buffer_load_dwordx4 v129, s[8:11], s42 offen lds
	s_waitcnt vmcnt(8)
	s_waitcnt lgkmcnt(0)
	s_barrier
; #define LDA(dst, b, h) for (int m = 0; m < 4; ++m) for (int k = 0; k < 2; ++k) \
;     dst[m][k] = *reinterpret_cast<const bf16x8*>((char*)SA(b, h) + lds_byte(wr * 64 + m * 16 + fr, k * 32 + fq * 8))
; #define LDB(dst, b, h) for (int n = 0; n < 2; ++n) for (int k = 0; k < 2; ++k) \
;     dst[n][k] = *reinterpret_cast<const bf16x8*>((char*)SB(b, h) + lds_byte(wc * 32 + n * 16 + fr, k * 32 + fq * 8))
; #define MMA(ai, bj, At, Bt_) do { __builtin_amdgcn_s_setprio(1); \
;     for (int m = 0; m < 4; ++m) for (int n = 0; n < 2; ++n) for (int k = 0; k < 2; ++k) \
;       acc[ai][bj][m][n] = __builtin_amdgcn_mfma_f32_16x16x32_bf16(Bt_[n][k], At[m][k], acc[ai][bj][m][n], 0, 0, 0); \
;     __builtin_amdgcn_s_setprio(0); } while (0)
; #define WAIT_V(n) asm volatile("s_waitcnt vmcnt(" #n ")" ::: "memory")
; #define WAIT_L(n) asm volatile("s_waitcnt lgkmcnt(" #n ")" ::: "memory")
; #define BAR __builtin_amdgcn_s_barrier()
; #define SCHED __builtin_amdgcn_sched_barrier(0)
; template <int MODE>
; DI void gemm_phase(const bf16_t* __restrict__ A, const bf16_t* __restrict__ Bt, int M, int N, int K, const Epi& ep) {
;     ...
;             WAIT_V(8); WAIT_L(0); BAR; MMA(1, 0, At, B0); MMA(1, 1, At, B1); BAR; SCHED;
;             LDB(B0, 1, 0); LDB(B1, 1, 1); SCHED; LDA(At, 1, 0); STAGE(SA(0, 1), rsA, brow + HALF, t + 2);
;             WAIT_V(8); WAIT_L(0); BAR; MMA(0, 0, At, B0); MMA(0, 1, At, B1); BAR; SCHED;
	s_setprio 1
	s_waitcnt lgkmcnt(7)
	v_mfma_f32_16x16x32_bf16 v[60:63], v[156:159], v[188:191], v[60:63]
	v_mfma_f32_16x16x32_bf16 v[56:59], v[164:167], v[188:191], v[56:59]
	s_waitcnt lgkmcnt(5)
	v_mfma_f32_16x16x32_bf16 v[52:55], v[156:159], v[196:199], v[52:55]
	v_mfma_f32_16x16x32_bf16 v[48:51], v[164:167], v[196:199], v[48:51]
	s_waitcnt lgkmcnt(3)
	v_mfma_f32_16x16x32_bf16 v[44:47], v[156:159], v[204:207], v[44:47]
	v_mfma_f32_16x16x32_bf16 v[40:43], v[164:167], v[204:207], v[40:43]
	s_waitcnt lgkmcnt(1)
	v_mfma_f32_16x16x32_bf16 v[36:39], v[156:159], v[214:217], v[36:39]
	v_mfma_f32_16x16x32_bf16 v[32:35], v[164:167], v[214:217], v[32:35]
	v_mfma_f32_16x16x32_bf16 v[60:63], v[160:163], v[192:195], v[60:63]
	v_mfma_f32_16x16x32_bf16 v[56:59], v[168:171], v[192:195], v[56:59]
	v_mfma_f32_16x16x32_bf16 v[52:55], v[160:163], v[200:203], v[52:55]
	v_mfma_f32_16x16x32_bf16 v[48:51], v[168:171], v[200:203], v[48:51]
	v_mfma_f32_16x16x32_bf16 v[44:47], v[160:163], v[208:211], v[44:47]
	v_mfma_f32_16x16x32_bf16 v[40:43], v[168:171], v[208:211], v[40:43]
	s_waitcnt lgkmcnt(0)
	v_mfma_f32_16x16x32_bf16 v[36:39], v[160:163], v[218:221], v[36:39]
	v_mfma_f32_16x16x32_bf16 v[32:35], v[168:171], v[218:221], v[32:35]
	s_setprio 0
	s_setprio 1
	v_mfma_f32_16x16x32_bf16 v[28:31], v[172:175], v[188:191], v[28:31]
	v_mfma_f32_16x16x32_bf16 v[24:27], v[180:183], v[188:191], v[24:27]
	v_mfma_f32_16x16x32_bf16 v[20:23], v[172:175], v[196:199], v[20:23]
	v_mfma_f32_16x16x32_bf16 v[16:19], v[180:183], v[196:199], v[16:19]
	v_mfma_f32_16x16x32_bf16 v[12:15], v[172:175], v[204:207], v[12:15]
	v_mfma_f32_16x16x32_bf16 v[8:11], v[180:183], v[204:207], v[8:11]
	v_mfma_f32_16x16x32_bf16 v[4:7], v[172:175], v[214:217], v[4:7]
	v_mfma_f32_16x16x32_bf16 v[0:3], v[180:183], v[214:217], v[0:3]
	v_mfma_f32_16x16x32_bf16 v[28:31], v[176:179], v[192:195], v[28:31]
	v_mfma_f32_16x16x32_bf16 v[24:27], v[184:187], v[192:195], v[24:27]
	v_mfma_f32_16x16x32_bf16 v[20:23], v[176:179], v[200:203], v[20:23]
	v_mfma_f32_16x16x32_bf16 v[16:19], v[184:187], v[200:203], v[16:19]
	v_mfma_f32_16x16x32_bf16 v[12:15], v[176:179], v[208:211], v[12:15]
	v_mfma_f32_16x16x32_bf16 v[8:11], v[184:187], v[208:211], v[8:11]
	v_mfma_f32_16x16x32_bf16 v[4:7], v[176:179], v[218:221], v[4:7]
	v_mfma_f32_16x16x32_bf16 v[0:3], v[184:187], v[218:221], v[0:3]
	s_setprio 0
	s_barrier
	ds_read_b128 v[156:159], v153
	ds_read_b128 v[160:163], v153 offset:1024
	ds_read_b128 v[164:167], v153 offset:2048
	ds_read_b128 v[168:171], v153 offset:3072
	ds_read_b128 v[172:175], v154
	ds_read_b128 v[176:179], v154 offset:1024
	ds_read_b128 v[180:183], v154 offset:2048
	ds_read_b128 v[184:187], v154 offset:3072
	v_readfirstlane_b32 s43, v136
	s_add_i32 s42, s40, 0x40100
	s_mov_b32 m0, s43
	v_readfirstlane_b32 s43, v137
	ds_read_b128 v[188:191], v149 offset:32768
	ds_read_b128 v[192:195], v149 offset:33792
	ds_read_b128 v[196:199], v150 offset:32768
	ds_read_b128 v[200:203], v150 offset:33792
	ds_read_b128 v[204:207], v151 offset:32768
	ds_read_b128 v[208:211], v151 offset:33792
	ds_read_b128 v[214:217], v152 offset:32768
	ds_read_b128 v[218:221], v152 offset:33792
	buffer_load_dwordx4 v128, s[8:11], s42 offen lds
	s_mov_b32 m0, s43
	s_nop 0
	buffer_load_dwordx4 v129, s[8:11], s42 offen lds
	s_waitcnt vmcnt(8)
	s_waitcnt lgkmcnt(0)
	s_barrier
	s_setprio 1
	s_waitcnt lgkmcnt(7)
	v_mfma_f32_16x16x32_bf16 v[124:127], v[156:159], v[188:191], v[124:127]
	v_mfma_f32_16x16x32_bf16 v[120:123], v[164:167], v[188:191], v[120:123]
	s_waitcnt lgkmcnt(5)
	v_mfma_f32_16x16x32_bf16 v[116:119], v[156:159], v[196:199], v[116:119]
	v_mfma_f32_16x16x32_bf16 v[112:115], v[164:167], v[196:199], v[112:115]
	s_waitcnt lgkmcnt(3)
	v_mfma_f32_16x16x32_bf16 v[108:111], v[156:159], v[204:207], v[108:111]
	v_mfma_f32_16x16x32_bf16 v[104:107], v[164:167], v[204:207], v[104:107]
	s_waitcnt lgkmcnt(1)
	v_mfma_f32_16x16x32_bf16 v[100:103], v[156:159], v[214:217], v[100:103]
	v_mfma_f32_16x16x32_bf16 v[96:99], v[164:167], v[214:217], v[96:99]
	v_mfma_f32_16x16x32_bf16 v[124:127], v[160:163], v[192:195], v[124:127]
	v_mfma_f32_16x16x32_bf16 v[120:123], v[168:171], v[192:195], v[120:123]
	v_mfma_f32_16x16x32_bf16 v[116:119], v[160:163], v[200:203], v[116:119]
	v_mfma_f32_16x16x32_bf16 v[112:115], v[168:171], v[200:203], v[112:115]
	v_mfma_f32_16x16x32_bf16 v[108:111], v[160:163], v[208:211], v[108:111]
	v_mfma_f32_16x16x32_bf16 v[104:107], v[168:171], v[208:211], v[104:107]
	s_waitcnt lgkmcnt(0)
	v_mfma_f32_16x16x32_bf16 v[100:103], v[160:163], v[218:221], v[100:103]
	v_mfma_f32_16x16x32_bf16 v[96:99], v[168:171], v[218:221], v[96:99]
	s_setprio 0
	s_setprio 1
	v_mfma_f32_16x16x32_bf16 v[92:95], v[172:175], v[188:191], v[92:95]
	v_mfma_f32_16x16x32_bf16 v[88:91], v[180:183], v[188:191], v[88:91]
	v_mfma_f32_16x16x32_bf16 v[84:87], v[172:175], v[196:199], v[84:87]
	v_mfma_f32_16x16x32_bf16 v[80:83], v[180:183], v[196:199], v[80:83]
	v_mfma_f32_16x16x32_bf16 v[76:79], v[172:175], v[204:207], v[76:79]
	v_mfma_f32_16x16x32_bf16 v[72:75], v[180:183], v[204:207], v[72:75]
	v_mfma_f32_16x16x32_bf16 v[68:71], v[172:175], v[214:217], v[68:71]
	v_mfma_f32_16x16x32_bf16 v[64:67], v[180:183], v[214:217], v[64:67]
	v_mfma_f32_16x16x32_bf16 v[92:95], v[176:179], v[192:195], v[92:95]
	v_mfma_f32_16x16x32_bf16 v[88:91], v[184:187], v[192:195], v[88:91]
	v_mfma_f32_16x16x32_bf16 v[84:87], v[176:179], v[200:203], v[84:87]
	v_mfma_f32_16x16x32_bf16 v[80:83], v[184:187], v[200:203], v[80:83]
	v_mfma_f32_16x16x32_bf16 v[76:79], v[176:179], v[208:211], v[76:79]
	v_mfma_f32_16x16x32_bf16 v[72:75], v[184:187], v[208:211], v[72:75]
	v_mfma_f32_16x16x32_bf16 v[68:71], v[176:179], v[218:221], v[68:71]
	v_mfma_f32_16x16x32_bf16 v[64:67], v[184:187], v[218:221], v[64:67]
	s_setprio 0
	s_barrier
; #define LDA(dst, b, h) for (int m = 0; m < 4; ++m) for (int k = 0; k < 2; ++k) \
;     dst[m][k] = *reinterpret_cast<const bf16x8*>((char*)SA(b, h) + lds_byte(wr * 64 + m * 16 + fr, k * 32 + fq * 8))
; #define LDB(dst, b, h) for (int n = 0; n < 2; ++n) for (int k = 0; k < 2; ++k) \
;     dst[n][k] = *reinterpret_cast<const bf16x8*>((char*)SB(b, h) + lds_byte(wc * 32 + n * 16 + fr, k * 32 + fq * 8))
; #define MMA(ai, bj, At, Bt_) do { __builtin_amdgcn_s_setprio(1); \
;     for (int m = 0; m < 4; ++m) for (int n = 0; n < 2; ++n) for (int k = 0; k < 2; ++k) \
;       acc[ai][bj][m][n] = __builtin_amdgcn_mfma_f32_16x16x32_bf16(Bt_[n][k], At[m][k], acc[ai][bj][m][n], 0, 0, 0); \
;     __builtin_amdgcn_s_setprio(0); } while (0)
; #define WAIT_V(n) asm volatile("s_waitcnt vmcnt(" #n ")" ::: "memory")
; #define WAIT_L(n) asm volatile("s_waitcnt lgkmcnt(" #n ")" ::: "memory")
; #define BAR __builtin_amdgcn_s_barrier()
; #define SCHED __builtin_amdgcn_sched_barrier(0)
; template <int MODE>
; DI void gemm_phase(const bf16_t* __restrict__ A, const bf16_t* __restrict__ Bt, int M, int N, int K, const Epi& ep) {
;     ...
;             LDA(At, 1, 1); STAGE(SB(1, 0), rsB, bcol, t + 3); STAGE(SB(1, 1), rsB, bcol + HALF, t + 3); STAGE(SA(1, 0), rsA, brow, t + 3);
;             WAIT_V(8); WAIT_L(0); BAR; MMA(1, 0, At, B0); MMA(1, 1, At, B1); BAR; SCHED;
;         }
;         {
;             LDB(B0, 0, 0); LDB(B1, 0, 1); SCHED; LDA(At, 0, 0); STAGE(SA(1, 1), rsA, brow + HALF, nt - 1);
;             WAIT_V(8); WAIT_L(0); BAR; MMA(0, 0, At, B0); MMA(0, 1, At, B1); BAR; SCHED;
	v_readfirstlane_b32 s43, v138
	s_add_i32 s42, s41, 0x180
	s_mov_b32 m0, s43
	v_readfirstlane_b32 s43, v139
	ds_read_b128 v[188:191], v149 offset:49152
	ds_read_b128 v[192:195], v149 offset:50176
	ds_read_b128 v[196:199], v150 offset:49152
	ds_read_b128 v[200:203], v150 offset:50176
	ds_read_b128 v[204:207], v151 offset:49152
	ds_read_b128 v[208:211], v151 offset:50176
	ds_read_b128 v[214:217], v152 offset:49152
	ds_read_b128 v[218:221], v152 offset:50176
	buffer_load_dwordx4 v128, s[4:7], s42 offen lds
	s_mov_b32 m0, s43
	s_add_i32 s41, s41, 0x40180
	buffer_load_dwordx4 v129, s[4:7], s42 offen lds
	v_readfirstlane_b32 s42, v142
	s_mov_b32 m0, s42
	v_readfirstlane_b32 s42, v143
	buffer_load_dwordx4 v128, s[4:7], s41 offen lds
	s_mov_b32 m0, s42
	s_addk_i32 s40, 0x180
	buffer_load_dwordx4 v129, s[4:7], s41 offen lds
	v_readfirstlane_b32 s6, v140
	s_mov_b32 m0, s6
	v_readfirstlane_b32 s6, v141
	buffer_load_dwordx4 v128, s[8:11], s40 offen lds
	s_mov_b32 m0, s6
	s_nop 0
	buffer_load_dwordx4 v129, s[8:11], s40 offen lds
	s_waitcnt vmcnt(8)
	s_waitcnt lgkmcnt(0)
	s_barrier
	s_setprio 1
	s_waitcnt lgkmcnt(7)
	v_mfma_f32_16x16x32_bf16 v[60:63], v[156:159], v[188:191], v[60:63]
	v_mfma_f32_16x16x32_bf16 v[56:59], v[164:167], v[188:191], v[56:59]
	s_waitcnt lgkmcnt(5)
	v_mfma_f32_16x16x32_bf16 v[52:55], v[156:159], v[196:199], v[52:55]
	v_mfma_f32_16x16x32_bf16 v[48:51], v[164:167], v[196:199], v[48:51]
	s_waitcnt lgkmcnt(3)
	v_mfma_f32_16x16x32_bf16 v[44:47], v[156:159], v[204:207], v[44:47]
	v_mfma_f32_16x16x32_bf16 v[40:43], v[164:167], v[204:207], v[40:43]
	s_waitcnt lgkmcnt(1)
	v_mfma_f32_16x16x32_bf16 v[36:39], v[156:159], v[214:217], v[36:39]
	v_mfma_f32_16x16x32_bf16 v[32:35], v[164:167], v[214:217], v[32:35]
	v_mfma_f32_16x16x32_bf16 v[60:63], v[160:163], v[192:195], v[60:63]
	v_mfma_f32_16x16x32_bf16 v[56:59], v[168:171], v[192:195], v[56:59]
	v_mfma_f32_16x16x32_bf16 v[52:55], v[160:163], v[200:203], v[52:55]
	v_mfma_f32_16x16x32_bf16 v[48:51], v[168:171], v[200:203], v[48:51]
	v_mfma_f32_16x16x32_bf16 v[44:47], v[160:163], v[208:211], v[44:47]
	v_mfma_f32_16x16x32_bf16 v[40:43], v[168:171], v[208:211], v[40:43]
	s_waitcnt lgkmcnt(0)
	v_mfma_f32_16x16x32_bf16 v[36:39], v[160:163], v[218:221], v[36:39]
	v_mfma_f32_16x16x32_bf16 v[32:35], v[168:171], v[218:221], v[32:35]
	s_setprio 0
	s_setprio 1
	v_mfma_f32_16x16x32_bf16 v[28:31], v[172:175], v[188:191], v[28:31]
	v_mfma_f32_16x16x32_bf16 v[24:27], v[180:183], v[188:191], v[24:27]
	v_mfma_f32_16x16x32_bf16 v[20:23], v[172:175], v[196:199], v[20:23]
	v_mfma_f32_16x16x32_bf16 v[16:19], v[180:183], v[196:199], v[16:19]
	v_mfma_f32_16x16x32_bf16 v[12:15], v[172:175], v[204:207], v[12:15]
	v_mfma_f32_16x16x32_bf16 v[8:11], v[180:183], v[204:207], v[8:11]
	v_mfma_f32_16x16x32_bf16 v[4:7], v[172:175], v[214:217], v[4:7]
	v_mfma_f32_16x16x32_bf16 v[0:3], v[180:183], v[214:217], v[0:3]
	v_mfma_f32_16x16x32_bf16 v[28:31], v[176:179], v[192:195], v[28:31]
	v_mfma_f32_16x16x32_bf16 v[24:27], v[184:187], v[192:195], v[24:27]
	v_mfma_f32_16x16x32_bf16 v[20:23], v[176:179], v[200:203], v[20:23]
	v_mfma_f32_16x16x32_bf16 v[16:19], v[184:187], v[200:203], v[16:19]
	v_mfma_f32_16x16x32_bf16 v[12:15], v[176:179], v[208:211], v[12:15]
	v_mfma_f32_16x16x32_bf16 v[8:11], v[184:187], v[208:211], v[8:11]
	v_mfma_f32_16x16x32_bf16 v[4:7], v[176:179], v[218:221], v[4:7]
	v_mfma_f32_16x16x32_bf16 v[0:3], v[184:187], v[218:221], v[0:3]
	s_add_i32 s30, s30, 2
	s_addk_i32 s31, 0x100
	s_cmp_gt_u32 s30, 11
	s_setprio 0
	s_barrier
	s_cbranch_scc0 .LBB0_558
	ds_read_b128 v[164:167], v147
	ds_read_b128 v[168:171], v147 offset:1024
	ds_read_b128 v[172:175], v147 offset:2048
	ds_read_b128 v[176:179], v147 offset:3072
	ds_read_b128 v[180:183], v148
	ds_read_b128 v[184:187], v148 offset:1024
	ds_read_b128 v[188:191], v148 offset:2048
	ds_read_b128 v[192:195], v148 offset:3072
	v_readfirstlane_b32 s7, v144
	s_or_b32 s6, s26, 0x780
	s_mov_b32 m0, s7
	v_readfirstlane_b32 s7, v145
	ds_read_b128 v[196:199], v149
	ds_read_b128 v[200:203], v149 offset:1024
	ds_read_b128 v[214:217], v150
	ds_read_b128 v[218:221], v150 offset:1024
	ds_read_b128 v[222:225], v151
	ds_read_b128 v[226:229], v151 offset:1024
	ds_read_b128 v[230:233], v152
	ds_read_b128 v[234:237], v152 offset:1024
	buffer_load_dwordx4 v128, s[8:11], s6 offen lds
	s_mov_b32 m0, s7
	s_nop 0
	buffer_load_dwordx4 v129, s[8:11], s6 offen lds
	s_waitcnt vmcnt(8)
	s_waitcnt lgkmcnt(0)
	s_barrier
; #define LDA(dst, b, h) for (int m = 0; m < 4; ++m) for (int k = 0; k < 2; ++k) \
;     dst[m][k] = *reinterpret_cast<const bf16x8*>((char*)SA(b, h) + lds_byte(wr * 64 + m * 16 + fr, k * 32 + fq * 8))
; #define MMA(ai, bj, At, Bt_) do { __builtin_amdgcn_s_setprio(1); \
;     for (int m = 0; m < 4; ++m) for (int n = 0; n < 2; ++n) for (int k = 0; k < 2; ++k) \
;       acc[ai][bj][m][n] = __builtin_amdgcn_mfma_f32_16x16x32_bf16(Bt_[n][k], At[m][k], acc[ai][bj][m][n], 0, 0, 0); \
;     __builtin_amdgcn_s_setprio(0); } while (0)
; #define WAIT_V(n) asm volatile("s_waitcnt vmcnt(" #n ")" ::: "memory")
; #define WAIT_L(n) asm volatile("s_waitcnt lgkmcnt(" #n ")" ::: "memory")
; #define BAR __builtin_amdgcn_s_barrier()
; #define SCHED __builtin_amdgcn_sched_barrier(0)
; template <int MODE>
; DI void gemm_phase(const bf16_t* __restrict__ A, const bf16_t* __restrict__ Bt, int M, int N, int K, const Epi& ep) {
;     ...
;             WAIT_V(8); WAIT_L(0); BAR; MMA(0, 0, At, B0); MMA(0, 1, At, B1); BAR; SCHED;
;             LDA(At, 0, 1);
;             WAIT_V(2); WAIT_L(0); BAR; MMA(1, 0, At, B0); MMA(1, 1, At, B1); BAR; SCHED;
	s_setprio 1
	s_waitcnt lgkmcnt(7)
	v_mfma_f32_16x16x32_bf16 v[124:127], v[164:167], v[196:199], v[124:127]
	v_mfma_f32_16x16x32_bf16 v[120:123], v[172:175], v[196:199], v[120:123]
	s_waitcnt lgkmcnt(5)
	v_mfma_f32_16x16x32_bf16 v[116:119], v[164:167], v[214:217], v[116:119]
	v_mfma_f32_16x16x32_bf16 v[112:115], v[172:175], v[214:217], v[112:115]
	s_waitcnt lgkmcnt(1)
	v_mfma_f32_16x16x32_bf16 v[96:99], v[172:175], v[230:233], v[96:99]
	v_mfma_f32_16x16x32_bf16 v[124:127], v[168:171], v[200:203], v[124:127]
	v_mfma_f32_16x16x32_bf16 v[120:123], v[176:179], v[200:203], v[120:123]
	v_mfma_f32_16x16x32_bf16 v[116:119], v[168:171], v[218:221], v[116:119]
	v_mfma_f32_16x16x32_bf16 v[112:115], v[176:179], v[218:221], v[112:115]
	v_mfma_f32_16x16x32_bf16 v[108:111], v[164:167], v[222:225], v[108:111]
	v_mfma_f32_16x16x32_bf16 v[104:107], v[172:175], v[222:225], v[104:107]
	v_mfma_f32_16x16x32_bf16 v[100:103], v[164:167], v[230:233], v[100:103]
	s_waitcnt lgkmcnt(0)
	v_mfma_f32_16x16x32_bf16 v[160:163], v[176:179], v[234:237], v[96:99]
	v_mfma_f32_16x16x32_bf16 v[238:241], v[168:171], v[226:229], v[108:111]
	v_mfma_f32_16x16x32_bf16 v[242:245], v[176:179], v[226:229], v[104:107]
	v_mfma_f32_16x16x32_bf16 v[246:249], v[168:171], v[234:237], v[100:103]
	s_setprio 0
	s_setprio 1
	v_mfma_f32_16x16x32_bf16 v[92:95], v[180:183], v[196:199], v[92:95]
	v_mfma_f32_16x16x32_bf16 v[88:91], v[188:191], v[196:199], v[88:91]
	v_mfma_f32_16x16x32_bf16 v[84:87], v[180:183], v[214:217], v[84:87]
	v_mfma_f32_16x16x32_bf16 v[80:83], v[188:191], v[214:217], v[80:83]
	v_mfma_f32_16x16x32_bf16 v[92:95], v[184:187], v[200:203], v[92:95]
	v_mfma_f32_16x16x32_bf16 v[88:91], v[192:195], v[200:203], v[88:91]
	v_mfma_f32_16x16x32_bf16 v[84:87], v[184:187], v[218:221], v[84:87]
	v_mfma_f32_16x16x32_bf16 v[80:83], v[192:195], v[218:221], v[80:83]
	v_mfma_f32_16x16x32_bf16 v[76:79], v[180:183], v[222:225], v[76:79]
	v_mfma_f32_16x16x32_bf16 v[72:75], v[188:191], v[222:225], v[72:75]
	v_mfma_f32_16x16x32_bf16 v[68:71], v[180:183], v[230:233], v[68:71]
	v_mfma_f32_16x16x32_bf16 v[64:67], v[188:191], v[230:233], v[64:67]
	v_mfma_f32_16x16x32_bf16 v[196:199], v[184:187], v[226:229], v[76:79]
	v_mfma_f32_16x16x32_bf16 v[200:203], v[192:195], v[226:229], v[72:75]
	v_mfma_f32_16x16x32_bf16 v[214:217], v[184:187], v[234:237], v[68:71]
	v_mfma_f32_16x16x32_bf16 v[218:221], v[192:195], v[234:237], v[64:67]
	s_setprio 0
	s_barrier
	s_nop 1
	ds_read_b128 v[64:67], v149 offset:16384
	ds_read_b128 v[68:71], v149 offset:17408
	ds_read_b128 v[72:75], v150 offset:16384
	ds_read_b128 v[76:79], v150 offset:17408
	ds_read_b128 v[96:99], v151 offset:16384
	ds_read_b128 v[100:103], v151 offset:17408
	ds_read_b128 v[104:107], v152 offset:16384
	ds_read_b128 v[108:111], v152 offset:17408
	s_waitcnt vmcnt(2)
	s_waitcnt lgkmcnt(0)
	s_barrier
	s_setprio 1
	s_waitcnt lgkmcnt(7)
	v_mfma_f32_16x16x32_bf16 v[60:63], v[164:167], v[64:67], v[60:63]
	v_mfma_f32_16x16x32_bf16 v[56:59], v[172:175], v[64:67], v[56:59]
	s_waitcnt lgkmcnt(5)
	v_mfma_f32_16x16x32_bf16 v[52:55], v[164:167], v[72:75], v[52:55]
	v_mfma_f32_16x16x32_bf16 v[48:51], v[172:175], v[72:75], v[48:51]
	v_mfma_f32_16x16x32_bf16 v[60:63], v[168:171], v[68:71], v[60:63]
	v_mfma_f32_16x16x32_bf16 v[56:59], v[176:179], v[68:71], v[56:59]
	s_waitcnt lgkmcnt(4)
	v_mfma_f32_16x16x32_bf16 v[52:55], v[168:171], v[76:79], v[52:55]
	v_mfma_f32_16x16x32_bf16 v[48:51], v[176:179], v[76:79], v[48:51]
	s_waitcnt lgkmcnt(3)
	v_mfma_f32_16x16x32_bf16 v[44:47], v[164:167], v[96:99], v[44:47]
	v_mfma_f32_16x16x32_bf16 v[40:43], v[172:175], v[96:99], v[40:43]
	s_waitcnt lgkmcnt(1)
	v_mfma_f32_16x16x32_bf16 v[36:39], v[164:167], v[104:107], v[36:39]
	v_mfma_f32_16x16x32_bf16 v[32:35], v[172:175], v[104:107], v[32:35]
	v_mfma_f32_16x16x32_bf16 v[222:225], v[168:171], v[100:103], v[44:47]
	v_mfma_f32_16x16x32_bf16 v[226:229], v[176:179], v[100:103], v[40:43]
	s_waitcnt lgkmcnt(0)
	v_mfma_f32_16x16x32_bf16 v[164:167], v[168:171], v[108:111], v[36:39]
	v_mfma_f32_16x16x32_bf16 v[168:171], v[176:179], v[108:111], v[32:35]
	s_setprio 0
	s_setprio 1
	v_mfma_f32_16x16x32_bf16 v[28:31], v[180:183], v[64:67], v[28:31]
	v_mfma_f32_16x16x32_bf16 v[24:27], v[188:191], v[64:67], v[24:27]
	v_mfma_f32_16x16x32_bf16 v[20:23], v[180:183], v[72:75], v[20:23]
	v_mfma_f32_16x16x32_bf16 v[16:19], v[188:191], v[72:75], v[16:19]
	v_mfma_f32_16x16x32_bf16 v[28:31], v[184:187], v[68:71], v[28:31]
	v_mfma_f32_16x16x32_bf16 v[24:27], v[192:195], v[68:71], v[24:27]
	v_mfma_f32_16x16x32_bf16 v[20:23], v[184:187], v[76:79], v[20:23]
	v_mfma_f32_16x16x32_bf16 v[16:19], v[192:195], v[76:79], v[16:19]
	v_mfma_f32_16x16x32_bf16 v[12:15], v[180:183], v[96:99], v[12:15]
	v_mfma_f32_16x16x32_bf16 v[8:11], v[188:191], v[96:99], v[8:11]
	v_mfma_f32_16x16x32_bf16 v[4:7], v[180:183], v[104:107], v[4:7]
	v_mfma_f32_16x16x32_bf16 v[0:3], v[188:191], v[104:107], v[0:3]
	v_mfma_f32_16x16x32_bf16 v[172:175], v[184:187], v[100:103], v[12:15]
	v_mfma_f32_16x16x32_bf16 v[176:179], v[192:195], v[100:103], v[8:11]
	v_mfma_f32_16x16x32_bf16 v[180:183], v[184:187], v[108:111], v[4:7]
	v_mfma_f32_16x16x32_bf16 v[184:187], v[192:195], v[108:111], v[0:3]
	s_setprio 0
	s_barrier
; #define LDA(dst, b, h) for (int m = 0; m < 4; ++m) for (int k = 0; k < 2; ++k) \
;     dst[m][k] = *reinterpret_cast<const bf16x8*>((char*)SA(b, h) + lds_byte(wr * 64 + m * 16 + fr, k * 32 + fq * 8))
; #define LDB(dst, b, h) for (int n = 0; n < 2; ++n) for (int k = 0; k < 2; ++k) \
;     dst[n][k] = *reinterpret_cast<const bf16x8*>((char*)SB(b, h) + lds_byte(wc * 32 + n * 16 + fr, k * 32 + fq * 8))
; #define MMA(ai, bj, At, Bt_) do { __builtin_amdgcn_s_setprio(1); \
;     for (int m = 0; m < 4; ++m) for (int n = 0; n < 2; ++n) for (int k = 0; k < 2; ++k) \
;       acc[ai][bj][m][n] = __builtin_amdgcn_mfma_f32_16x16x32_bf16(Bt_[n][k], At[m][k], acc[ai][bj][m][n], 0, 0, 0); \
;     __builtin_amdgcn_s_setprio(0); } while (0)
; #define WAIT_V(n) asm volatile("s_waitcnt vmcnt(" #n ")" ::: "memory")
; #define WAIT_L(n) asm volatile("s_waitcnt lgkmcnt(" #n ")" ::: "memory")
; #define BAR __builtin_amdgcn_s_barrier()
; #define SCHED __builtin_amdgcn_sched_barrier(0)
; template <int MODE>
; DI void gemm_phase(const bf16_t* __restrict__ A, const bf16_t* __restrict__ Bt, int M, int N, int K, const Epi& ep) {
;     ...
;             LDB(B0, 1, 0); LDB(B1, 1, 1); SCHED; LDA(At, 1, 0);
;             WAIT_V(0); WAIT_L(0); BAR; MMA(0, 0, At, B0); MMA(0, 1, At, B1); BAR; SCHED;
;             LDA(At, 1, 1);
;             WAIT_L(0); BAR; MMA(1, 0, At, B0); MMA(1, 1, At, B1); BAR; SCHED;
;         }
;         if (wr == 0) BAR;
	s_nop 1
	ds_read_b128 v[0:3], v153
	ds_read_b128 v[4:7], v153 offset:1024
	ds_read_b128 v[8:11], v153 offset:2048
	ds_read_b128 v[12:15], v153 offset:3072
	ds_read_b128 v[188:191], v154
	ds_read_b128 v[192:195], v154 offset:1024
	ds_read_b128 v[230:233], v154 offset:2048
	ds_read_b128 v[234:237], v154 offset:3072
	ds_read_b128 v[32:35], v149 offset:32768
	ds_read_b128 v[36:39], v149 offset:33792
	ds_read_b128 v[40:43], v150 offset:32768
	ds_read_b128 v[44:47], v150 offset:33792
	ds_read_b128 v[208:211], v151 offset:32768
	ds_read_b128 v[204:207], v151 offset:33792
	ds_read_b128 v[156:159], v152 offset:32768
	ds_read_b128 v[64:67], v152 offset:33792
	s_waitcnt vmcnt(0)
	s_waitcnt lgkmcnt(0)
	s_barrier
	s_setprio 1
	s_waitcnt lgkmcnt(7)
	v_mfma_f32_16x16x32_bf16 v[68:71], v[0:3], v[32:35], v[124:127]
	s_waitcnt lgkmcnt(6)
	v_mfma_f32_16x16x32_bf16 v[96:99], v[4:7], v[36:39], v[68:71]
	v_mfma_f32_16x16x32_bf16 v[68:71], v[8:11], v[32:35], v[120:123]
	v_mfma_f32_16x16x32_bf16 v[100:103], v[12:15], v[36:39], v[68:71]
	s_waitcnt lgkmcnt(5)
	v_mfma_f32_16x16x32_bf16 v[68:71], v[0:3], v[40:43], v[116:119]
	s_waitcnt lgkmcnt(4)
	v_mfma_f32_16x16x32_bf16 v[104:107], v[4:7], v[44:47], v[68:71]
	v_mfma_f32_16x16x32_bf16 v[68:71], v[8:11], v[40:43], v[112:115]
	v_mfma_f32_16x16x32_bf16 v[108:111], v[12:15], v[44:47], v[68:71]
	s_waitcnt lgkmcnt(3)
	v_mfma_f32_16x16x32_bf16 v[68:71], v[0:3], v[208:211], v[238:241]
	s_waitcnt lgkmcnt(2)
	v_mfma_f32_16x16x32_bf16 v[112:115], v[4:7], v[204:207], v[68:71]
	v_mfma_f32_16x16x32_bf16 v[68:71], v[8:11], v[208:211], v[242:245]
	v_mfma_f32_16x16x32_bf16 v[116:119], v[12:15], v[204:207], v[68:71]
	s_waitcnt lgkmcnt(1)
	v_mfma_f32_16x16x32_bf16 v[68:71], v[0:3], v[156:159], v[246:249]
	s_waitcnt lgkmcnt(0)
	v_mfma_f32_16x16x32_bf16 v[120:123], v[4:7], v[64:67], v[68:71]
	v_mfma_f32_16x16x32_bf16 v[68:71], v[8:11], v[156:159], v[160:163]
	v_mfma_f32_16x16x32_bf16 v[124:127], v[12:15], v[64:67], v[68:71]
	s_setprio 0
	s_setprio 1
	v_mfma_f32_16x16x32_bf16 v[68:71], v[188:191], v[32:35], v[92:95]
	v_mfma_f32_16x16x32_bf16 v[32:35], v[230:233], v[32:35], v[88:91]
	v_mfma_f32_16x16x32_bf16 v[160:163], v[192:195], v[36:39], v[68:71]
	v_mfma_f32_16x16x32_bf16 v[68:71], v[234:237], v[36:39], v[32:35]
	v_mfma_f32_16x16x32_bf16 v[32:35], v[188:191], v[40:43], v[84:87]
	v_mfma_f32_16x16x32_bf16 v[72:75], v[192:195], v[44:47], v[32:35]
	v_mfma_f32_16x16x32_bf16 v[32:35], v[230:233], v[40:43], v[80:83]
	v_mfma_f32_16x16x32_bf16 v[76:79], v[234:237], v[44:47], v[32:35]
	v_mfma_f32_16x16x32_bf16 v[32:35], v[188:191], v[208:211], v[196:199]
	v_mfma_f32_16x16x32_bf16 v[80:83], v[192:195], v[204:207], v[32:35]
	v_mfma_f32_16x16x32_bf16 v[32:35], v[230:233], v[208:211], v[200:203]
	v_mfma_f32_16x16x32_bf16 v[84:87], v[234:237], v[204:207], v[32:35]
	v_mfma_f32_16x16x32_bf16 v[32:35], v[188:191], v[156:159], v[214:217]
	v_mfma_f32_16x16x32_bf16 v[88:91], v[192:195], v[64:67], v[32:35]
	v_mfma_f32_16x16x32_bf16 v[32:35], v[230:233], v[156:159], v[218:221]
	v_mfma_f32_16x16x32_bf16 v[92:95], v[234:237], v[64:67], v[32:35]
	s_setprio 0
	s_barrier
	ds_read_b128 v[64:67], v149 offset:49152
	ds_read_b128 v[156:159], v149 offset:50176
	ds_read_b128 v[196:199], v150 offset:49152
	ds_read_b128 v[200:203], v150 offset:50176
	ds_read_b128 v[204:207], v151 offset:49152
	ds_read_b128 v[208:211], v151 offset:50176
	ds_read_b128 v[214:217], v152 offset:49152
	ds_read_b128 v[218:221], v152 offset:50176
	s_waitcnt lgkmcnt(0)
	s_barrier
	s_setprio 1
	s_waitcnt lgkmcnt(7)
	v_mfma_f32_16x16x32_bf16 v[32:35], v[0:3], v[64:67], v[60:63]
	s_waitcnt lgkmcnt(5)
	v_mfma_f32_16x16x32_bf16 v[40:43], v[0:3], v[196:199], v[52:55]
	v_mfma_f32_16x16x32_bf16 v[44:47], v[8:11], v[196:199], v[48:51]
	s_waitcnt lgkmcnt(3)
	v_mfma_f32_16x16x32_bf16 v[48:51], v[0:3], v[204:207], v[222:225]
	s_waitcnt lgkmcnt(1)
	v_mfma_f32_16x16x32_bf16 v[0:3], v[0:3], v[214:217], v[164:167]
	v_mfma_f32_16x16x32_bf16 v[36:39], v[8:11], v[64:67], v[56:59]
	v_mfma_f32_16x16x32_bf16 v[52:55], v[8:11], v[204:207], v[226:229]
	s_waitcnt lgkmcnt(0)
	v_mfma_f32_16x16x32_bf16 v[56:59], v[4:7], v[218:221], v[0:3]
	v_mfma_f32_16x16x32_bf16 v[0:3], v[8:11], v[214:217], v[168:171]
	v_mfma_f32_16x16x32_bf16 v[32:35], v[4:7], v[156:159], v[32:35]
	v_mfma_f32_16x16x32_bf16 v[36:39], v[12:15], v[156:159], v[36:39]
	v_mfma_f32_16x16x32_bf16 v[40:43], v[4:7], v[200:203], v[40:43]
	v_mfma_f32_16x16x32_bf16 v[44:47], v[12:15], v[200:203], v[44:47]
	v_mfma_f32_16x16x32_bf16 v[48:51], v[4:7], v[208:211], v[48:51]
	v_mfma_f32_16x16x32_bf16 v[52:55], v[12:15], v[208:211], v[52:55]
	v_mfma_f32_16x16x32_bf16 v[60:63], v[12:15], v[218:221], v[0:3]
	s_setprio 0
	s_setprio 1
	v_mfma_f32_16x16x32_bf16 v[0:3], v[188:191], v[64:67], v[28:31]
	v_mfma_f32_16x16x32_bf16 v[4:7], v[230:233], v[64:67], v[24:27]
	v_mfma_f32_16x16x32_bf16 v[8:11], v[188:191], v[196:199], v[20:23]
	v_mfma_f32_16x16x32_bf16 v[12:15], v[230:233], v[196:199], v[16:19]
	v_mfma_f32_16x16x32_bf16 v[16:19], v[188:191], v[204:207], v[172:175]
	v_mfma_f32_16x16x32_bf16 v[20:23], v[230:233], v[204:207], v[176:179]
	v_mfma_f32_16x16x32_bf16 v[24:27], v[188:191], v[214:217], v[180:183]
	v_mfma_f32_16x16x32_bf16 v[28:31], v[230:233], v[214:217], v[184:187]
	v_mfma_f32_16x16x32_bf16 v[0:3], v[192:195], v[156:159], v[0:3]
	v_mfma_f32_16x16x32_bf16 v[4:7], v[234:237], v[156:159], v[4:7]
	v_mfma_f32_16x16x32_bf16 v[8:11], v[192:195], v[200:203], v[8:11]
	v_mfma_f32_16x16x32_bf16 v[12:15], v[234:237], v[200:203], v[12:15]
	v_mfma_f32_16x16x32_bf16 v[16:19], v[192:195], v[208:211], v[16:19]
	v_mfma_f32_16x16x32_bf16 v[20:23], v[234:237], v[208:211], v[20:23]
	v_mfma_f32_16x16x32_bf16 v[24:27], v[192:195], v[218:221], v[24:27]
	v_mfma_f32_16x16x32_bf16 v[28:31], v[234:237], v[218:221], v[28:31]
	s_setprio 0
	s_barrier
	s_and_saveexec_b64 s[6:7], s[38:39]
	s_cbranch_execz .LBB0_550
	s_barrier
	s_branch .LBB0_550

; #define LDA(dst, b, h) for (int m = 0; m < 4; ++m) for (int k = 0; k < 2; ++k) \
;     dst[m][k] = *reinterpret_cast<const bf16x8*>((char*)SA(b, h) + lds_byte(wr * 64 + m * 16 + fr, k * 32 + fq * 8))
; #define LDB(dst, b, h) for (int n = 0; n < 2; ++n) for (int k = 0; k < 2; ++k) \
;     dst[n][k] = *reinterpret_cast<const bf16x8*>((char*)SB(b, h) + lds_byte(wc * 32 + n * 16 + fr, k * 32 + fq * 8))
; #define MMA(ai, bj, At, Bt_) do { __builtin_amdgcn_s_setprio(1); \
;     for (int m = 0; m < 4; ++m) for (int n = 0; n < 2; ++n) for (int k = 0; k < 2; ++k) \
;       acc[ai][bj][m][n] = __builtin_amdgcn_mfma_f32_16x16x32_bf16(Bt_[n][k], At[m][k], acc[ai][bj][m][n], 0, 0, 0); \
;     __builtin_amdgcn_s_setprio(0); } while (0)
; #define WAIT_V(n) asm volatile("s_waitcnt vmcnt(" #n ")" ::: "memory")
; #define WAIT_L(n) asm volatile("s_waitcnt lgkmcnt(" #n ")" ::: "memory")
; #define BAR __builtin_amdgcn_s_barrier()
; #define SCHED __builtin_amdgcn_sched_barrier(0)
; template <int MODE>
; DI void gemm_phase(const bf16_t* __restrict__ A, const bf16_t* __restrict__ Bt, int M, int N, int K, const Epi& ep) {
;     ...
;             LDB(B0, 0, 0); LDB(B1, 0, 1); SCHED; LDA(At, 0, 0); STAGE(SA(1, 1), rsA, brow + HALF, t + 1);
;             WAIT_V(8); WAIT_L(0); BAR; MMA(0, 0, At, B0); MMA(0, 1, At, B1); BAR; SCHED;
;             LDA(At, 0, 1); STAGE(SB(0, 0), rsB, bcol, t + 2); STAGE(SB(0, 1), rsB, bcol + HALF, t + 2); STAGE(SA(0, 0), rsA, brow, t + 2);
.LBB0_1023:
	ds_read_b128 v[156:159], v147
	ds_read_b128 v[160:163], v147 offset:1024
	ds_read_b128 v[164:167], v147 offset:2048
	ds_read_b128 v[168:171], v147 offset:3072
	ds_read_b128 v[172:175], v148
	ds_read_b128 v[176:179], v148 offset:1024
	ds_read_b128 v[180:183], v148 offset:2048
	ds_read_b128 v[184:187], v148 offset:3072
	s_add_i32 s42, s31, s41
	v_readfirstlane_b32 s15, v144
	s_add_i32 s14, s42, 0x40080
	s_mov_b32 s26, s10
	s_mov_b32 s27, s11
	s_mov_b32 m0, s15
	v_readfirstlane_b32 s15, v145
	ds_read_b128 v[188:191], v149
	ds_read_b128 v[192:195], v149 offset:1024
	ds_read_b128 v[196:199], v150
	ds_read_b128 v[200:203], v150 offset:1024
	ds_read_b128 v[204:207], v151
	ds_read_b128 v[208:211], v151 offset:1024
	ds_read_b128 v[214:217], v152
	ds_read_b128 v[218:221], v152 offset:1024
	buffer_load_dwordx4 v128, s[24:27], s14 offen lds
	s_mov_b32 m0, s15
	s_nop 0
	buffer_load_dwordx4 v129, s[24:27], s14 offen lds
	s_waitcnt vmcnt(8)
	s_waitcnt lgkmcnt(0)
	s_barrier
	s_setprio 1
	s_waitcnt lgkmcnt(7)
	v_mfma_f32_16x16x32_bf16 v[124:127], v[156:159], v[188:191], v[124:127]
	v_mfma_f32_16x16x32_bf16 v[120:123], v[164:167], v[188:191], v[120:123]
	s_waitcnt lgkmcnt(5)
	v_mfma_f32_16x16x32_bf16 v[116:119], v[156:159], v[196:199], v[116:119]
	v_mfma_f32_16x16x32_bf16 v[112:115], v[164:167], v[196:199], v[112:115]
	s_waitcnt lgkmcnt(3)
	v_mfma_f32_16x16x32_bf16 v[108:111], v[156:159], v[204:207], v[108:111]
	v_mfma_f32_16x16x32_bf16 v[104:107], v[164:167], v[204:207], v[104:107]
	s_waitcnt lgkmcnt(1)
	v_mfma_f32_16x16x32_bf16 v[100:103], v[156:159], v[214:217], v[100:103]
	v_mfma_f32_16x16x32_bf16 v[96:99], v[164:167], v[214:217], v[96:99]
	v_mfma_f32_16x16x32_bf16 v[124:127], v[160:163], v[192:195], v[124:127]
	v_mfma_f32_16x16x32_bf16 v[120:123], v[168:171], v[192:195], v[120:123]
	v_mfma_f32_16x16x32_bf16 v[116:119], v[160:163], v[200:203], v[116:119]
	v_mfma_f32_16x16x32_bf16 v[112:115], v[168:171], v[200:203], v[112:115]
	v_mfma_f32_16x16x32_bf16 v[108:111], v[160:163], v[208:211], v[108:111]
	v_mfma_f32_16x16x32_bf16 v[104:107], v[168:171], v[208:211], v[104:107]
	s_waitcnt lgkmcnt(0)
	v_mfma_f32_16x16x32_bf16 v[100:103], v[160:163], v[218:221], v[100:103]
	v_mfma_f32_16x16x32_bf16 v[96:99], v[168:171], v[218:221], v[96:99]
	s_setprio 0
	s_setprio 1
	v_mfma_f32_16x16x32_bf16 v[92:95], v[172:175], v[188:191], v[92:95]
	v_mfma_f32_16x16x32_bf16 v[88:91], v[180:183], v[188:191], v[88:91]
	v_mfma_f32_16x16x32_bf16 v[84:87], v[172:175], v[196:199], v[84:87]
	v_mfma_f32_16x16x32_bf16 v[80:83], v[180:183], v[196:199], v[80:83]
	v_mfma_f32_16x16x32_bf16 v[76:79], v[172:175], v[204:207], v[76:79]
	v_mfma_f32_16x16x32_bf16 v[72:75], v[180:183], v[204:207], v[72:75]
	v_mfma_f32_16x16x32_bf16 v[68:71], v[172:175], v[214:217], v[68:71]
	v_mfma_f32_16x16x32_bf16 v[64:67], v[180:183], v[214:217], v[64:67]
	v_mfma_f32_16x16x32_bf16 v[92:95], v[176:179], v[192:195], v[92:95]
	v_mfma_f32_16x16x32_bf16 v[88:91], v[184:187], v[192:195], v[88:91]
	v_mfma_f32_16x16x32_bf16 v[84:87], v[176:179], v[200:203], v[84:87]
	v_mfma_f32_16x16x32_bf16 v[80:83], v[184:187], v[200:203], v[80:83]
	v_mfma_f32_16x16x32_bf16 v[76:79], v[176:179], v[208:211], v[76:79]
	v_mfma_f32_16x16x32_bf16 v[72:75], v[184:187], v[208:211], v[72:75]
	v_mfma_f32_16x16x32_bf16 v[68:71], v[176:179], v[218:221], v[68:71]
	v_mfma_f32_16x16x32_bf16 v[64:67], v[184:187], v[218:221], v[64:67]
	s_setprio 0
	s_barrier
	s_add_i32 s43, s6, s41
	v_readfirstlane_b32 s45, v130
	s_add_i32 s44, s43, 0x100
	s_mov_b32 s14, s10
	s_mov_b32 s15, s11
	s_mov_b32 m0, s45
	v_readfirstlane_b32 s45, v131
	ds_read_b128 v[188:191], v149 offset:16384
	ds_read_b128 v[192:195], v149 offset:17408
	ds_read_b128 v[196:199], v150 offset:16384
	ds_read_b128 v[200:203], v150 offset:17408
	ds_read_b128 v[204:207], v151 offset:16384
	ds_read_b128 v[208:211], v151 offset:17408
	ds_read_b128 v[214:217], v152 offset:16384
	ds_read_b128 v[218:221], v152 offset:17408
	buffer_load_dwordx4 v128, s[12:15], s44 offen lds
	s_mov_b32 m0, s45
	v_readfirstlane_b32 s45, v132
	buffer_load_dwordx4 v129, s[12:15], s44 offen lds
	s_add_i32 s44, s43, 0x40100
	s_mov_b32 m0, s45
	v_readfirstlane_b32 s45, v133
	buffer_load_dwordx4 v128, s[12:15], s44 offen lds
	s_mov_b32 m0, s45
	v_readfirstlane_b32 s45, v134
	buffer_load_dwordx4 v129, s[12:15], s44 offen lds
	s_add_i32 s44, s42, 0x100
	s_mov_b32 m0, s45
	v_readfirstlane_b32 s45, v135
	buffer_load_dwordx4 v128, s[24:27], s44 offen lds
	s_mov_b32 m0, s45
	s_nop 0
	buffer_load_dwordx4 v129, s[24:27], s44 offen lds
	s_waitcnt vmcnt(8)
	s_waitcnt lgkmcnt(0)
	s_barrier
; #define LDA(dst, b, h) for (int m = 0; m < 4; ++m) for (int k = 0; k < 2; ++k) \
;     dst[m][k] = *reinterpret_cast<const bf16x8*>((char*)SA(b, h) + lds_byte(wr * 64 + m * 16 + fr, k * 32 + fq * 8))
; #define LDB(dst, b, h) for (int n = 0; n < 2; ++n) for (int k = 0; k < 2; ++k) \
;     dst[n][k] = *reinterpret_cast<const bf16x8*>((char*)SB(b, h) + lds_byte(wc * 32 + n * 16 + fr, k * 32 + fq * 8))
; #define MMA(ai, bj, At, Bt_) do { __builtin_amdgcn_s_setprio(1); \
;     for (int m = 0; m < 4; ++m) for (int n = 0; n < 2; ++n) for (int k = 0; k < 2; ++k) \
;       acc[ai][bj][m][n] = __builtin_amdgcn_mfma_f32_16x16x32_bf16(Bt_[n][k], At[m][k], acc[ai][bj][m][n], 0, 0, 0); \
;     __builtin_amdgcn_s_setprio(0); } while (0)
; #define WAIT_V(n) asm volatile("s_waitcnt vmcnt(" #n ")" ::: "memory")
; #define WAIT_L(n) asm volatile("s_waitcnt lgkmcnt(" #n ")" ::: "memory")
; #define BAR __builtin_amdgcn_s_barrier()
; #define SCHED __builtin_amdgcn_sched_barrier(0)
; template <int MODE>
; DI void gemm_phase(const bf16_t* __restrict__ A, const bf16_t* __restrict__ Bt, int M, int N, int K, const Epi& ep) {
;     ...
;             WAIT_V(8); WAIT_L(0); BAR; MMA(1, 0, At, B0); MMA(1, 1, At, B1); BAR; SCHED;
;             LDB(B0, 1, 0); LDB(B1, 1, 1); SCHED; LDA(At, 1, 0); STAGE(SA(0, 1), rsA, brow + HALF, t + 2);
;             WAIT_V(8); WAIT_L(0); BAR; MMA(0, 0, At, B0); MMA(0, 1, At, B1); BAR; SCHED;
	s_setprio 1
	s_waitcnt lgkmcnt(7)
	v_mfma_f32_16x16x32_bf16 v[60:63], v[156:159], v[188:191], v[60:63]
	v_mfma_f32_16x16x32_bf16 v[56:59], v[164:167], v[188:191], v[56:59]
	s_waitcnt lgkmcnt(5)
	v_mfma_f32_16x16x32_bf16 v[52:55], v[156:159], v[196:199], v[52:55]
	v_mfma_f32_16x16x32_bf16 v[48:51], v[164:167], v[196:199], v[48:51]
	s_waitcnt lgkmcnt(3)
	v_mfma_f32_16x16x32_bf16 v[44:47], v[156:159], v[204:207], v[44:47]
	v_mfma_f32_16x16x32_bf16 v[40:43], v[164:167], v[204:207], v[40:43]
	s_waitcnt lgkmcnt(1)
	v_mfma_f32_16x16x32_bf16 v[36:39], v[156:159], v[214:217], v[36:39]
	v_mfma_f32_16x16x32_bf16 v[32:35], v[164:167], v[214:217], v[32:35]
	v_mfma_f32_16x16x32_bf16 v[60:63], v[160:163], v[192:195], v[60:63]
	v_mfma_f32_16x16x32_bf16 v[56:59], v[168:171], v[192:195], v[56:59]
	v_mfma_f32_16x16x32_bf16 v[52:55], v[160:163], v[200:203], v[52:55]
	v_mfma_f32_16x16x32_bf16 v[48:51], v[168:171], v[200:203], v[48:51]
	v_mfma_f32_16x16x32_bf16 v[44:47], v[160:163], v[208:211], v[44:47]
	v_mfma_f32_16x16x32_bf16 v[40:43], v[168:171], v[208:211], v[40:43]
	s_waitcnt lgkmcnt(0)
	v_mfma_f32_16x16x32_bf16 v[36:39], v[160:163], v[218:221], v[36:39]
	v_mfma_f32_16x16x32_bf16 v[32:35], v[168:171], v[218:221], v[32:35]
	s_setprio 0
	s_setprio 1
	v_mfma_f32_16x16x32_bf16 v[28:31], v[172:175], v[188:191], v[28:31]
	v_mfma_f32_16x16x32_bf16 v[24:27], v[180:183], v[188:191], v[24:27]
	v_mfma_f32_16x16x32_bf16 v[20:23], v[172:175], v[196:199], v[20:23]
	v_mfma_f32_16x16x32_bf16 v[16:19], v[180:183], v[196:199], v[16:19]
	v_mfma_f32_16x16x32_bf16 v[12:15], v[172:175], v[204:207], v[12:15]
	v_mfma_f32_16x16x32_bf16 v[8:11], v[180:183], v[204:207], v[8:11]
	v_mfma_f32_16x16x32_bf16 v[4:7], v[172:175], v[214:217], v[4:7]
	v_mfma_f32_16x16x32_bf16 v[0:3], v[180:183], v[214:217], v[0:3]
	v_mfma_f32_16x16x32_bf16 v[28:31], v[176:179], v[192:195], v[28:31]
	v_mfma_f32_16x16x32_bf16 v[24:27], v[184:187], v[192:195], v[24:27]
	v_mfma_f32_16x16x32_bf16 v[20:23], v[176:179], v[200:203], v[20:23]
	v_mfma_f32_16x16x32_bf16 v[16:19], v[184:187], v[200:203], v[16:19]
	v_mfma_f32_16x16x32_bf16 v[12:15], v[176:179], v[208:211], v[12:15]
	v_mfma_f32_16x16x32_bf16 v[8:11], v[184:187], v[208:211], v[8:11]
	v_mfma_f32_16x16x32_bf16 v[4:7], v[176:179], v[218:221], v[4:7]
	v_mfma_f32_16x16x32_bf16 v[0:3], v[184:187], v[218:221], v[0:3]
	s_setprio 0
	s_barrier
	ds_read_b128 v[156:159], v153
	ds_read_b128 v[160:163], v153 offset:1024
	ds_read_b128 v[164:167], v153 offset:2048
	ds_read_b128 v[168:171], v153 offset:3072
	ds_read_b128 v[172:175], v154
	ds_read_b128 v[176:179], v154 offset:1024
	ds_read_b128 v[180:183], v154 offset:2048
	ds_read_b128 v[184:187], v154 offset:3072
	v_readfirstlane_b32 s45, v136
	s_add_i32 s44, s42, 0x40100
	s_mov_b32 m0, s45
	v_readfirstlane_b32 s45, v137
	ds_read_b128 v[188:191], v149 offset:32768
	ds_read_b128 v[192:195], v149 offset:33792
	ds_read_b128 v[196:199], v150 offset:32768
	ds_read_b128 v[200:203], v150 offset:33792
	ds_read_b128 v[204:207], v151 offset:32768
	ds_read_b128 v[208:211], v151 offset:33792
	ds_read_b128 v[214:217], v152 offset:32768
	ds_read_b128 v[218:221], v152 offset:33792
	buffer_load_dwordx4 v128, s[24:27], s44 offen lds
	s_mov_b32 m0, s45
	s_nop 0
	buffer_load_dwordx4 v129, s[24:27], s44 offen lds
	s_waitcnt vmcnt(8)
	s_waitcnt lgkmcnt(0)
	s_barrier
	s_setprio 1
	s_waitcnt lgkmcnt(7)
	v_mfma_f32_16x16x32_bf16 v[124:127], v[156:159], v[188:191], v[124:127]
	v_mfma_f32_16x16x32_bf16 v[120:123], v[164:167], v[188:191], v[120:123]
	s_waitcnt lgkmcnt(5)
	v_mfma_f32_16x16x32_bf16 v[116:119], v[156:159], v[196:199], v[116:119]
	v_mfma_f32_16x16x32_bf16 v[112:115], v[164:167], v[196:199], v[112:115]
	s_waitcnt lgkmcnt(3)
	v_mfma_f32_16x16x32_bf16 v[108:111], v[156:159], v[204:207], v[108:111]
	v_mfma_f32_16x16x32_bf16 v[104:107], v[164:167], v[204:207], v[104:107]
	s_waitcnt lgkmcnt(1)
	v_mfma_f32_16x16x32_bf16 v[100:103], v[156:159], v[214:217], v[100:103]
	v_mfma_f32_16x16x32_bf16 v[96:99], v[164:167], v[214:217], v[96:99]
	v_mfma_f32_16x16x32_bf16 v[124:127], v[160:163], v[192:195], v[124:127]
	v_mfma_f32_16x16x32_bf16 v[120:123], v[168:171], v[192:195], v[120:123]
	v_mfma_f32_16x16x32_bf16 v[116:119], v[160:163], v[200:203], v[116:119]
	v_mfma_f32_16x16x32_bf16 v[112:115], v[168:171], v[200:203], v[112:115]
	v_mfma_f32_16x16x32_bf16 v[108:111], v[160:163], v[208:211], v[108:111]
	v_mfma_f32_16x16x32_bf16 v[104:107], v[168:171], v[208:211], v[104:107]
	s_waitcnt lgkmcnt(0)
	v_mfma_f32_16x16x32_bf16 v[100:103], v[160:163], v[218:221], v[100:103]
	v_mfma_f32_16x16x32_bf16 v[96:99], v[168:171], v[218:221], v[96:99]
	s_setprio 0
	s_setprio 1
	v_mfma_f32_16x16x32_bf16 v[92:95], v[172:175], v[188:191], v[92:95]
	v_mfma_f32_16x16x32_bf16 v[88:91], v[180:183], v[188:191], v[88:91]
	v_mfma_f32_16x16x32_bf16 v[84:87], v[172:175], v[196:199], v[84:87]
	v_mfma_f32_16x16x32_bf16 v[80:83], v[180:183], v[196:199], v[80:83]
	v_mfma_f32_16x16x32_bf16 v[76:79], v[172:175], v[204:207], v[76:79]
	v_mfma_f32_16x16x32_bf16 v[72:75], v[180:183], v[204:207], v[72:75]
	v_mfma_f32_16x16x32_bf16 v[68:71], v[172:175], v[214:217], v[68:71]
	v_mfma_f32_16x16x32_bf16 v[64:67], v[180:183], v[214:217], v[64:67]
	v_mfma_f32_16x16x32_bf16 v[92:95], v[176:179], v[192:195], v[92:95]
	v_mfma_f32_16x16x32_bf16 v[88:91], v[184:187], v[192:195], v[88:91]
	v_mfma_f32_16x16x32_bf16 v[84:87], v[176:179], v[200:203], v[84:87]
	v_mfma_f32_16x16x32_bf16 v[80:83], v[184:187], v[200:203], v[80:83]
	v_mfma_f32_16x16x32_bf16 v[76:79], v[176:179], v[208:211], v[76:79]
	v_mfma_f32_16x16x32_bf16 v[72:75], v[184:187], v[208:211], v[72:75]
	v_mfma_f32_16x16x32_bf16 v[68:71], v[176:179], v[218:221], v[68:71]
	v_mfma_f32_16x16x32_bf16 v[64:67], v[184:187], v[218:221], v[64:67]
	s_setprio 0
	s_barrier
; #define LDA(dst, b, h) for (int m = 0; m < 4; ++m) for (int k = 0; k < 2; ++k) \
;     dst[m][k] = *reinterpret_cast<const bf16x8*>((char*)SA(b, h) + lds_byte(wr * 64 + m * 16 + fr, k * 32 + fq * 8))
; #define LDB(dst, b, h) for (int n = 0; n < 2; ++n) for (int k = 0; k < 2; ++k) \
;     dst[n][k] = *reinterpret_cast<const bf16x8*>((char*)SB(b, h) + lds_byte(wc * 32 + n * 16 + fr, k * 32 + fq * 8))
; #define MMA(ai, bj, At, Bt_) do { __builtin_amdgcn_s_setprio(1); \
;     for (int m = 0; m < 4; ++m) for (int n = 0; n < 2; ++n) for (int k = 0; k < 2; ++k) \
;       acc[ai][bj][m][n] = __builtin_amdgcn_mfma_f32_16x16x32_bf16(Bt_[n][k], At[m][k], acc[ai][bj][m][n], 0, 0, 0); \
;     __builtin_amdgcn_s_setprio(0); } while (0)
; #define WAIT_V(n) asm volatile("s_waitcnt vmcnt(" #n ")" ::: "memory")
; #define WAIT_L(n) asm volatile("s_waitcnt lgkmcnt(" #n ")" ::: "memory")
; #define BAR __builtin_amdgcn_s_barrier()
; #define SCHED __builtin_amdgcn_sched_barrier(0)
; template <int MODE>
; DI void gemm_phase(const bf16_t* __restrict__ A, const bf16_t* __restrict__ Bt, int M, int N, int K, const Epi& ep) {
;     ...
;             LDA(At, 1, 1); STAGE(SB(1, 0), rsB, bcol, t + 3); STAGE(SB(1, 1), rsB, bcol + HALF, t + 3); STAGE(SA(1, 0), rsA, brow, t + 3);
;             WAIT_V(8); WAIT_L(0); BAR; MMA(1, 0, At, B0); MMA(1, 1, At, B1); BAR; SCHED;
;         }
;         {
;             LDB(B0, 0, 0); LDB(B1, 0, 1); SCHED; LDA(At, 0, 0); STAGE(SA(1, 1), rsA, brow + HALF, nt - 1);
;             WAIT_V(8); WAIT_L(0); BAR; MMA(0, 0, At, B0); MMA(0, 1, At, B1); BAR; SCHED;
	v_readfirstlane_b32 s45, v138
	s_add_i32 s44, s43, 0x180
	s_mov_b32 m0, s45
	v_readfirstlane_b32 s45, v139
	ds_read_b128 v[188:191], v149 offset:49152
	ds_read_b128 v[192:195], v149 offset:50176
	ds_read_b128 v[196:199], v150 offset:49152
	ds_read_b128 v[200:203], v150 offset:50176
	ds_read_b128 v[204:207], v151 offset:49152
	ds_read_b128 v[208:211], v151 offset:50176
	ds_read_b128 v[214:217], v152 offset:49152
	ds_read_b128 v[218:221], v152 offset:50176
	buffer_load_dwordx4 v128, s[12:15], s44 offen lds
	s_mov_b32 m0, s45
	s_add_i32 s43, s43, 0x40180
	buffer_load_dwordx4 v129, s[12:15], s44 offen lds
	v_readfirstlane_b32 s44, v142
	s_mov_b32 m0, s44
	v_readfirstlane_b32 s44, v143
	buffer_load_dwordx4 v128, s[12:15], s43 offen lds
	s_mov_b32 m0, s44
	s_addk_i32 s42, 0x180
	buffer_load_dwordx4 v129, s[12:15], s43 offen lds
	v_readfirstlane_b32 s14, v140
	s_mov_b32 m0, s14
	v_readfirstlane_b32 s14, v141
	buffer_load_dwordx4 v128, s[24:27], s42 offen lds
	s_mov_b32 m0, s14
	s_nop 0
	buffer_load_dwordx4 v129, s[24:27], s42 offen lds
	s_waitcnt vmcnt(8)
	s_waitcnt lgkmcnt(0)
	s_barrier
	s_setprio 1
	s_waitcnt lgkmcnt(7)
	v_mfma_f32_16x16x32_bf16 v[60:63], v[156:159], v[188:191], v[60:63]
	v_mfma_f32_16x16x32_bf16 v[56:59], v[164:167], v[188:191], v[56:59]
	s_waitcnt lgkmcnt(5)
	v_mfma_f32_16x16x32_bf16 v[52:55], v[156:159], v[196:199], v[52:55]
	v_mfma_f32_16x16x32_bf16 v[48:51], v[164:167], v[196:199], v[48:51]
	s_waitcnt lgkmcnt(3)
	v_mfma_f32_16x16x32_bf16 v[44:47], v[156:159], v[204:207], v[44:47]
	v_mfma_f32_16x16x32_bf16 v[40:43], v[164:167], v[204:207], v[40:43]
	s_waitcnt lgkmcnt(1)
	v_mfma_f32_16x16x32_bf16 v[36:39], v[156:159], v[214:217], v[36:39]
	v_mfma_f32_16x16x32_bf16 v[32:35], v[164:167], v[214:217], v[32:35]
	v_mfma_f32_16x16x32_bf16 v[60:63], v[160:163], v[192:195], v[60:63]
	v_mfma_f32_16x16x32_bf16 v[56:59], v[168:171], v[192:195], v[56:59]
	v_mfma_f32_16x16x32_bf16 v[52:55], v[160:163], v[200:203], v[52:55]
	v_mfma_f32_16x16x32_bf16 v[48:51], v[168:171], v[200:203], v[48:51]
	v_mfma_f32_16x16x32_bf16 v[44:47], v[160:163], v[208:211], v[44:47]
	v_mfma_f32_16x16x32_bf16 v[40:43], v[168:171], v[208:211], v[40:43]
	s_waitcnt lgkmcnt(0)
	v_mfma_f32_16x16x32_bf16 v[36:39], v[160:163], v[218:221], v[36:39]
	v_mfma_f32_16x16x32_bf16 v[32:35], v[168:171], v[218:221], v[32:35]
	s_setprio 0
	s_setprio 1
	v_mfma_f32_16x16x32_bf16 v[28:31], v[172:175], v[188:191], v[28:31]
	v_mfma_f32_16x16x32_bf16 v[24:27], v[180:183], v[188:191], v[24:27]
	v_mfma_f32_16x16x32_bf16 v[20:23], v[172:175], v[196:199], v[20:23]
	v_mfma_f32_16x16x32_bf16 v[16:19], v[180:183], v[196:199], v[16:19]
	v_mfma_f32_16x16x32_bf16 v[12:15], v[172:175], v[204:207], v[12:15]
	v_mfma_f32_16x16x32_bf16 v[8:11], v[180:183], v[204:207], v[8:11]
	v_mfma_f32_16x16x32_bf16 v[4:7], v[172:175], v[214:217], v[4:7]
	v_mfma_f32_16x16x32_bf16 v[0:3], v[180:183], v[214:217], v[0:3]
	v_mfma_f32_16x16x32_bf16 v[28:31], v[176:179], v[192:195], v[28:31]
	v_mfma_f32_16x16x32_bf16 v[24:27], v[184:187], v[192:195], v[24:27]
	v_mfma_f32_16x16x32_bf16 v[20:23], v[176:179], v[200:203], v[20:23]
	v_mfma_f32_16x16x32_bf16 v[16:19], v[184:187], v[200:203], v[16:19]
	v_mfma_f32_16x16x32_bf16 v[12:15], v[176:179], v[208:211], v[12:15]
	v_mfma_f32_16x16x32_bf16 v[8:11], v[184:187], v[208:211], v[8:11]
	v_mfma_f32_16x16x32_bf16 v[4:7], v[176:179], v[218:221], v[4:7]
	v_mfma_f32_16x16x32_bf16 v[0:3], v[184:187], v[218:221], v[0:3]
	s_add_i32 s40, s40, 2
	s_addk_i32 s41, 0x100
	s_cmp_gt_u32 s40, 11
	s_setprio 0
	s_barrier
	s_cbranch_scc0 .LBB0_1023
	ds_read_b128 v[156:159], v147
	ds_read_b128 v[160:163], v147 offset:1024
	ds_read_b128 v[164:167], v147 offset:2048
	ds_read_b128 v[168:171], v147 offset:3072
	ds_read_b128 v[172:175], v148
	ds_read_b128 v[176:179], v148 offset:1024
	ds_read_b128 v[180:183], v148 offset:2048
	ds_read_b128 v[184:187], v148 offset:3072
	s_or_b32 s6, s7, 0x780
	v_readfirstlane_b32 s7, v144
	s_mov_b32 m0, s7
	v_readfirstlane_b32 s7, v145
	ds_read_b128 v[188:191], v149
	ds_read_b128 v[192:195], v149 offset:1024
	ds_read_b128 v[196:199], v150
	ds_read_b128 v[200:203], v150 offset:1024
	ds_read_b128 v[204:207], v151
	ds_read_b128 v[208:211], v151 offset:1024
	ds_read_b128 v[214:217], v152
	ds_read_b128 v[218:221], v152 offset:1024
	buffer_load_dwordx4 v128, s[24:27], s6 offen lds
	s_mov_b32 m0, s7
	s_nop 0
	buffer_load_dwordx4 v129, s[24:27], s6 offen lds
	s_waitcnt vmcnt(8)
	s_waitcnt lgkmcnt(0)
	s_barrier
; #define LDA(dst, b, h) for (int m = 0; m < 4; ++m) for (int k = 0; k < 2; ++k) \
;     dst[m][k] = *reinterpret_cast<const bf16x8*>((char*)SA(b, h) + lds_byte(wr * 64 + m * 16 + fr, k * 32 + fq * 8))
; #define MMA(ai, bj, At, Bt_) do { __builtin_amdgcn_s_setprio(1); \
;     for (int m = 0; m < 4; ++m) for (int n = 0; n < 2; ++n) for (int k = 0; k < 2; ++k) \
;       acc[ai][bj][m][n] = __builtin_amdgcn_mfma_f32_16x16x32_bf16(Bt_[n][k], At[m][k], acc[ai][bj][m][n], 0, 0, 0); \
;     __builtin_amdgcn_s_setprio(0); } while (0)
; #define WAIT_V(n) asm volatile("s_waitcnt vmcnt(" #n ")" ::: "memory")
; #define WAIT_L(n) asm volatile("s_waitcnt lgkmcnt(" #n ")" ::: "memory")
; #define BAR __builtin_amdgcn_s_barrier()
; #define SCHED __builtin_amdgcn_sched_barrier(0)
; template <int MODE>
; DI void gemm_phase(const bf16_t* __restrict__ A, const bf16_t* __restrict__ Bt, int M, int N, int K, const Epi& ep) {
;     ...
;             WAIT_V(8); WAIT_L(0); BAR; MMA(0, 0, At, B0); MMA(0, 1, At, B1); BAR; SCHED;
;             LDA(At, 0, 1);
;             WAIT_V(2); WAIT_L(0); BAR; MMA(1, 0, At, B0); MMA(1, 1, At, B1); BAR; SCHED;
	s_setprio 1
	s_waitcnt lgkmcnt(7)
	v_mfma_f32_16x16x32_bf16 v[124:127], v[156:159], v[188:191], v[124:127]
	v_mfma_f32_16x16x32_bf16 v[120:123], v[164:167], v[188:191], v[120:123]
	s_waitcnt lgkmcnt(5)
	v_mfma_f32_16x16x32_bf16 v[116:119], v[156:159], v[196:199], v[116:119]
	v_mfma_f32_16x16x32_bf16 v[112:115], v[164:167], v[196:199], v[112:115]
	s_waitcnt lgkmcnt(3)
	v_mfma_f32_16x16x32_bf16 v[108:111], v[156:159], v[204:207], v[108:111]
	v_mfma_f32_16x16x32_bf16 v[124:127], v[160:163], v[192:195], v[124:127]
	v_mfma_f32_16x16x32_bf16 v[120:123], v[168:171], v[192:195], v[120:123]
	v_mfma_f32_16x16x32_bf16 v[116:119], v[160:163], v[200:203], v[116:119]
	v_mfma_f32_16x16x32_bf16 v[112:115], v[168:171], v[200:203], v[112:115]
	s_waitcnt lgkmcnt(2)
	v_mfma_f32_16x16x32_bf16 v[222:225], v[160:163], v[208:211], v[108:111]
	v_mfma_f32_16x16x32_bf16 v[104:107], v[164:167], v[204:207], v[104:107]
	s_waitcnt lgkmcnt(1)
	v_mfma_f32_16x16x32_bf16 v[100:103], v[156:159], v[214:217], v[100:103]
	v_mfma_f32_16x16x32_bf16 v[96:99], v[164:167], v[214:217], v[96:99]
	v_mfma_f32_16x16x32_bf16 v[226:229], v[168:171], v[208:211], v[104:107]
	s_waitcnt lgkmcnt(0)
	v_mfma_f32_16x16x32_bf16 v[230:233], v[160:163], v[218:221], v[100:103]
	v_mfma_f32_16x16x32_bf16 v[234:237], v[168:171], v[218:221], v[96:99]
	s_setprio 0
	s_setprio 1
	v_mfma_f32_16x16x32_bf16 v[92:95], v[172:175], v[188:191], v[92:95]
	v_mfma_f32_16x16x32_bf16 v[88:91], v[180:183], v[188:191], v[88:91]
	v_mfma_f32_16x16x32_bf16 v[84:87], v[172:175], v[196:199], v[84:87]
	v_mfma_f32_16x16x32_bf16 v[80:83], v[180:183], v[196:199], v[80:83]
	v_mfma_f32_16x16x32_bf16 v[92:95], v[176:179], v[192:195], v[92:95]
	v_mfma_f32_16x16x32_bf16 v[88:91], v[184:187], v[192:195], v[88:91]
	v_mfma_f32_16x16x32_bf16 v[84:87], v[176:179], v[200:203], v[84:87]
	v_mfma_f32_16x16x32_bf16 v[80:83], v[184:187], v[200:203], v[80:83]
	v_mfma_f32_16x16x32_bf16 v[76:79], v[172:175], v[204:207], v[76:79]
	v_mfma_f32_16x16x32_bf16 v[72:75], v[180:183], v[204:207], v[72:75]
	v_mfma_f32_16x16x32_bf16 v[68:71], v[172:175], v[214:217], v[68:71]
	v_mfma_f32_16x16x32_bf16 v[64:67], v[180:183], v[214:217], v[64:67]
	v_mfma_f32_16x16x32_bf16 v[188:191], v[176:179], v[208:211], v[76:79]
	v_mfma_f32_16x16x32_bf16 v[192:195], v[184:187], v[208:211], v[72:75]
	v_mfma_f32_16x16x32_bf16 v[196:199], v[176:179], v[218:221], v[68:71]
	v_mfma_f32_16x16x32_bf16 v[200:203], v[184:187], v[218:221], v[64:67]
	s_setprio 0
	s_barrier
	s_nop 1
	ds_read_b128 v[64:67], v149 offset:16384
	ds_read_b128 v[68:71], v149 offset:17408
	ds_read_b128 v[72:75], v150 offset:16384
	ds_read_b128 v[76:79], v150 offset:17408
	ds_read_b128 v[96:99], v151 offset:16384
	ds_read_b128 v[100:103], v151 offset:17408
	ds_read_b128 v[104:107], v152 offset:16384
	ds_read_b128 v[108:111], v152 offset:17408
	s_waitcnt vmcnt(2)
	s_waitcnt lgkmcnt(0)
	s_barrier
	s_setprio 1
	s_waitcnt lgkmcnt(7)
	v_mfma_f32_16x16x32_bf16 v[60:63], v[156:159], v[64:67], v[60:63]
	v_mfma_f32_16x16x32_bf16 v[56:59], v[164:167], v[64:67], v[56:59]
	s_waitcnt lgkmcnt(5)
	v_mfma_f32_16x16x32_bf16 v[52:55], v[156:159], v[72:75], v[52:55]
	v_mfma_f32_16x16x32_bf16 v[48:51], v[164:167], v[72:75], v[48:51]
	v_mfma_f32_16x16x32_bf16 v[60:63], v[160:163], v[68:71], v[60:63]
	v_mfma_f32_16x16x32_bf16 v[56:59], v[168:171], v[68:71], v[56:59]
	s_waitcnt lgkmcnt(4)
	v_mfma_f32_16x16x32_bf16 v[52:55], v[160:163], v[76:79], v[52:55]
	v_mfma_f32_16x16x32_bf16 v[48:51], v[168:171], v[76:79], v[48:51]
	s_waitcnt lgkmcnt(3)
	v_mfma_f32_16x16x32_bf16 v[44:47], v[156:159], v[96:99], v[44:47]
	v_mfma_f32_16x16x32_bf16 v[40:43], v[164:167], v[96:99], v[40:43]
	s_waitcnt lgkmcnt(1)
	v_mfma_f32_16x16x32_bf16 v[36:39], v[156:159], v[104:107], v[36:39]
	v_mfma_f32_16x16x32_bf16 v[32:35], v[164:167], v[104:107], v[32:35]
	v_mfma_f32_16x16x32_bf16 v[204:207], v[160:163], v[100:103], v[44:47]
	v_mfma_f32_16x16x32_bf16 v[208:211], v[168:171], v[100:103], v[40:43]
	s_waitcnt lgkmcnt(0)
	v_mfma_f32_16x16x32_bf16 v[156:159], v[160:163], v[108:111], v[36:39]
	v_mfma_f32_16x16x32_bf16 v[160:163], v[168:171], v[108:111], v[32:35]
	s_setprio 0
	s_setprio 1
	v_mfma_f32_16x16x32_bf16 v[28:31], v[172:175], v[64:67], v[28:31]
	v_mfma_f32_16x16x32_bf16 v[24:27], v[180:183], v[64:67], v[24:27]
	v_mfma_f32_16x16x32_bf16 v[20:23], v[172:175], v[72:75], v[20:23]
	v_mfma_f32_16x16x32_bf16 v[16:19], v[180:183], v[72:75], v[16:19]
	v_mfma_f32_16x16x32_bf16 v[28:31], v[176:179], v[68:71], v[28:31]
	v_mfma_f32_16x16x32_bf16 v[24:27], v[184:187], v[68:71], v[24:27]
	v_mfma_f32_16x16x32_bf16 v[20:23], v[176:179], v[76:79], v[20:23]
	v_mfma_f32_16x16x32_bf16 v[16:19], v[184:187], v[76:79], v[16:19]
	v_mfma_f32_16x16x32_bf16 v[12:15], v[172:175], v[96:99], v[12:15]
	v_mfma_f32_16x16x32_bf16 v[8:11], v[180:183], v[96:99], v[8:11]
	v_mfma_f32_16x16x32_bf16 v[4:7], v[172:175], v[104:107], v[4:7]
	v_mfma_f32_16x16x32_bf16 v[0:3], v[180:183], v[104:107], v[0:3]
	v_mfma_f32_16x16x32_bf16 v[164:167], v[176:179], v[100:103], v[12:15]
	v_mfma_f32_16x16x32_bf16 v[168:171], v[184:187], v[100:103], v[8:11]
	v_mfma_f32_16x16x32_bf16 v[172:175], v[176:179], v[108:111], v[4:7]
	v_mfma_f32_16x16x32_bf16 v[176:179], v[184:187], v[108:111], v[0:3]
	s_setprio 0
	s_barrier
; #define LDA(dst, b, h) for (int m = 0; m < 4; ++m) for (int k = 0; k < 2; ++k) \
;     dst[m][k] = *reinterpret_cast<const bf16x8*>((char*)SA(b, h) + lds_byte(wr * 64 + m * 16 + fr, k * 32 + fq * 8))
; #define LDB(dst, b, h) for (int n = 0; n < 2; ++n) for (int k = 0; k < 2; ++k) \
;     dst[n][k] = *reinterpret_cast<const bf16x8*>((char*)SB(b, h) + lds_byte(wc * 32 + n * 16 + fr, k * 32 + fq * 8))
; #define MMA(ai, bj, At, Bt_) do { __builtin_amdgcn_s_setprio(1); \
;     for (int m = 0; m < 4; ++m) for (int n = 0; n < 2; ++n) for (int k = 0; k < 2; ++k) \
;       acc[ai][bj][m][n] = __builtin_amdgcn_mfma_f32_16x16x32_bf16(Bt_[n][k], At[m][k], acc[ai][bj][m][n], 0, 0, 0); \
;     __builtin_amdgcn_s_setprio(0); } while (0)
; #define WAIT_V(n) asm volatile("s_waitcnt vmcnt(" #n ")" ::: "memory")
; #define WAIT_L(n) asm volatile("s_waitcnt lgkmcnt(" #n ")" ::: "memory")
; #define BAR __builtin_amdgcn_s_barrier()
; #define SCHED __builtin_amdgcn_sched_barrier(0)
; template <int MODE>
; DI void gemm_phase(const bf16_t* __restrict__ A, const bf16_t* __restrict__ Bt, int M, int N, int K, const Epi& ep) {
;     ...
;             LDB(B0, 1, 0); LDB(B1, 1, 1); SCHED; LDA(At, 1, 0);
;             WAIT_V(0); WAIT_L(0); BAR; MMA(0, 0, At, B0); MMA(0, 1, At, B1); BAR; SCHED;
;             LDA(At, 1, 1);
;             WAIT_L(0); BAR; MMA(1, 0, At, B0); MMA(1, 1, At, B1); BAR; SCHED;
;         }
;         if (wr == 0) BAR;
	s_nop 1
	ds_read_b128 v[0:3], v153
	ds_read_b128 v[4:7], v153 offset:1024
	ds_read_b128 v[8:11], v153 offset:2048
	ds_read_b128 v[12:15], v153 offset:3072
	ds_read_b128 v[180:183], v154
	ds_read_b128 v[184:187], v154 offset:1024
	ds_read_b128 v[214:217], v154 offset:2048
	ds_read_b128 v[218:221], v154 offset:3072
	ds_read_b128 v[32:35], v149 offset:32768
	ds_read_b128 v[36:39], v149 offset:33792
	ds_read_b128 v[40:43], v150 offset:32768
	ds_read_b128 v[44:47], v150 offset:33792
	ds_read_b128 v[238:241], v151 offset:32768
	ds_read_b128 v[242:245], v151 offset:33792
	ds_read_b128 v[246:249], v152 offset:32768
	ds_read_b128 v[64:67], v152 offset:33792
	s_waitcnt vmcnt(0)
	s_waitcnt lgkmcnt(0)
	s_barrier
	s_setprio 1
	s_waitcnt lgkmcnt(7)
	v_mfma_f32_16x16x32_bf16 v[68:71], v[0:3], v[32:35], v[124:127]
	s_waitcnt lgkmcnt(6)
	v_mfma_f32_16x16x32_bf16 v[96:99], v[4:7], v[36:39], v[68:71]
	v_mfma_f32_16x16x32_bf16 v[68:71], v[8:11], v[32:35], v[120:123]
	v_mfma_f32_16x16x32_bf16 v[100:103], v[12:15], v[36:39], v[68:71]
	s_waitcnt lgkmcnt(5)
	v_mfma_f32_16x16x32_bf16 v[68:71], v[0:3], v[40:43], v[116:119]
	s_waitcnt lgkmcnt(4)
	v_mfma_f32_16x16x32_bf16 v[104:107], v[4:7], v[44:47], v[68:71]
	v_mfma_f32_16x16x32_bf16 v[68:71], v[8:11], v[40:43], v[112:115]
	v_mfma_f32_16x16x32_bf16 v[108:111], v[12:15], v[44:47], v[68:71]
	s_waitcnt lgkmcnt(3)
	v_mfma_f32_16x16x32_bf16 v[68:71], v[0:3], v[238:241], v[222:225]
	s_waitcnt lgkmcnt(2)
	v_mfma_f32_16x16x32_bf16 v[112:115], v[4:7], v[242:245], v[68:71]
	v_mfma_f32_16x16x32_bf16 v[68:71], v[8:11], v[238:241], v[226:229]
	v_mfma_f32_16x16x32_bf16 v[116:119], v[12:15], v[242:245], v[68:71]
	s_waitcnt lgkmcnt(1)
	v_mfma_f32_16x16x32_bf16 v[68:71], v[0:3], v[246:249], v[230:233]
	s_waitcnt lgkmcnt(0)
	v_mfma_f32_16x16x32_bf16 v[120:123], v[4:7], v[64:67], v[68:71]
	v_mfma_f32_16x16x32_bf16 v[68:71], v[8:11], v[246:249], v[234:237]
	v_mfma_f32_16x16x32_bf16 v[124:127], v[12:15], v[64:67], v[68:71]
	s_setprio 0
	s_setprio 1
	v_mfma_f32_16x16x32_bf16 v[68:71], v[180:183], v[32:35], v[92:95]
	v_mfma_f32_16x16x32_bf16 v[32:35], v[214:217], v[32:35], v[88:91]
	v_mfma_f32_16x16x32_bf16 v[222:225], v[184:187], v[36:39], v[68:71]
	v_mfma_f32_16x16x32_bf16 v[68:71], v[218:221], v[36:39], v[32:35]
	v_mfma_f32_16x16x32_bf16 v[32:35], v[180:183], v[40:43], v[84:87]
	v_mfma_f32_16x16x32_bf16 v[72:75], v[184:187], v[44:47], v[32:35]
	v_mfma_f32_16x16x32_bf16 v[32:35], v[214:217], v[40:43], v[80:83]
	v_mfma_f32_16x16x32_bf16 v[76:79], v[218:221], v[44:47], v[32:35]
	v_mfma_f32_16x16x32_bf16 v[32:35], v[180:183], v[238:241], v[188:191]
	v_mfma_f32_16x16x32_bf16 v[80:83], v[184:187], v[242:245], v[32:35]
	v_mfma_f32_16x16x32_bf16 v[32:35], v[214:217], v[238:241], v[192:195]
	v_mfma_f32_16x16x32_bf16 v[84:87], v[218:221], v[242:245], v[32:35]
	v_mfma_f32_16x16x32_bf16 v[32:35], v[180:183], v[246:249], v[196:199]
	v_mfma_f32_16x16x32_bf16 v[88:91], v[184:187], v[64:67], v[32:35]
	v_mfma_f32_16x16x32_bf16 v[32:35], v[214:217], v[246:249], v[200:203]
	v_mfma_f32_16x16x32_bf16 v[92:95], v[218:221], v[64:67], v[32:35]
	s_setprio 0
	s_barrier
	ds_read_b128 v[64:67], v149 offset:49152
	ds_read_b128 v[188:191], v149 offset:50176
	ds_read_b128 v[192:195], v150 offset:49152
	ds_read_b128 v[196:199], v150 offset:50176
	ds_read_b128 v[200:203], v151 offset:49152
	ds_read_b128 v[226:229], v151 offset:50176
	ds_read_b128 v[230:233], v152 offset:49152
	ds_read_b128 v[234:237], v152 offset:50176
	s_waitcnt lgkmcnt(0)
	s_barrier
	s_setprio 1
	s_waitcnt lgkmcnt(7)
	v_mfma_f32_16x16x32_bf16 v[32:35], v[0:3], v[64:67], v[60:63]
	s_waitcnt lgkmcnt(5)
	v_mfma_f32_16x16x32_bf16 v[40:43], v[0:3], v[192:195], v[52:55]
	v_mfma_f32_16x16x32_bf16 v[44:47], v[8:11], v[192:195], v[48:51]
	s_waitcnt lgkmcnt(3)
	v_mfma_f32_16x16x32_bf16 v[48:51], v[0:3], v[200:203], v[204:207]
	s_waitcnt lgkmcnt(1)
	v_mfma_f32_16x16x32_bf16 v[0:3], v[0:3], v[230:233], v[156:159]
	v_mfma_f32_16x16x32_bf16 v[36:39], v[8:11], v[64:67], v[56:59]
	v_mfma_f32_16x16x32_bf16 v[52:55], v[8:11], v[200:203], v[208:211]
	s_waitcnt lgkmcnt(0)
	v_mfma_f32_16x16x32_bf16 v[56:59], v[4:7], v[234:237], v[0:3]
	v_mfma_f32_16x16x32_bf16 v[0:3], v[8:11], v[230:233], v[160:163]
	v_mfma_f32_16x16x32_bf16 v[32:35], v[4:7], v[188:191], v[32:35]
	v_mfma_f32_16x16x32_bf16 v[36:39], v[12:15], v[188:191], v[36:39]
	v_mfma_f32_16x16x32_bf16 v[40:43], v[4:7], v[196:199], v[40:43]
	v_mfma_f32_16x16x32_bf16 v[44:47], v[12:15], v[196:199], v[44:47]
	v_mfma_f32_16x16x32_bf16 v[48:51], v[4:7], v[226:229], v[48:51]
	v_mfma_f32_16x16x32_bf16 v[52:55], v[12:15], v[226:229], v[52:55]
	v_mfma_f32_16x16x32_bf16 v[60:63], v[12:15], v[234:237], v[0:3]
	s_setprio 0
	s_setprio 1
	v_mfma_f32_16x16x32_bf16 v[0:3], v[180:183], v[64:67], v[28:31]
	v_mfma_f32_16x16x32_bf16 v[4:7], v[214:217], v[64:67], v[24:27]
	v_mfma_f32_16x16x32_bf16 v[8:11], v[180:183], v[192:195], v[20:23]
	v_mfma_f32_16x16x32_bf16 v[12:15], v[214:217], v[192:195], v[16:19]
	v_mfma_f32_16x16x32_bf16 v[16:19], v[180:183], v[200:203], v[164:167]
	v_mfma_f32_16x16x32_bf16 v[20:23], v[214:217], v[200:203], v[168:171]
	v_mfma_f32_16x16x32_bf16 v[24:27], v[180:183], v[230:233], v[172:175]
	v_mfma_f32_16x16x32_bf16 v[28:31], v[214:217], v[230:233], v[176:179]
	v_mfma_f32_16x16x32_bf16 v[0:3], v[184:187], v[188:191], v[0:3]
	v_mfma_f32_16x16x32_bf16 v[4:7], v[218:221], v[188:191], v[4:7]
	v_mfma_f32_16x16x32_bf16 v[8:11], v[184:187], v[196:199], v[8:11]
	v_mfma_f32_16x16x32_bf16 v[12:15], v[218:221], v[196:199], v[12:15]
	v_mfma_f32_16x16x32_bf16 v[16:19], v[184:187], v[226:229], v[16:19]
	v_mfma_f32_16x16x32_bf16 v[20:23], v[218:221], v[226:229], v[20:23]
	v_mfma_f32_16x16x32_bf16 v[24:27], v[184:187], v[234:237], v[24:27]
	v_mfma_f32_16x16x32_bf16 v[28:31], v[218:221], v[234:237], v[28:31]
	s_setprio 0
	s_barrier
	s_and_saveexec_b64 s[6:7], s[38:39]
	s_cbranch_execz .LBB0_1015
	s_barrier
	s_branch .LBB0_1015

; #define LDA(dst, b, h) for (int m = 0; m < 4; ++m) for (int k = 0; k < 2; ++k) \
;     dst[m][k] = *reinterpret_cast<const bf16x8*>((char*)SA(b, h) + lds_byte(wr * 64 + m * 16 + fr, k * 32 + fq * 8))
; #define LDB(dst, b, h) for (int n = 0; n < 2; ++n) for (int k = 0; k < 2; ++k) \
;     dst[n][k] = *reinterpret_cast<const bf16x8*>((char*)SB(b, h) + lds_byte(wc * 32 + n * 16 + fr, k * 32 + fq * 8))
; #define MMA(ai, bj, At, Bt_) do { __builtin_amdgcn_s_setprio(1); \
;     for (int m = 0; m < 4; ++m) for (int n = 0; n < 2; ++n) for (int k = 0; k < 2; ++k) \
;       acc[ai][bj][m][n] = __builtin_amdgcn_mfma_f32_16x16x32_bf16(Bt_[n][k], At[m][k], acc[ai][bj][m][n], 0, 0, 0); \
;     __builtin_amdgcn_s_setprio(0); } while (0)
; #define WAIT_V(n) asm volatile("s_waitcnt vmcnt(" #n ")" ::: "memory")
; #define WAIT_L(n) asm volatile("s_waitcnt lgkmcnt(" #n ")" ::: "memory")
; #define BAR __builtin_amdgcn_s_barrier()
; #define SCHED __builtin_amdgcn_sched_barrier(0)
; template <int MODE>
; DI void gemm_phase(const bf16_t* __restrict__ A, const bf16_t* __restrict__ Bt, int M, int N, int K, const Epi& ep) {
;     ...
;             LDB(B0, 0, 0); LDB(B1, 0, 1); SCHED; LDA(At, 0, 0); STAGE(SA(1, 1), rsA, brow + HALF, t + 1);
;             WAIT_V(8); WAIT_L(0); BAR; MMA(0, 0, At, B0); MMA(0, 1, At, B1); BAR; SCHED;
;             LDA(At, 0, 1); STAGE(SB(0, 0), rsB, bcol, t + 2); STAGE(SB(0, 1), rsB, bcol + HALF, t + 2); STAGE(SA(0, 0), rsA, brow, t + 2);
.LBB0_1150:
	ds_read_b128 v[128:131], v186
	ds_read_b128 v[132:135], v186 offset:1024
	ds_read_b128 v[136:139], v186 offset:2048
	ds_read_b128 v[140:143], v186 offset:3072
	ds_read_b128 v[144:147], v187
	ds_read_b128 v[148:151], v187 offset:1024
	ds_read_b128 v[152:155], v187 offset:2048
	ds_read_b128 v[156:159], v187 offset:3072
	s_add_i32 s41, s0, s40
	v_readfirstlane_b32 s43, v184
	s_add_i32 s42, s41, 0x40080
	s_mov_b32 m0, s43
	v_readfirstlane_b32 s43, v185
	ds_read_b128 v[160:163], v188
	ds_read_b128 v[164:167], v188 offset:1024
	ds_read_b128 v[196:199], v189
	ds_read_b128 v[200:203], v189 offset:1024
	ds_read_b128 v[204:207], v190
	ds_read_b128 v[208:211], v190 offset:1024
	ds_read_b128 v[214:217], v191
	ds_read_b128 v[218:221], v191 offset:1024
	buffer_load_dwordx4 v168, s[8:11], s42 offen lds
	s_mov_b32 m0, s43
	s_nop 0
	buffer_load_dwordx4 v169, s[8:11], s42 offen lds
	s_waitcnt vmcnt(8)
	s_waitcnt lgkmcnt(0)
	s_barrier
	s_setprio 1
	s_waitcnt lgkmcnt(7)
	v_mfma_f32_16x16x32_bf16 v[124:127], v[128:131], v[160:163], v[124:127]
	v_mfma_f32_16x16x32_bf16 v[120:123], v[136:139], v[160:163], v[120:123]
	s_waitcnt lgkmcnt(5)
	v_mfma_f32_16x16x32_bf16 v[116:119], v[128:131], v[196:199], v[116:119]
	v_mfma_f32_16x16x32_bf16 v[112:115], v[136:139], v[196:199], v[112:115]
	s_waitcnt lgkmcnt(3)
	v_mfma_f32_16x16x32_bf16 v[108:111], v[128:131], v[204:207], v[108:111]
	v_mfma_f32_16x16x32_bf16 v[104:107], v[136:139], v[204:207], v[104:107]
	s_waitcnt lgkmcnt(1)
	v_mfma_f32_16x16x32_bf16 v[100:103], v[128:131], v[214:217], v[100:103]
	v_mfma_f32_16x16x32_bf16 v[96:99], v[136:139], v[214:217], v[96:99]
	v_mfma_f32_16x16x32_bf16 v[124:127], v[132:135], v[164:167], v[124:127]
	v_mfma_f32_16x16x32_bf16 v[120:123], v[140:143], v[164:167], v[120:123]
	v_mfma_f32_16x16x32_bf16 v[116:119], v[132:135], v[200:203], v[116:119]
	v_mfma_f32_16x16x32_bf16 v[112:115], v[140:143], v[200:203], v[112:115]
	v_mfma_f32_16x16x32_bf16 v[108:111], v[132:135], v[208:211], v[108:111]
	v_mfma_f32_16x16x32_bf16 v[104:107], v[140:143], v[208:211], v[104:107]
	s_waitcnt lgkmcnt(0)
	v_mfma_f32_16x16x32_bf16 v[100:103], v[132:135], v[218:221], v[100:103]
	v_mfma_f32_16x16x32_bf16 v[96:99], v[140:143], v[218:221], v[96:99]
	s_setprio 0
	s_setprio 1
	v_mfma_f32_16x16x32_bf16 v[92:95], v[144:147], v[160:163], v[92:95]
	v_mfma_f32_16x16x32_bf16 v[88:91], v[152:155], v[160:163], v[88:91]
	v_mfma_f32_16x16x32_bf16 v[84:87], v[144:147], v[196:199], v[84:87]
	v_mfma_f32_16x16x32_bf16 v[80:83], v[152:155], v[196:199], v[80:83]
	v_mfma_f32_16x16x32_bf16 v[76:79], v[144:147], v[204:207], v[76:79]
	v_mfma_f32_16x16x32_bf16 v[72:75], v[152:155], v[204:207], v[72:75]
	v_mfma_f32_16x16x32_bf16 v[68:71], v[144:147], v[214:217], v[68:71]
	v_mfma_f32_16x16x32_bf16 v[64:67], v[152:155], v[214:217], v[64:67]
	v_mfma_f32_16x16x32_bf16 v[92:95], v[148:151], v[164:167], v[92:95]
	v_mfma_f32_16x16x32_bf16 v[88:91], v[156:159], v[164:167], v[88:91]
	v_mfma_f32_16x16x32_bf16 v[84:87], v[148:151], v[200:203], v[84:87]
	v_mfma_f32_16x16x32_bf16 v[80:83], v[156:159], v[200:203], v[80:83]
	v_mfma_f32_16x16x32_bf16 v[76:79], v[148:151], v[208:211], v[76:79]
	v_mfma_f32_16x16x32_bf16 v[72:75], v[156:159], v[208:211], v[72:75]
	v_mfma_f32_16x16x32_bf16 v[68:71], v[148:151], v[218:221], v[68:71]
	v_mfma_f32_16x16x32_bf16 v[64:67], v[156:159], v[218:221], v[64:67]
	s_setprio 0
	s_barrier
	s_add_i32 s42, s1, s40
	v_readfirstlane_b32 s44, v170
	s_add_i32 s43, s42, 0x100
	s_mov_b32 s66, s10
	s_mov_b32 s67, s11
	s_mov_b32 m0, s44
	v_readfirstlane_b32 s44, v171
	ds_read_b128 v[160:163], v188 offset:16384
	ds_read_b128 v[164:167], v188 offset:17408
	ds_read_b128 v[196:199], v189 offset:16384
	ds_read_b128 v[200:203], v189 offset:17408
	ds_read_b128 v[204:207], v190 offset:16384
	ds_read_b128 v[208:211], v190 offset:17408
	ds_read_b128 v[214:217], v191 offset:16384
	ds_read_b128 v[218:221], v191 offset:17408
	buffer_load_dwordx4 v168, s[64:67], s43 offen lds
	s_mov_b32 m0, s44
	v_readfirstlane_b32 s44, v172
	buffer_load_dwordx4 v169, s[64:67], s43 offen lds
	s_add_i32 s43, s42, 0x40100
	s_mov_b32 m0, s44
	v_readfirstlane_b32 s44, v173
	buffer_load_dwordx4 v168, s[64:67], s43 offen lds
	s_mov_b32 m0, s44
	v_readfirstlane_b32 s44, v174
	buffer_load_dwordx4 v169, s[64:67], s43 offen lds
	s_add_i32 s43, s41, 0x100
	s_mov_b32 m0, s44
	v_readfirstlane_b32 s44, v175
	buffer_load_dwordx4 v168, s[8:11], s43 offen lds
	s_mov_b32 m0, s44
	s_nop 0
	buffer_load_dwordx4 v169, s[8:11], s43 offen lds
	s_waitcnt vmcnt(8)
	s_waitcnt lgkmcnt(0)
	s_barrier
; #define LDA(dst, b, h) for (int m = 0; m < 4; ++m) for (int k = 0; k < 2; ++k) \
;     dst[m][k] = *reinterpret_cast<const bf16x8*>((char*)SA(b, h) + lds_byte(wr * 64 + m * 16 + fr, k * 32 + fq * 8))
; #define LDB(dst, b, h) for (int n = 0; n < 2; ++n) for (int k = 0; k < 2; ++k) \
;     dst[n][k] = *reinterpret_cast<const bf16x8*>((char*)SB(b, h) + lds_byte(wc * 32 + n * 16 + fr, k * 32 + fq * 8))
; #define MMA(ai, bj, At, Bt_) do { __builtin_amdgcn_s_setprio(1); \
;     for (int m = 0; m < 4; ++m) for (int n = 0; n < 2; ++n) for (int k = 0; k < 2; ++k) \
;       acc[ai][bj][m][n] = __builtin_amdgcn_mfma_f32_16x16x32_bf16(Bt_[n][k], At[m][k], acc[ai][bj][m][n], 0, 0, 0); \
;     __builtin_amdgcn_s_setprio(0); } while (0)
; #define WAIT_V(n) asm volatile("s_waitcnt vmcnt(" #n ")" ::: "memory")
; #define WAIT_L(n) asm volatile("s_waitcnt lgkmcnt(" #n ")" ::: "memory")
; #define BAR __builtin_amdgcn_s_barrier()
; #define SCHED __builtin_amdgcn_sched_barrier(0)
; template <int MODE>
; DI void gemm_phase(const bf16_t* __restrict__ A, const bf16_t* __restrict__ Bt, int M, int N, int K, const Epi& ep) {
;     ...
;             WAIT_V(8); WAIT_L(0); BAR; MMA(1, 0, At, B0); MMA(1, 1, At, B1); BAR; SCHED;
;             LDB(B0, 1, 0); LDB(B1, 1, 1); SCHED; LDA(At, 1, 0); STAGE(SA(0, 1), rsA, brow + HALF, t + 2);
;             WAIT_V(8); WAIT_L(0); BAR; MMA(0, 0, At, B0); MMA(0, 1, At, B1); BAR; SCHED;
	s_setprio 1
	s_waitcnt lgkmcnt(7)
	v_mfma_f32_16x16x32_bf16 v[60:63], v[128:131], v[160:163], v[60:63]
	v_mfma_f32_16x16x32_bf16 v[56:59], v[136:139], v[160:163], v[56:59]
	s_waitcnt lgkmcnt(5)
	v_mfma_f32_16x16x32_bf16 v[52:55], v[128:131], v[196:199], v[52:55]
	v_mfma_f32_16x16x32_bf16 v[48:51], v[136:139], v[196:199], v[48:51]
	s_waitcnt lgkmcnt(3)
	v_mfma_f32_16x16x32_bf16 v[44:47], v[128:131], v[204:207], v[44:47]
	v_mfma_f32_16x16x32_bf16 v[40:43], v[136:139], v[204:207], v[40:43]
	s_waitcnt lgkmcnt(1)
	v_mfma_f32_16x16x32_bf16 v[36:39], v[128:131], v[214:217], v[36:39]
	v_mfma_f32_16x16x32_bf16 v[32:35], v[136:139], v[214:217], v[32:35]
	v_mfma_f32_16x16x32_bf16 v[60:63], v[132:135], v[164:167], v[60:63]
	v_mfma_f32_16x16x32_bf16 v[56:59], v[140:143], v[164:167], v[56:59]
	v_mfma_f32_16x16x32_bf16 v[52:55], v[132:135], v[200:203], v[52:55]
	v_mfma_f32_16x16x32_bf16 v[48:51], v[140:143], v[200:203], v[48:51]
	v_mfma_f32_16x16x32_bf16 v[44:47], v[132:135], v[208:211], v[44:47]
	v_mfma_f32_16x16x32_bf16 v[40:43], v[140:143], v[208:211], v[40:43]
	s_waitcnt lgkmcnt(0)
	v_mfma_f32_16x16x32_bf16 v[36:39], v[132:135], v[218:221], v[36:39]
	v_mfma_f32_16x16x32_bf16 v[32:35], v[140:143], v[218:221], v[32:35]
	s_setprio 0
	s_setprio 1
	v_mfma_f32_16x16x32_bf16 v[28:31], v[144:147], v[160:163], v[28:31]
	v_mfma_f32_16x16x32_bf16 v[24:27], v[152:155], v[160:163], v[24:27]
	v_mfma_f32_16x16x32_bf16 v[20:23], v[144:147], v[196:199], v[20:23]
	v_mfma_f32_16x16x32_bf16 v[16:19], v[152:155], v[196:199], v[16:19]
	v_mfma_f32_16x16x32_bf16 v[12:15], v[144:147], v[204:207], v[12:15]
	v_mfma_f32_16x16x32_bf16 v[8:11], v[152:155], v[204:207], v[8:11]
	v_mfma_f32_16x16x32_bf16 v[4:7], v[144:147], v[214:217], v[4:7]
	v_mfma_f32_16x16x32_bf16 v[0:3], v[152:155], v[214:217], v[0:3]
	v_mfma_f32_16x16x32_bf16 v[28:31], v[148:151], v[164:167], v[28:31]
	v_mfma_f32_16x16x32_bf16 v[24:27], v[156:159], v[164:167], v[24:27]
	v_mfma_f32_16x16x32_bf16 v[20:23], v[148:151], v[200:203], v[20:23]
	v_mfma_f32_16x16x32_bf16 v[16:19], v[156:159], v[200:203], v[16:19]
	v_mfma_f32_16x16x32_bf16 v[12:15], v[148:151], v[208:211], v[12:15]
	v_mfma_f32_16x16x32_bf16 v[8:11], v[156:159], v[208:211], v[8:11]
	v_mfma_f32_16x16x32_bf16 v[4:7], v[148:151], v[218:221], v[4:7]
	v_mfma_f32_16x16x32_bf16 v[0:3], v[156:159], v[218:221], v[0:3]
	s_setprio 0
	s_barrier
	ds_read_b128 v[128:131], v192
	ds_read_b128 v[132:135], v192 offset:1024
	ds_read_b128 v[136:139], v192 offset:2048
	ds_read_b128 v[140:143], v192 offset:3072
	ds_read_b128 v[144:147], v193
	ds_read_b128 v[148:151], v193 offset:1024
	ds_read_b128 v[152:155], v193 offset:2048
	ds_read_b128 v[156:159], v193 offset:3072
	v_readfirstlane_b32 s44, v176
	s_add_i32 s43, s41, 0x40100
	s_mov_b32 m0, s44
	v_readfirstlane_b32 s44, v177
	ds_read_b128 v[160:163], v188 offset:32768
	ds_read_b128 v[164:167], v188 offset:33792
	ds_read_b128 v[196:199], v189 offset:32768
	ds_read_b128 v[200:203], v189 offset:33792
	ds_read_b128 v[204:207], v190 offset:32768
	ds_read_b128 v[208:211], v190 offset:33792
	ds_read_b128 v[214:217], v191 offset:32768
	ds_read_b128 v[218:221], v191 offset:33792
	buffer_load_dwordx4 v168, s[8:11], s43 offen lds
	s_mov_b32 m0, s44
	s_nop 0
	buffer_load_dwordx4 v169, s[8:11], s43 offen lds
	s_waitcnt vmcnt(8)
	s_waitcnt lgkmcnt(0)
	s_barrier
	s_setprio 1
	s_waitcnt lgkmcnt(7)
	v_mfma_f32_16x16x32_bf16 v[124:127], v[128:131], v[160:163], v[124:127]
	v_mfma_f32_16x16x32_bf16 v[120:123], v[136:139], v[160:163], v[120:123]
	s_waitcnt lgkmcnt(5)
	v_mfma_f32_16x16x32_bf16 v[116:119], v[128:131], v[196:199], v[116:119]
	v_mfma_f32_16x16x32_bf16 v[112:115], v[136:139], v[196:199], v[112:115]
	s_waitcnt lgkmcnt(3)
	v_mfma_f32_16x16x32_bf16 v[108:111], v[128:131], v[204:207], v[108:111]
	v_mfma_f32_16x16x32_bf16 v[104:107], v[136:139], v[204:207], v[104:107]
	s_waitcnt lgkmcnt(1)
	v_mfma_f32_16x16x32_bf16 v[100:103], v[128:131], v[214:217], v[100:103]
	v_mfma_f32_16x16x32_bf16 v[96:99], v[136:139], v[214:217], v[96:99]
	v_mfma_f32_16x16x32_bf16 v[124:127], v[132:135], v[164:167], v[124:127]
	v_mfma_f32_16x16x32_bf16 v[120:123], v[140:143], v[164:167], v[120:123]
	v_mfma_f32_16x16x32_bf16 v[116:119], v[132:135], v[200:203], v[116:119]
	v_mfma_f32_16x16x32_bf16 v[112:115], v[140:143], v[200:203], v[112:115]
	v_mfma_f32_16x16x32_bf16 v[108:111], v[132:135], v[208:211], v[108:111]
	v_mfma_f32_16x16x32_bf16 v[104:107], v[140:143], v[208:211], v[104:107]
	s_waitcnt lgkmcnt(0)
	v_mfma_f32_16x16x32_bf16 v[100:103], v[132:135], v[218:221], v[100:103]
	v_mfma_f32_16x16x32_bf16 v[96:99], v[140:143], v[218:221], v[96:99]
	s_setprio 0
	s_setprio 1
	v_mfma_f32_16x16x32_bf16 v[92:95], v[144:147], v[160:163], v[92:95]
	v_mfma_f32_16x16x32_bf16 v[88:91], v[152:155], v[160:163], v[88:91]
	v_mfma_f32_16x16x32_bf16 v[84:87], v[144:147], v[196:199], v[84:87]
	v_mfma_f32_16x16x32_bf16 v[80:83], v[152:155], v[196:199], v[80:83]
	v_mfma_f32_16x16x32_bf16 v[76:79], v[144:147], v[204:207], v[76:79]
	v_mfma_f32_16x16x32_bf16 v[72:75], v[152:155], v[204:207], v[72:75]
	v_mfma_f32_16x16x32_bf16 v[68:71], v[144:147], v[214:217], v[68:71]
	v_mfma_f32_16x16x32_bf16 v[64:67], v[152:155], v[214:217], v[64:67]
	v_mfma_f32_16x16x32_bf16 v[92:95], v[148:151], v[164:167], v[92:95]
	v_mfma_f32_16x16x32_bf16 v[88:91], v[156:159], v[164:167], v[88:91]
	v_mfma_f32_16x16x32_bf16 v[84:87], v[148:151], v[200:203], v[84:87]
	v_mfma_f32_16x16x32_bf16 v[80:83], v[156:159], v[200:203], v[80:83]
	v_mfma_f32_16x16x32_bf16 v[76:79], v[148:151], v[208:211], v[76:79]
	v_mfma_f32_16x16x32_bf16 v[72:75], v[156:159], v[208:211], v[72:75]
	v_mfma_f32_16x16x32_bf16 v[68:71], v[148:151], v[218:221], v[68:71]
	v_mfma_f32_16x16x32_bf16 v[64:67], v[156:159], v[218:221], v[64:67]
	s_setprio 0
	s_barrier
; #define LDA(dst, b, h) for (int m = 0; m < 4; ++m) for (int k = 0; k < 2; ++k) \
;     dst[m][k] = *reinterpret_cast<const bf16x8*>((char*)SA(b, h) + lds_byte(wr * 64 + m * 16 + fr, k * 32 + fq * 8))
; #define LDB(dst, b, h) for (int n = 0; n < 2; ++n) for (int k = 0; k < 2; ++k) \
;     dst[n][k] = *reinterpret_cast<const bf16x8*>((char*)SB(b, h) + lds_byte(wc * 32 + n * 16 + fr, k * 32 + fq * 8))
; #define MMA(ai, bj, At, Bt_) do { __builtin_amdgcn_s_setprio(1); \
;     for (int m = 0; m < 4; ++m) for (int n = 0; n < 2; ++n) for (int k = 0; k < 2; ++k) \
;       acc[ai][bj][m][n] = __builtin_amdgcn_mfma_f32_16x16x32_bf16(Bt_[n][k], At[m][k], acc[ai][bj][m][n], 0, 0, 0); \
;     __builtin_amdgcn_s_setprio(0); } while (0)
; #define WAIT_V(n) asm volatile("s_waitcnt vmcnt(" #n ")" ::: "memory")
; #define WAIT_L(n) asm volatile("s_waitcnt lgkmcnt(" #n ")" ::: "memory")
; #define BAR __builtin_amdgcn_s_barrier()
; #define SCHED __builtin_amdgcn_sched_barrier(0)
; template <int MODE>
; DI void gemm_phase(const bf16_t* __restrict__ A, const bf16_t* __restrict__ Bt, int M, int N, int K, const Epi& ep) {
;     ...
;             LDA(At, 1, 1); STAGE(SB(1, 0), rsB, bcol, t + 3); STAGE(SB(1, 1), rsB, bcol + HALF, t + 3); STAGE(SA(1, 0), rsA, brow, t + 3);
;             WAIT_V(8); WAIT_L(0); BAR; MMA(1, 0, At, B0); MMA(1, 1, At, B1); BAR; SCHED;
;         }
;         {
;             LDB(B0, 0, 0); LDB(B1, 0, 1); SCHED; LDA(At, 0, 0); STAGE(SA(1, 1), rsA, brow + HALF, nt - 1);
;             WAIT_V(8); WAIT_L(0); BAR; MMA(0, 0, At, B0); MMA(0, 1, At, B1); BAR; SCHED;
	v_readfirstlane_b32 s44, v178
	s_add_i32 s43, s42, 0x180
	s_mov_b32 m0, s44
	v_readfirstlane_b32 s44, v179
	ds_read_b128 v[160:163], v188 offset:49152
	ds_read_b128 v[164:167], v188 offset:50176
	ds_read_b128 v[196:199], v189 offset:49152
	ds_read_b128 v[200:203], v189 offset:50176
	ds_read_b128 v[204:207], v190 offset:49152
	ds_read_b128 v[208:211], v190 offset:50176
	ds_read_b128 v[214:217], v191 offset:49152
	ds_read_b128 v[218:221], v191 offset:50176
	buffer_load_dwordx4 v168, s[64:67], s43 offen lds
	s_mov_b32 m0, s44
	s_add_i32 s42, s42, 0x40180
	buffer_load_dwordx4 v169, s[64:67], s43 offen lds
	v_readfirstlane_b32 s43, v182
	s_mov_b32 m0, s43
	v_readfirstlane_b32 s43, v183
	buffer_load_dwordx4 v168, s[64:67], s42 offen lds
	s_mov_b32 m0, s43
	s_addk_i32 s41, 0x180
	buffer_load_dwordx4 v169, s[64:67], s42 offen lds
	v_readfirstlane_b32 s42, v180
	s_mov_b32 m0, s42
	v_readfirstlane_b32 s42, v181
	buffer_load_dwordx4 v168, s[8:11], s41 offen lds
	s_mov_b32 m0, s42
	s_nop 0
	buffer_load_dwordx4 v169, s[8:11], s41 offen lds
	s_waitcnt vmcnt(8)
	s_waitcnt lgkmcnt(0)
	s_barrier
	s_setprio 1
	s_waitcnt lgkmcnt(7)
	v_mfma_f32_16x16x32_bf16 v[60:63], v[128:131], v[160:163], v[60:63]
	v_mfma_f32_16x16x32_bf16 v[56:59], v[136:139], v[160:163], v[56:59]
	s_waitcnt lgkmcnt(5)
	v_mfma_f32_16x16x32_bf16 v[52:55], v[128:131], v[196:199], v[52:55]
	v_mfma_f32_16x16x32_bf16 v[48:51], v[136:139], v[196:199], v[48:51]
	s_waitcnt lgkmcnt(3)
	v_mfma_f32_16x16x32_bf16 v[44:47], v[128:131], v[204:207], v[44:47]
	v_mfma_f32_16x16x32_bf16 v[40:43], v[136:139], v[204:207], v[40:43]
	s_waitcnt lgkmcnt(1)
	v_mfma_f32_16x16x32_bf16 v[36:39], v[128:131], v[214:217], v[36:39]
	v_mfma_f32_16x16x32_bf16 v[32:35], v[136:139], v[214:217], v[32:35]
	v_mfma_f32_16x16x32_bf16 v[60:63], v[132:135], v[164:167], v[60:63]
	v_mfma_f32_16x16x32_bf16 v[56:59], v[140:143], v[164:167], v[56:59]
	v_mfma_f32_16x16x32_bf16 v[52:55], v[132:135], v[200:203], v[52:55]
	v_mfma_f32_16x16x32_bf16 v[48:51], v[140:143], v[200:203], v[48:51]
	v_mfma_f32_16x16x32_bf16 v[44:47], v[132:135], v[208:211], v[44:47]
	v_mfma_f32_16x16x32_bf16 v[40:43], v[140:143], v[208:211], v[40:43]
	s_waitcnt lgkmcnt(0)
	v_mfma_f32_16x16x32_bf16 v[36:39], v[132:135], v[218:221], v[36:39]
	v_mfma_f32_16x16x32_bf16 v[32:35], v[140:143], v[218:221], v[32:35]
	s_setprio 0
	s_setprio 1
	v_mfma_f32_16x16x32_bf16 v[28:31], v[144:147], v[160:163], v[28:31]
	v_mfma_f32_16x16x32_bf16 v[24:27], v[152:155], v[160:163], v[24:27]
	v_mfma_f32_16x16x32_bf16 v[20:23], v[144:147], v[196:199], v[20:23]
	v_mfma_f32_16x16x32_bf16 v[16:19], v[152:155], v[196:199], v[16:19]
	v_mfma_f32_16x16x32_bf16 v[12:15], v[144:147], v[204:207], v[12:15]
	v_mfma_f32_16x16x32_bf16 v[8:11], v[152:155], v[204:207], v[8:11]
	v_mfma_f32_16x16x32_bf16 v[4:7], v[144:147], v[214:217], v[4:7]
	v_mfma_f32_16x16x32_bf16 v[0:3], v[152:155], v[214:217], v[0:3]
	v_mfma_f32_16x16x32_bf16 v[28:31], v[148:151], v[164:167], v[28:31]
	v_mfma_f32_16x16x32_bf16 v[24:27], v[156:159], v[164:167], v[24:27]
	v_mfma_f32_16x16x32_bf16 v[20:23], v[148:151], v[200:203], v[20:23]
	v_mfma_f32_16x16x32_bf16 v[16:19], v[156:159], v[200:203], v[16:19]
	v_mfma_f32_16x16x32_bf16 v[12:15], v[148:151], v[208:211], v[12:15]
	v_mfma_f32_16x16x32_bf16 v[8:11], v[156:159], v[208:211], v[8:11]
	v_mfma_f32_16x16x32_bf16 v[4:7], v[148:151], v[218:221], v[4:7]
	v_mfma_f32_16x16x32_bf16 v[0:3], v[156:159], v[218:221], v[0:3]
	s_add_i32 s31, s31, 2
	s_addk_i32 s40, 0x100
	s_cmp_lt_u32 s31, 12
	s_setprio 0
	s_barrier
	s_cbranch_scc1 .LBB0_1150
	ds_read_b128 v[128:131], v186
	ds_read_b128 v[132:135], v186 offset:1024
	ds_read_b128 v[136:139], v186 offset:2048
	ds_read_b128 v[140:143], v186 offset:3072
	ds_read_b128 v[144:147], v187
	ds_read_b128 v[148:151], v187 offset:1024
	ds_read_b128 v[152:155], v187 offset:2048
	ds_read_b128 v[156:159], v187 offset:3072
	v_readfirstlane_b32 s1, v184
	s_or_b32 s0, s30, 0x40780
	s_mov_b32 m0, s1
	v_readfirstlane_b32 s1, v185
	ds_read_b128 v[160:163], v188
	ds_read_b128 v[164:167], v188 offset:1024
	ds_read_b128 v[196:199], v189
	ds_read_b128 v[200:203], v189 offset:1024
	ds_read_b128 v[204:207], v190
	ds_read_b128 v[208:211], v190 offset:1024
	ds_read_b128 v[214:217], v191
	ds_read_b128 v[218:221], v191 offset:1024
	buffer_load_dwordx4 v168, s[8:11], s0 offen lds
	s_mov_b32 m0, s1
	s_nop 0
	buffer_load_dwordx4 v169, s[8:11], s0 offen lds
	s_waitcnt vmcnt(8)
	s_waitcnt lgkmcnt(0)
	s_barrier
; #define LDA(dst, b, h) for (int m = 0; m < 4; ++m) for (int k = 0; k < 2; ++k) \
;     dst[m][k] = *reinterpret_cast<const bf16x8*>((char*)SA(b, h) + lds_byte(wr * 64 + m * 16 + fr, k * 32 + fq * 8))
; #define MMA(ai, bj, At, Bt_) do { __builtin_amdgcn_s_setprio(1); \
;     for (int m = 0; m < 4; ++m) for (int n = 0; n < 2; ++n) for (int k = 0; k < 2; ++k) \
;       acc[ai][bj][m][n] = __builtin_amdgcn_mfma_f32_16x16x32_bf16(Bt_[n][k], At[m][k], acc[ai][bj][m][n], 0, 0, 0); \
;     __builtin_amdgcn_s_setprio(0); } while (0)
; #define WAIT_V(n) asm volatile("s_waitcnt vmcnt(" #n ")" ::: "memory")
; #define WAIT_L(n) asm volatile("s_waitcnt lgkmcnt(" #n ")" ::: "memory")
; #define BAR __builtin_amdgcn_s_barrier()
; #define SCHED __builtin_amdgcn_sched_barrier(0)
; template <int MODE>
; DI void gemm_phase(const bf16_t* __restrict__ A, const bf16_t* __restrict__ Bt, int M, int N, int K, const Epi& ep) {
;     ...
;             WAIT_V(8); WAIT_L(0); BAR; MMA(0, 0, At, B0); MMA(0, 1, At, B1); BAR; SCHED;
;             LDA(At, 0, 1);
;             WAIT_V(2); WAIT_L(0); BAR; MMA(1, 0, At, B0); MMA(1, 1, At, B1); BAR; SCHED;
	s_setprio 1
	s_waitcnt lgkmcnt(7)
	v_mfma_f32_16x16x32_bf16 v[124:127], v[128:131], v[160:163], v[124:127]
	v_mfma_f32_16x16x32_bf16 v[120:123], v[136:139], v[160:163], v[120:123]
	s_waitcnt lgkmcnt(5)
	v_mfma_f32_16x16x32_bf16 v[116:119], v[128:131], v[196:199], v[116:119]
	v_mfma_f32_16x16x32_bf16 v[112:115], v[136:139], v[196:199], v[112:115]
	s_waitcnt lgkmcnt(3)
	v_mfma_f32_16x16x32_bf16 v[108:111], v[128:131], v[204:207], v[108:111]
	v_mfma_f32_16x16x32_bf16 v[124:127], v[132:135], v[164:167], v[124:127]
	v_mfma_f32_16x16x32_bf16 v[120:123], v[140:143], v[164:167], v[120:123]
	v_mfma_f32_16x16x32_bf16 v[116:119], v[132:135], v[200:203], v[116:119]
	v_mfma_f32_16x16x32_bf16 v[112:115], v[140:143], v[200:203], v[112:115]
	s_waitcnt lgkmcnt(2)
	v_mfma_f32_16x16x32_bf16 v[222:225], v[132:135], v[208:211], v[108:111]
	v_mfma_f32_16x16x32_bf16 v[104:107], v[136:139], v[204:207], v[104:107]
	s_waitcnt lgkmcnt(1)
	v_mfma_f32_16x16x32_bf16 v[100:103], v[128:131], v[214:217], v[100:103]
	v_mfma_f32_16x16x32_bf16 v[96:99], v[136:139], v[214:217], v[96:99]
	v_mfma_f32_16x16x32_bf16 v[226:229], v[140:143], v[208:211], v[104:107]
	s_waitcnt lgkmcnt(0)
	v_mfma_f32_16x16x32_bf16 v[230:233], v[132:135], v[218:221], v[100:103]
	v_mfma_f32_16x16x32_bf16 v[234:237], v[140:143], v[218:221], v[96:99]
	s_setprio 0
	s_setprio 1
	v_mfma_f32_16x16x32_bf16 v[92:95], v[144:147], v[160:163], v[92:95]
	v_mfma_f32_16x16x32_bf16 v[88:91], v[152:155], v[160:163], v[88:91]
	v_mfma_f32_16x16x32_bf16 v[84:87], v[144:147], v[196:199], v[84:87]
	v_mfma_f32_16x16x32_bf16 v[80:83], v[152:155], v[196:199], v[80:83]
	v_mfma_f32_16x16x32_bf16 v[92:95], v[148:151], v[164:167], v[92:95]
	v_mfma_f32_16x16x32_bf16 v[88:91], v[156:159], v[164:167], v[88:91]
	v_mfma_f32_16x16x32_bf16 v[84:87], v[148:151], v[200:203], v[84:87]
	v_mfma_f32_16x16x32_bf16 v[80:83], v[156:159], v[200:203], v[80:83]
	v_mfma_f32_16x16x32_bf16 v[76:79], v[144:147], v[204:207], v[76:79]
	v_mfma_f32_16x16x32_bf16 v[72:75], v[152:155], v[204:207], v[72:75]
	v_mfma_f32_16x16x32_bf16 v[68:71], v[144:147], v[214:217], v[68:71]
	v_mfma_f32_16x16x32_bf16 v[64:67], v[152:155], v[214:217], v[64:67]
	v_mfma_f32_16x16x32_bf16 v[160:163], v[148:151], v[208:211], v[76:79]
	v_mfma_f32_16x16x32_bf16 v[164:167], v[156:159], v[208:211], v[72:75]
	v_mfma_f32_16x16x32_bf16 v[196:199], v[148:151], v[218:221], v[68:71]
	v_mfma_f32_16x16x32_bf16 v[200:203], v[156:159], v[218:221], v[64:67]
	s_setprio 0
	s_barrier
	s_nop 1
	ds_read_b128 v[64:67], v188 offset:16384
	ds_read_b128 v[68:71], v188 offset:17408
	ds_read_b128 v[72:75], v189 offset:16384
	ds_read_b128 v[76:79], v189 offset:17408
	ds_read_b128 v[96:99], v190 offset:16384
	ds_read_b128 v[100:103], v190 offset:17408
	ds_read_b128 v[104:107], v191 offset:16384
	ds_read_b128 v[108:111], v191 offset:17408
	s_waitcnt vmcnt(2)
	s_waitcnt lgkmcnt(0)
	s_barrier
	s_setprio 1
	s_waitcnt lgkmcnt(7)
	v_mfma_f32_16x16x32_bf16 v[60:63], v[128:131], v[64:67], v[60:63]
	v_mfma_f32_16x16x32_bf16 v[56:59], v[136:139], v[64:67], v[56:59]
	s_waitcnt lgkmcnt(5)
	v_mfma_f32_16x16x32_bf16 v[52:55], v[128:131], v[72:75], v[52:55]
	v_mfma_f32_16x16x32_bf16 v[48:51], v[136:139], v[72:75], v[48:51]
	v_mfma_f32_16x16x32_bf16 v[60:63], v[132:135], v[68:71], v[60:63]
	v_mfma_f32_16x16x32_bf16 v[56:59], v[140:143], v[68:71], v[56:59]
	s_waitcnt lgkmcnt(4)
	v_mfma_f32_16x16x32_bf16 v[52:55], v[132:135], v[76:79], v[52:55]
	v_mfma_f32_16x16x32_bf16 v[48:51], v[140:143], v[76:79], v[48:51]
	s_waitcnt lgkmcnt(3)
	v_mfma_f32_16x16x32_bf16 v[44:47], v[128:131], v[96:99], v[44:47]
	v_mfma_f32_16x16x32_bf16 v[40:43], v[136:139], v[96:99], v[40:43]
	s_waitcnt lgkmcnt(1)
	v_mfma_f32_16x16x32_bf16 v[36:39], v[128:131], v[104:107], v[36:39]
	v_mfma_f32_16x16x32_bf16 v[32:35], v[136:139], v[104:107], v[32:35]
	v_mfma_f32_16x16x32_bf16 v[204:207], v[132:135], v[100:103], v[44:47]
	v_mfma_f32_16x16x32_bf16 v[208:211], v[140:143], v[100:103], v[40:43]
	s_waitcnt lgkmcnt(0)
	v_mfma_f32_16x16x32_bf16 v[128:131], v[132:135], v[108:111], v[36:39]
	v_mfma_f32_16x16x32_bf16 v[132:135], v[140:143], v[108:111], v[32:35]
	s_setprio 0
	s_setprio 1
	v_mfma_f32_16x16x32_bf16 v[28:31], v[144:147], v[64:67], v[28:31]
	v_mfma_f32_16x16x32_bf16 v[24:27], v[152:155], v[64:67], v[24:27]
	v_mfma_f32_16x16x32_bf16 v[20:23], v[144:147], v[72:75], v[20:23]
	v_mfma_f32_16x16x32_bf16 v[16:19], v[152:155], v[72:75], v[16:19]
	v_mfma_f32_16x16x32_bf16 v[28:31], v[148:151], v[68:71], v[28:31]
	v_mfma_f32_16x16x32_bf16 v[24:27], v[156:159], v[68:71], v[24:27]
	v_mfma_f32_16x16x32_bf16 v[20:23], v[148:151], v[76:79], v[20:23]
	v_mfma_f32_16x16x32_bf16 v[16:19], v[156:159], v[76:79], v[16:19]
	v_mfma_f32_16x16x32_bf16 v[12:15], v[144:147], v[96:99], v[12:15]
	v_mfma_f32_16x16x32_bf16 v[8:11], v[152:155], v[96:99], v[8:11]
	v_mfma_f32_16x16x32_bf16 v[4:7], v[144:147], v[104:107], v[4:7]
	v_mfma_f32_16x16x32_bf16 v[0:3], v[152:155], v[104:107], v[0:3]
	v_mfma_f32_16x16x32_bf16 v[136:139], v[148:151], v[100:103], v[12:15]
	v_mfma_f32_16x16x32_bf16 v[140:143], v[156:159], v[100:103], v[8:11]
	v_mfma_f32_16x16x32_bf16 v[144:147], v[148:151], v[108:111], v[4:7]
	v_mfma_f32_16x16x32_bf16 v[148:151], v[156:159], v[108:111], v[0:3]
	s_setprio 0
	s_barrier
; #define LDA(dst, b, h) for (int m = 0; m < 4; ++m) for (int k = 0; k < 2; ++k) \
;     dst[m][k] = *reinterpret_cast<const bf16x8*>((char*)SA(b, h) + lds_byte(wr * 64 + m * 16 + fr, k * 32 + fq * 8))
; #define LDB(dst, b, h) for (int n = 0; n < 2; ++n) for (int k = 0; k < 2; ++k) \
;     dst[n][k] = *reinterpret_cast<const bf16x8*>((char*)SB(b, h) + lds_byte(wc * 32 + n * 16 + fr, k * 32 + fq * 8))
; #define MMA(ai, bj, At, Bt_) do { __builtin_amdgcn_s_setprio(1); \
;     for (int m = 0; m < 4; ++m) for (int n = 0; n < 2; ++n) for (int k = 0; k < 2; ++k) \
;       acc[ai][bj][m][n] = __builtin_amdgcn_mfma_f32_16x16x32_bf16(Bt_[n][k], At[m][k], acc[ai][bj][m][n], 0, 0, 0); \
;     __builtin_amdgcn_s_setprio(0); } while (0)
; #define WAIT_V(n) asm volatile("s_waitcnt vmcnt(" #n ")" ::: "memory")
; #define WAIT_L(n) asm volatile("s_waitcnt lgkmcnt(" #n ")" ::: "memory")
; #define BAR __builtin_amdgcn_s_barrier()
; #define SCHED __builtin_amdgcn_sched_barrier(0)
; template <int MODE>
; DI void gemm_phase(const bf16_t* __restrict__ A, const bf16_t* __restrict__ Bt, int M, int N, int K, const Epi& ep) {
;     ...
;             LDB(B0, 1, 0); LDB(B1, 1, 1); SCHED; LDA(At, 1, 0);
;             WAIT_V(0); WAIT_L(0); BAR; MMA(0, 0, At, B0); MMA(0, 1, At, B1); BAR; SCHED;
;             LDA(At, 1, 1);
;             WAIT_L(0); BAR; MMA(1, 0, At, B0); MMA(1, 1, At, B1); BAR; SCHED;
;         }
;         if (wr == 0) BAR;
	s_nop 1
	ds_read_b128 v[0:3], v192
	ds_read_b128 v[4:7], v192 offset:1024
	ds_read_b128 v[8:11], v192 offset:2048
	ds_read_b128 v[12:15], v192 offset:3072
	ds_read_b128 v[152:155], v193
	ds_read_b128 v[156:159], v193 offset:1024
	ds_read_b128 v[214:217], v193 offset:2048
	ds_read_b128 v[218:221], v193 offset:3072
	ds_read_b128 v[32:35], v188 offset:32768
	ds_read_b128 v[36:39], v188 offset:33792
	ds_read_b128 v[40:43], v189 offset:32768
	ds_read_b128 v[44:47], v189 offset:33792
	ds_read_b128 v[238:241], v190 offset:32768
	ds_read_b128 v[242:245], v190 offset:33792
	ds_read_b128 v[246:249], v191 offset:32768
	ds_read_b128 v[64:67], v191 offset:33792
	s_waitcnt vmcnt(0)
	s_waitcnt lgkmcnt(0)
	s_barrier
	s_setprio 1
	s_waitcnt lgkmcnt(7)
	v_mfma_f32_16x16x32_bf16 v[68:71], v[0:3], v[32:35], v[124:127]
	s_waitcnt lgkmcnt(6)
	v_mfma_f32_16x16x32_bf16 v[96:99], v[4:7], v[36:39], v[68:71]
	v_mfma_f32_16x16x32_bf16 v[68:71], v[8:11], v[32:35], v[120:123]
	v_mfma_f32_16x16x32_bf16 v[100:103], v[12:15], v[36:39], v[68:71]
	s_waitcnt lgkmcnt(5)
	v_mfma_f32_16x16x32_bf16 v[68:71], v[0:3], v[40:43], v[116:119]
	s_waitcnt lgkmcnt(4)
	v_mfma_f32_16x16x32_bf16 v[104:107], v[4:7], v[44:47], v[68:71]
	v_mfma_f32_16x16x32_bf16 v[68:71], v[8:11], v[40:43], v[112:115]
	v_mfma_f32_16x16x32_bf16 v[108:111], v[12:15], v[44:47], v[68:71]
	s_waitcnt lgkmcnt(3)
	v_mfma_f32_16x16x32_bf16 v[68:71], v[0:3], v[238:241], v[222:225]
	s_waitcnt lgkmcnt(2)
	v_mfma_f32_16x16x32_bf16 v[112:115], v[4:7], v[242:245], v[68:71]
	v_mfma_f32_16x16x32_bf16 v[68:71], v[8:11], v[238:241], v[226:229]
	v_mfma_f32_16x16x32_bf16 v[116:119], v[12:15], v[242:245], v[68:71]
	s_waitcnt lgkmcnt(1)
	v_mfma_f32_16x16x32_bf16 v[68:71], v[0:3], v[246:249], v[230:233]
	s_waitcnt lgkmcnt(0)
	v_mfma_f32_16x16x32_bf16 v[120:123], v[4:7], v[64:67], v[68:71]
	v_mfma_f32_16x16x32_bf16 v[68:71], v[8:11], v[246:249], v[234:237]
	v_mfma_f32_16x16x32_bf16 v[124:127], v[12:15], v[64:67], v[68:71]
	s_setprio 0
	s_setprio 1
	v_mfma_f32_16x16x32_bf16 v[68:71], v[152:155], v[32:35], v[92:95]
	v_mfma_f32_16x16x32_bf16 v[32:35], v[214:217], v[32:35], v[88:91]
	v_mfma_f32_16x16x32_bf16 v[222:225], v[156:159], v[36:39], v[68:71]
	v_mfma_f32_16x16x32_bf16 v[68:71], v[218:221], v[36:39], v[32:35]
	v_mfma_f32_16x16x32_bf16 v[32:35], v[152:155], v[40:43], v[84:87]
	v_mfma_f32_16x16x32_bf16 v[72:75], v[156:159], v[44:47], v[32:35]
	v_mfma_f32_16x16x32_bf16 v[32:35], v[214:217], v[40:43], v[80:83]
	v_mfma_f32_16x16x32_bf16 v[76:79], v[218:221], v[44:47], v[32:35]
	v_mfma_f32_16x16x32_bf16 v[32:35], v[152:155], v[238:241], v[160:163]
	v_mfma_f32_16x16x32_bf16 v[80:83], v[156:159], v[242:245], v[32:35]
	v_mfma_f32_16x16x32_bf16 v[32:35], v[214:217], v[238:241], v[164:167]
	v_mfma_f32_16x16x32_bf16 v[84:87], v[218:221], v[242:245], v[32:35]
	v_mfma_f32_16x16x32_bf16 v[32:35], v[152:155], v[246:249], v[196:199]
	v_mfma_f32_16x16x32_bf16 v[88:91], v[156:159], v[64:67], v[32:35]
	v_mfma_f32_16x16x32_bf16 v[32:35], v[214:217], v[246:249], v[200:203]
	v_mfma_f32_16x16x32_bf16 v[92:95], v[218:221], v[64:67], v[32:35]
	s_setprio 0
	s_barrier
	ds_read_b128 v[64:67], v188 offset:49152
	ds_read_b128 v[160:163], v188 offset:50176
	ds_read_b128 v[164:167], v189 offset:49152
	ds_read_b128 v[196:199], v189 offset:50176
	ds_read_b128 v[200:203], v190 offset:49152
	ds_read_b128 v[226:229], v190 offset:50176
	ds_read_b128 v[230:233], v191 offset:49152
	ds_read_b128 v[234:237], v191 offset:50176
	s_waitcnt lgkmcnt(0)
	s_barrier
	s_setprio 1
	s_waitcnt lgkmcnt(7)
	v_mfma_f32_16x16x32_bf16 v[32:35], v[0:3], v[64:67], v[60:63]
	s_waitcnt lgkmcnt(5)
	v_mfma_f32_16x16x32_bf16 v[40:43], v[0:3], v[164:167], v[52:55]
	v_mfma_f32_16x16x32_bf16 v[44:47], v[8:11], v[164:167], v[48:51]
	s_waitcnt lgkmcnt(3)
	v_mfma_f32_16x16x32_bf16 v[48:51], v[0:3], v[200:203], v[204:207]
	s_waitcnt lgkmcnt(1)
	v_mfma_f32_16x16x32_bf16 v[0:3], v[0:3], v[230:233], v[128:131]
	v_mfma_f32_16x16x32_bf16 v[36:39], v[8:11], v[64:67], v[56:59]
	v_mfma_f32_16x16x32_bf16 v[52:55], v[8:11], v[200:203], v[208:211]
	s_waitcnt lgkmcnt(0)
	v_mfma_f32_16x16x32_bf16 v[56:59], v[4:7], v[234:237], v[0:3]
	v_mfma_f32_16x16x32_bf16 v[0:3], v[8:11], v[230:233], v[132:135]
	v_mfma_f32_16x16x32_bf16 v[32:35], v[4:7], v[160:163], v[32:35]
	v_mfma_f32_16x16x32_bf16 v[36:39], v[12:15], v[160:163], v[36:39]
	v_mfma_f32_16x16x32_bf16 v[40:43], v[4:7], v[196:199], v[40:43]
	v_mfma_f32_16x16x32_bf16 v[44:47], v[12:15], v[196:199], v[44:47]
	v_mfma_f32_16x16x32_bf16 v[48:51], v[4:7], v[226:229], v[48:51]
	v_mfma_f32_16x16x32_bf16 v[52:55], v[12:15], v[226:229], v[52:55]
	v_mfma_f32_16x16x32_bf16 v[60:63], v[12:15], v[234:237], v[0:3]
	s_setprio 0
	s_setprio 1
	v_mfma_f32_16x16x32_bf16 v[0:3], v[152:155], v[64:67], v[28:31]
	v_mfma_f32_16x16x32_bf16 v[4:7], v[214:217], v[64:67], v[24:27]
	v_mfma_f32_16x16x32_bf16 v[8:11], v[152:155], v[164:167], v[20:23]
	v_mfma_f32_16x16x32_bf16 v[12:15], v[214:217], v[164:167], v[16:19]
	v_mfma_f32_16x16x32_bf16 v[16:19], v[152:155], v[200:203], v[136:139]
	v_mfma_f32_16x16x32_bf16 v[20:23], v[214:217], v[200:203], v[140:143]
	v_mfma_f32_16x16x32_bf16 v[24:27], v[152:155], v[230:233], v[144:147]
	v_mfma_f32_16x16x32_bf16 v[28:31], v[214:217], v[230:233], v[148:151]
	v_mfma_f32_16x16x32_bf16 v[0:3], v[156:159], v[160:163], v[0:3]
	v_mfma_f32_16x16x32_bf16 v[4:7], v[218:221], v[160:163], v[4:7]
	v_mfma_f32_16x16x32_bf16 v[8:11], v[156:159], v[196:199], v[8:11]
	v_mfma_f32_16x16x32_bf16 v[12:15], v[218:221], v[196:199], v[12:15]
	v_mfma_f32_16x16x32_bf16 v[16:19], v[156:159], v[226:229], v[16:19]
	v_mfma_f32_16x16x32_bf16 v[20:23], v[218:221], v[226:229], v[20:23]
	v_mfma_f32_16x16x32_bf16 v[24:27], v[156:159], v[234:237], v[24:27]
	v_mfma_f32_16x16x32_bf16 v[28:31], v[218:221], v[234:237], v[28:31]
	s_setprio 0
	s_barrier
	s_and_saveexec_b64 s[0:1], s[38:39]
	s_cbranch_execz .LBB0_1153
	s_barrier

; #define LDA(dst, b, h) for (int m = 0; m < 4; ++m) for (int k = 0; k < 2; ++k) \
;     dst[m][k] = *reinterpret_cast<const bf16x8*>((char*)SA(b, h) + lds_byte(wr * 64 + m * 16 + fr, k * 32 + fq * 8))
; #define LDB(dst, b, h) for (int n = 0; n < 2; ++n) for (int k = 0; k < 2; ++k) \
;     dst[n][k] = *reinterpret_cast<const bf16x8*>((char*)SB(b, h) + lds_byte(wc * 32 + n * 16 + fr, k * 32 + fq * 8))
; #define MMA(ai, bj, At, Bt_) do { __builtin_amdgcn_s_setprio(1); \
;     for (int m = 0; m < 4; ++m) for (int n = 0; n < 2; ++n) for (int k = 0; k < 2; ++k) \
;       acc[ai][bj][m][n] = __builtin_amdgcn_mfma_f32_16x16x32_bf16(Bt_[n][k], At[m][k], acc[ai][bj][m][n], 0, 0, 0); \
;     __builtin_amdgcn_s_setprio(0); } while (0)
; #define WAIT_V(n) asm volatile("s_waitcnt vmcnt(" #n ")" ::: "memory")
; #define WAIT_L(n) asm volatile("s_waitcnt lgkmcnt(" #n ")" ::: "memory")
; #define BAR __builtin_amdgcn_s_barrier()
; #define SCHED __builtin_amdgcn_sched_barrier(0)
; template <int MODE>
; DI void gemm_phase(const bf16_t* __restrict__ A, const bf16_t* __restrict__ Bt, int M, int N, int K, const Epi& ep) {
;     ...
;             LDB(B0, 0, 0); LDB(B1, 0, 1); SCHED; LDA(At, 0, 0); STAGE(SA(1, 1), rsA, brow + HALF, t + 1);
;             WAIT_V(8); WAIT_L(0); BAR; MMA(0, 0, At, B0); MMA(0, 1, At, B1); BAR; SCHED;
;             LDA(At, 0, 1); STAGE(SB(0, 0), rsB, bcol, t + 2); STAGE(SB(0, 1), rsB, bcol + HALF, t + 2); STAGE(SA(0, 0), rsA, brow, t + 2);
.LBB0_1452:
	ds_read_b128 v[156:159], v147
	ds_read_b128 v[160:163], v147 offset:1024
	ds_read_b128 v[164:167], v147 offset:2048
	ds_read_b128 v[168:171], v147 offset:3072
	ds_read_b128 v[172:175], v148
	ds_read_b128 v[176:179], v148 offset:1024
	ds_read_b128 v[180:183], v148 offset:2048
	ds_read_b128 v[184:187], v148 offset:3072
	s_add_i32 s40, s6, s27
	v_readfirstlane_b32 s42, v144
	s_add_i32 s41, s40, 0xb0080
	s_mov_b32 s30, s10
	s_mov_b32 s31, s11
	s_mov_b32 m0, s42
	v_readfirstlane_b32 s42, v145
	ds_read_b128 v[188:191], v149
	ds_read_b128 v[192:195], v149 offset:1024
	ds_read_b128 v[196:199], v150
	ds_read_b128 v[200:203], v150 offset:1024
	ds_read_b128 v[204:207], v151
	ds_read_b128 v[208:211], v151 offset:1024
	ds_read_b128 v[214:217], v152
	ds_read_b128 v[218:221], v152 offset:1024
	buffer_load_dwordx4 v128, s[28:31], s41 offen lds
	s_mov_b32 m0, s42
	s_nop 0
	buffer_load_dwordx4 v129, s[28:31], s41 offen lds
	s_waitcnt vmcnt(8)
	s_waitcnt lgkmcnt(0)
	s_barrier
	s_setprio 1
	s_waitcnt lgkmcnt(7)
	v_mfma_f32_16x16x32_bf16 v[124:127], v[156:159], v[188:191], v[124:127]
	v_mfma_f32_16x16x32_bf16 v[120:123], v[164:167], v[188:191], v[120:123]
	s_waitcnt lgkmcnt(5)
	v_mfma_f32_16x16x32_bf16 v[116:119], v[156:159], v[196:199], v[116:119]
	v_mfma_f32_16x16x32_bf16 v[112:115], v[164:167], v[196:199], v[112:115]
	s_waitcnt lgkmcnt(3)
	v_mfma_f32_16x16x32_bf16 v[108:111], v[156:159], v[204:207], v[108:111]
	v_mfma_f32_16x16x32_bf16 v[104:107], v[164:167], v[204:207], v[104:107]
	s_waitcnt lgkmcnt(1)
	v_mfma_f32_16x16x32_bf16 v[100:103], v[156:159], v[214:217], v[100:103]
	v_mfma_f32_16x16x32_bf16 v[96:99], v[164:167], v[214:217], v[96:99]
	v_mfma_f32_16x16x32_bf16 v[124:127], v[160:163], v[192:195], v[124:127]
	v_mfma_f32_16x16x32_bf16 v[120:123], v[168:171], v[192:195], v[120:123]
	v_mfma_f32_16x16x32_bf16 v[116:119], v[160:163], v[200:203], v[116:119]
	v_mfma_f32_16x16x32_bf16 v[112:115], v[168:171], v[200:203], v[112:115]
	v_mfma_f32_16x16x32_bf16 v[108:111], v[160:163], v[208:211], v[108:111]
	v_mfma_f32_16x16x32_bf16 v[104:107], v[168:171], v[208:211], v[104:107]
	s_waitcnt lgkmcnt(0)
	v_mfma_f32_16x16x32_bf16 v[100:103], v[160:163], v[218:221], v[100:103]
	v_mfma_f32_16x16x32_bf16 v[96:99], v[168:171], v[218:221], v[96:99]
	s_setprio 0
	s_setprio 1
	v_mfma_f32_16x16x32_bf16 v[92:95], v[172:175], v[188:191], v[92:95]
	v_mfma_f32_16x16x32_bf16 v[88:91], v[180:183], v[188:191], v[88:91]
	v_mfma_f32_16x16x32_bf16 v[84:87], v[172:175], v[196:199], v[84:87]
	v_mfma_f32_16x16x32_bf16 v[80:83], v[180:183], v[196:199], v[80:83]
	v_mfma_f32_16x16x32_bf16 v[76:79], v[172:175], v[204:207], v[76:79]
	v_mfma_f32_16x16x32_bf16 v[72:75], v[180:183], v[204:207], v[72:75]
	v_mfma_f32_16x16x32_bf16 v[68:71], v[172:175], v[214:217], v[68:71]
	v_mfma_f32_16x16x32_bf16 v[64:67], v[180:183], v[214:217], v[64:67]
	v_mfma_f32_16x16x32_bf16 v[92:95], v[176:179], v[192:195], v[92:95]
	v_mfma_f32_16x16x32_bf16 v[88:91], v[184:187], v[192:195], v[88:91]
	v_mfma_f32_16x16x32_bf16 v[84:87], v[176:179], v[200:203], v[84:87]
	v_mfma_f32_16x16x32_bf16 v[80:83], v[184:187], v[200:203], v[80:83]
	v_mfma_f32_16x16x32_bf16 v[76:79], v[176:179], v[208:211], v[76:79]
	v_mfma_f32_16x16x32_bf16 v[72:75], v[184:187], v[208:211], v[72:75]
	v_mfma_f32_16x16x32_bf16 v[68:71], v[176:179], v[218:221], v[68:71]
	v_mfma_f32_16x16x32_bf16 v[64:67], v[184:187], v[218:221], v[64:67]
	s_setprio 0
	s_barrier
	s_add_i32 s41, s23, s27
	v_readfirstlane_b32 s43, v130
	s_add_i32 s42, s41, 0x100
	s_mov_b32 s70, s10
	s_mov_b32 s71, s11
	s_mov_b32 m0, s43
	v_readfirstlane_b32 s43, v131
	ds_read_b128 v[188:191], v149 offset:16384
	ds_read_b128 v[192:195], v149 offset:17408
	ds_read_b128 v[196:199], v150 offset:16384
	ds_read_b128 v[200:203], v150 offset:17408
	ds_read_b128 v[204:207], v151 offset:16384
	ds_read_b128 v[208:211], v151 offset:17408
	ds_read_b128 v[214:217], v152 offset:16384
	ds_read_b128 v[218:221], v152 offset:17408
	buffer_load_dwordx4 v128, s[68:71], s42 offen lds
	s_mov_b32 m0, s43
	v_readfirstlane_b32 s43, v132
	buffer_load_dwordx4 v129, s[68:71], s42 offen lds
	s_add_i32 s42, s41, 0xb0100
	s_mov_b32 m0, s43
	v_readfirstlane_b32 s43, v133
	buffer_load_dwordx4 v128, s[68:71], s42 offen lds
	s_mov_b32 m0, s43
	v_readfirstlane_b32 s43, v134
	buffer_load_dwordx4 v129, s[68:71], s42 offen lds
	s_add_i32 s42, s40, 0x100
	s_mov_b32 m0, s43
	v_readfirstlane_b32 s43, v135
	buffer_load_dwordx4 v128, s[28:31], s42 offen lds
	s_mov_b32 m0, s43
	s_nop 0
	buffer_load_dwordx4 v129, s[28:31], s42 offen lds
	s_waitcnt vmcnt(8)
	s_waitcnt lgkmcnt(0)
	s_barrier
; #define LDA(dst, b, h) for (int m = 0; m < 4; ++m) for (int k = 0; k < 2; ++k) \
;     dst[m][k] = *reinterpret_cast<const bf16x8*>((char*)SA(b, h) + lds_byte(wr * 64 + m * 16 + fr, k * 32 + fq * 8))
; #define LDB(dst, b, h) for (int n = 0; n < 2; ++n) for (int k = 0; k < 2; ++k) \
;     dst[n][k] = *reinterpret_cast<const bf16x8*>((char*)SB(b, h) + lds_byte(wc * 32 + n * 16 + fr, k * 32 + fq * 8))
; #define MMA(ai, bj, At, Bt_) do { __builtin_amdgcn_s_setprio(1); \
;     for (int m = 0; m < 4; ++m) for (int n = 0; n < 2; ++n) for (int k = 0; k < 2; ++k) \
;       acc[ai][bj][m][n] = __builtin_amdgcn_mfma_f32_16x16x32_bf16(Bt_[n][k], At[m][k], acc[ai][bj][m][n], 0, 0, 0); \
;     __builtin_amdgcn_s_setprio(0); } while (0)
; #define WAIT_V(n) asm volatile("s_waitcnt vmcnt(" #n ")" ::: "memory")
; #define WAIT_L(n) asm volatile("s_waitcnt lgkmcnt(" #n ")" ::: "memory")
; #define BAR __builtin_amdgcn_s_barrier()
; #define SCHED __builtin_amdgcn_sched_barrier(0)
; template <int MODE>
; DI void gemm_phase(const bf16_t* __restrict__ A, const bf16_t* __restrict__ Bt, int M, int N, int K, const Epi& ep) {
;     ...
;             WAIT_V(8); WAIT_L(0); BAR; MMA(1, 0, At, B0); MMA(1, 1, At, B1); BAR; SCHED;
;             LDB(B0, 1, 0); LDB(B1, 1, 1); SCHED; LDA(At, 1, 0); STAGE(SA(0, 1), rsA, brow + HALF, t + 2);
;             WAIT_V(8); WAIT_L(0); BAR; MMA(0, 0, At, B0); MMA(0, 1, At, B1); BAR; SCHED;
	s_setprio 1
	s_waitcnt lgkmcnt(7)
	v_mfma_f32_16x16x32_bf16 v[60:63], v[156:159], v[188:191], v[60:63]
	v_mfma_f32_16x16x32_bf16 v[56:59], v[164:167], v[188:191], v[56:59]
	s_waitcnt lgkmcnt(5)
	v_mfma_f32_16x16x32_bf16 v[52:55], v[156:159], v[196:199], v[52:55]
	v_mfma_f32_16x16x32_bf16 v[48:51], v[164:167], v[196:199], v[48:51]
	s_waitcnt lgkmcnt(3)
	v_mfma_f32_16x16x32_bf16 v[44:47], v[156:159], v[204:207], v[44:47]
	v_mfma_f32_16x16x32_bf16 v[40:43], v[164:167], v[204:207], v[40:43]
	s_waitcnt lgkmcnt(1)
	v_mfma_f32_16x16x32_bf16 v[36:39], v[156:159], v[214:217], v[36:39]
	v_mfma_f32_16x16x32_bf16 v[32:35], v[164:167], v[214:217], v[32:35]
	v_mfma_f32_16x16x32_bf16 v[60:63], v[160:163], v[192:195], v[60:63]
	v_mfma_f32_16x16x32_bf16 v[56:59], v[168:171], v[192:195], v[56:59]
	v_mfma_f32_16x16x32_bf16 v[52:55], v[160:163], v[200:203], v[52:55]
	v_mfma_f32_16x16x32_bf16 v[48:51], v[168:171], v[200:203], v[48:51]
	v_mfma_f32_16x16x32_bf16 v[44:47], v[160:163], v[208:211], v[44:47]
	v_mfma_f32_16x16x32_bf16 v[40:43], v[168:171], v[208:211], v[40:43]
	s_waitcnt lgkmcnt(0)
	v_mfma_f32_16x16x32_bf16 v[36:39], v[160:163], v[218:221], v[36:39]
	v_mfma_f32_16x16x32_bf16 v[32:35], v[168:171], v[218:221], v[32:35]
	s_setprio 0
	s_setprio 1
	v_mfma_f32_16x16x32_bf16 v[28:31], v[172:175], v[188:191], v[28:31]
	v_mfma_f32_16x16x32_bf16 v[24:27], v[180:183], v[188:191], v[24:27]
	v_mfma_f32_16x16x32_bf16 v[20:23], v[172:175], v[196:199], v[20:23]
	v_mfma_f32_16x16x32_bf16 v[16:19], v[180:183], v[196:199], v[16:19]
	v_mfma_f32_16x16x32_bf16 v[12:15], v[172:175], v[204:207], v[12:15]
	v_mfma_f32_16x16x32_bf16 v[8:11], v[180:183], v[204:207], v[8:11]
	v_mfma_f32_16x16x32_bf16 v[4:7], v[172:175], v[214:217], v[4:7]
	v_mfma_f32_16x16x32_bf16 v[0:3], v[180:183], v[214:217], v[0:3]
	v_mfma_f32_16x16x32_bf16 v[28:31], v[176:179], v[192:195], v[28:31]
	v_mfma_f32_16x16x32_bf16 v[24:27], v[184:187], v[192:195], v[24:27]
	v_mfma_f32_16x16x32_bf16 v[20:23], v[176:179], v[200:203], v[20:23]
	v_mfma_f32_16x16x32_bf16 v[16:19], v[184:187], v[200:203], v[16:19]
	v_mfma_f32_16x16x32_bf16 v[12:15], v[176:179], v[208:211], v[12:15]
	v_mfma_f32_16x16x32_bf16 v[8:11], v[184:187], v[208:211], v[8:11]
	v_mfma_f32_16x16x32_bf16 v[4:7], v[176:179], v[218:221], v[4:7]
	v_mfma_f32_16x16x32_bf16 v[0:3], v[184:187], v[218:221], v[0:3]
	s_setprio 0
	s_barrier
	ds_read_b128 v[156:159], v153
	ds_read_b128 v[160:163], v153 offset:1024
	ds_read_b128 v[164:167], v153 offset:2048
	ds_read_b128 v[168:171], v153 offset:3072
	ds_read_b128 v[172:175], v154
	ds_read_b128 v[176:179], v154 offset:1024
	ds_read_b128 v[180:183], v154 offset:2048
	ds_read_b128 v[184:187], v154 offset:3072
	v_readfirstlane_b32 s43, v136
	s_add_i32 s42, s40, 0xb0100
	s_mov_b32 m0, s43
	v_readfirstlane_b32 s43, v137
	ds_read_b128 v[188:191], v149 offset:32768
	ds_read_b128 v[192:195], v149 offset:33792
	ds_read_b128 v[196:199], v150 offset:32768
	ds_read_b128 v[200:203], v150 offset:33792
	ds_read_b128 v[204:207], v151 offset:32768
	ds_read_b128 v[208:211], v151 offset:33792
	ds_read_b128 v[214:217], v152 offset:32768
	ds_read_b128 v[218:221], v152 offset:33792
	buffer_load_dwordx4 v128, s[28:31], s42 offen lds
	s_mov_b32 m0, s43
	s_nop 0
	buffer_load_dwordx4 v129, s[28:31], s42 offen lds
	s_waitcnt vmcnt(8)
	s_waitcnt lgkmcnt(0)
	s_barrier
	s_setprio 1
	s_waitcnt lgkmcnt(7)
	v_mfma_f32_16x16x32_bf16 v[124:127], v[156:159], v[188:191], v[124:127]
	v_mfma_f32_16x16x32_bf16 v[120:123], v[164:167], v[188:191], v[120:123]
	s_waitcnt lgkmcnt(5)
	v_mfma_f32_16x16x32_bf16 v[116:119], v[156:159], v[196:199], v[116:119]
	v_mfma_f32_16x16x32_bf16 v[112:115], v[164:167], v[196:199], v[112:115]
	s_waitcnt lgkmcnt(3)
	v_mfma_f32_16x16x32_bf16 v[108:111], v[156:159], v[204:207], v[108:111]
	v_mfma_f32_16x16x32_bf16 v[104:107], v[164:167], v[204:207], v[104:107]
	s_waitcnt lgkmcnt(1)
	v_mfma_f32_16x16x32_bf16 v[100:103], v[156:159], v[214:217], v[100:103]
	v_mfma_f32_16x16x32_bf16 v[96:99], v[164:167], v[214:217], v[96:99]
	v_mfma_f32_16x16x32_bf16 v[124:127], v[160:163], v[192:195], v[124:127]
	v_mfma_f32_16x16x32_bf16 v[120:123], v[168:171], v[192:195], v[120:123]
	v_mfma_f32_16x16x32_bf16 v[116:119], v[160:163], v[200:203], v[116:119]
	v_mfma_f32_16x16x32_bf16 v[112:115], v[168:171], v[200:203], v[112:115]
	v_mfma_f32_16x16x32_bf16 v[108:111], v[160:163], v[208:211], v[108:111]
	v_mfma_f32_16x16x32_bf16 v[104:107], v[168:171], v[208:211], v[104:107]
	s_waitcnt lgkmcnt(0)
	v_mfma_f32_16x16x32_bf16 v[100:103], v[160:163], v[218:221], v[100:103]
	v_mfma_f32_16x16x32_bf16 v[96:99], v[168:171], v[218:221], v[96:99]
	s_setprio 0
	s_setprio 1
	v_mfma_f32_16x16x32_bf16 v[92:95], v[172:175], v[188:191], v[92:95]
	v_mfma_f32_16x16x32_bf16 v[88:91], v[180:183], v[188:191], v[88:91]
	v_mfma_f32_16x16x32_bf16 v[84:87], v[172:175], v[196:199], v[84:87]
	v_mfma_f32_16x16x32_bf16 v[80:83], v[180:183], v[196:199], v[80:83]
	v_mfma_f32_16x16x32_bf16 v[76:79], v[172:175], v[204:207], v[76:79]
	v_mfma_f32_16x16x32_bf16 v[72:75], v[180:183], v[204:207], v[72:75]
	v_mfma_f32_16x16x32_bf16 v[68:71], v[172:175], v[214:217], v[68:71]
	v_mfma_f32_16x16x32_bf16 v[64:67], v[180:183], v[214:217], v[64:67]
	v_mfma_f32_16x16x32_bf16 v[92:95], v[176:179], v[192:195], v[92:95]
	v_mfma_f32_16x16x32_bf16 v[88:91], v[184:187], v[192:195], v[88:91]
	v_mfma_f32_16x16x32_bf16 v[84:87], v[176:179], v[200:203], v[84:87]
	v_mfma_f32_16x16x32_bf16 v[80:83], v[184:187], v[200:203], v[80:83]
	v_mfma_f32_16x16x32_bf16 v[76:79], v[176:179], v[208:211], v[76:79]
	v_mfma_f32_16x16x32_bf16 v[72:75], v[184:187], v[208:211], v[72:75]
	v_mfma_f32_16x16x32_bf16 v[68:71], v[176:179], v[218:221], v[68:71]
	v_mfma_f32_16x16x32_bf16 v[64:67], v[184:187], v[218:221], v[64:67]
	s_setprio 0
	s_barrier
; #define LDA(dst, b, h) for (int m = 0; m < 4; ++m) for (int k = 0; k < 2; ++k) \
;     dst[m][k] = *reinterpret_cast<const bf16x8*>((char*)SA(b, h) + lds_byte(wr * 64 + m * 16 + fr, k * 32 + fq * 8))
; #define LDB(dst, b, h) for (int n = 0; n < 2; ++n) for (int k = 0; k < 2; ++k) \
;     dst[n][k] = *reinterpret_cast<const bf16x8*>((char*)SB(b, h) + lds_byte(wc * 32 + n * 16 + fr, k * 32 + fq * 8))
; #define MMA(ai, bj, At, Bt_) do { __builtin_amdgcn_s_setprio(1); \
;     for (int m = 0; m < 4; ++m) for (int n = 0; n < 2; ++n) for (int k = 0; k < 2; ++k) \
;       acc[ai][bj][m][n] = __builtin_amdgcn_mfma_f32_16x16x32_bf16(Bt_[n][k], At[m][k], acc[ai][bj][m][n], 0, 0, 0); \
;     __builtin_amdgcn_s_setprio(0); } while (0)
; #define WAIT_V(n) asm volatile("s_waitcnt vmcnt(" #n ")" ::: "memory")
; #define WAIT_L(n) asm volatile("s_waitcnt lgkmcnt(" #n ")" ::: "memory")
; #define BAR __builtin_amdgcn_s_barrier()
; #define SCHED __builtin_amdgcn_sched_barrier(0)
; template <int MODE>
; DI void gemm_phase(const bf16_t* __restrict__ A, const bf16_t* __restrict__ Bt, int M, int N, int K, const Epi& ep) {
;     ...
;             LDA(At, 1, 1); STAGE(SB(1, 0), rsB, bcol, t + 3); STAGE(SB(1, 1), rsB, bcol + HALF, t + 3); STAGE(SA(1, 0), rsA, brow, t + 3);
;             WAIT_V(8); WAIT_L(0); BAR; MMA(1, 0, At, B0); MMA(1, 1, At, B1); BAR; SCHED;
;         }
;         {
;             LDB(B0, 0, 0); LDB(B1, 0, 1); SCHED; LDA(At, 0, 0); STAGE(SA(1, 1), rsA, brow + HALF, nt - 1);
;             WAIT_V(8); WAIT_L(0); BAR; MMA(0, 0, At, B0); MMA(0, 1, At, B1); BAR; SCHED;
	v_readfirstlane_b32 s43, v138
	s_add_i32 s42, s41, 0x180
	s_mov_b32 m0, s43
	v_readfirstlane_b32 s43, v139
	ds_read_b128 v[188:191], v149 offset:49152
	ds_read_b128 v[192:195], v149 offset:50176
	ds_read_b128 v[196:199], v150 offset:49152
	ds_read_b128 v[200:203], v150 offset:50176
	ds_read_b128 v[204:207], v151 offset:49152
	ds_read_b128 v[208:211], v151 offset:50176
	ds_read_b128 v[214:217], v152 offset:49152
	ds_read_b128 v[218:221], v152 offset:50176
	buffer_load_dwordx4 v128, s[68:71], s42 offen lds
	s_mov_b32 m0, s43
	s_add_i32 s41, s41, 0xb0180
	buffer_load_dwordx4 v129, s[68:71], s42 offen lds
	v_readfirstlane_b32 s42, v142
	s_mov_b32 m0, s42
	v_readfirstlane_b32 s42, v143
	buffer_load_dwordx4 v128, s[68:71], s41 offen lds
	s_mov_b32 m0, s42
	s_addk_i32 s40, 0x180
	buffer_load_dwordx4 v129, s[68:71], s41 offen lds
	v_readfirstlane_b32 s41, v140
	s_mov_b32 m0, s41
	v_readfirstlane_b32 s41, v141
	buffer_load_dwordx4 v128, s[28:31], s40 offen lds
	s_mov_b32 m0, s41
	s_nop 0
	buffer_load_dwordx4 v129, s[28:31], s40 offen lds
	s_waitcnt vmcnt(8)
	s_waitcnt lgkmcnt(0)
	s_barrier
	s_setprio 1
	s_waitcnt lgkmcnt(7)
	v_mfma_f32_16x16x32_bf16 v[60:63], v[156:159], v[188:191], v[60:63]
	v_mfma_f32_16x16x32_bf16 v[56:59], v[164:167], v[188:191], v[56:59]
	s_waitcnt lgkmcnt(5)
	v_mfma_f32_16x16x32_bf16 v[52:55], v[156:159], v[196:199], v[52:55]
	v_mfma_f32_16x16x32_bf16 v[48:51], v[164:167], v[196:199], v[48:51]
	s_waitcnt lgkmcnt(3)
	v_mfma_f32_16x16x32_bf16 v[44:47], v[156:159], v[204:207], v[44:47]
	v_mfma_f32_16x16x32_bf16 v[40:43], v[164:167], v[204:207], v[40:43]
	s_waitcnt lgkmcnt(1)
	v_mfma_f32_16x16x32_bf16 v[36:39], v[156:159], v[214:217], v[36:39]
	v_mfma_f32_16x16x32_bf16 v[32:35], v[164:167], v[214:217], v[32:35]
	v_mfma_f32_16x16x32_bf16 v[60:63], v[160:163], v[192:195], v[60:63]
	v_mfma_f32_16x16x32_bf16 v[56:59], v[168:171], v[192:195], v[56:59]
	v_mfma_f32_16x16x32_bf16 v[52:55], v[160:163], v[200:203], v[52:55]
	v_mfma_f32_16x16x32_bf16 v[48:51], v[168:171], v[200:203], v[48:51]
	v_mfma_f32_16x16x32_bf16 v[44:47], v[160:163], v[208:211], v[44:47]
	v_mfma_f32_16x16x32_bf16 v[40:43], v[168:171], v[208:211], v[40:43]
	s_waitcnt lgkmcnt(0)
	v_mfma_f32_16x16x32_bf16 v[36:39], v[160:163], v[218:221], v[36:39]
	v_mfma_f32_16x16x32_bf16 v[32:35], v[168:171], v[218:221], v[32:35]
	s_setprio 0
	s_setprio 1
	v_mfma_f32_16x16x32_bf16 v[28:31], v[172:175], v[188:191], v[28:31]
	v_mfma_f32_16x16x32_bf16 v[24:27], v[180:183], v[188:191], v[24:27]
	v_mfma_f32_16x16x32_bf16 v[20:23], v[172:175], v[196:199], v[20:23]
	v_mfma_f32_16x16x32_bf16 v[16:19], v[180:183], v[196:199], v[16:19]
	v_mfma_f32_16x16x32_bf16 v[12:15], v[172:175], v[204:207], v[12:15]
	v_mfma_f32_16x16x32_bf16 v[8:11], v[180:183], v[204:207], v[8:11]
	v_mfma_f32_16x16x32_bf16 v[4:7], v[172:175], v[214:217], v[4:7]
	v_mfma_f32_16x16x32_bf16 v[0:3], v[180:183], v[214:217], v[0:3]
	v_mfma_f32_16x16x32_bf16 v[28:31], v[176:179], v[192:195], v[28:31]
	v_mfma_f32_16x16x32_bf16 v[24:27], v[184:187], v[192:195], v[24:27]
	v_mfma_f32_16x16x32_bf16 v[20:23], v[176:179], v[200:203], v[20:23]
	v_mfma_f32_16x16x32_bf16 v[16:19], v[184:187], v[200:203], v[16:19]
	v_mfma_f32_16x16x32_bf16 v[12:15], v[176:179], v[208:211], v[12:15]
	v_mfma_f32_16x16x32_bf16 v[8:11], v[184:187], v[208:211], v[8:11]
	v_mfma_f32_16x16x32_bf16 v[4:7], v[176:179], v[218:221], v[4:7]
	v_mfma_f32_16x16x32_bf16 v[0:3], v[184:187], v[218:221], v[0:3]
	s_add_i32 s7, s7, 2
	s_addk_i32 s27, 0x100
	s_cmp_gt_u32 s7, 39
	s_setprio 0
	s_barrier
	s_cbranch_scc0 .LBB0_1452
	ds_read_b128 v[156:159], v147
	ds_read_b128 v[160:163], v147 offset:1024
	ds_read_b128 v[164:167], v147 offset:2048
	ds_read_b128 v[168:171], v147 offset:3072
	ds_read_b128 v[172:175], v148
	ds_read_b128 v[176:179], v148 offset:1024
	ds_read_b128 v[180:183], v148 offset:2048
	ds_read_b128 v[184:187], v148 offset:3072
	v_readfirstlane_b32 s7, v144
	s_or_b32 s6, s26, 0x1580
	s_mov_b32 m0, s7
	v_readfirstlane_b32 s7, v145
	ds_read_b128 v[188:191], v149
	ds_read_b128 v[192:195], v149 offset:1024
	ds_read_b128 v[196:199], v150
	ds_read_b128 v[200:203], v150 offset:1024
	ds_read_b128 v[204:207], v151
	ds_read_b128 v[208:211], v151 offset:1024
	ds_read_b128 v[214:217], v152
	ds_read_b128 v[218:221], v152 offset:1024
	buffer_load_dwordx4 v128, s[28:31], s6 offen lds
	s_mov_b32 m0, s7
	s_nop 0
	buffer_load_dwordx4 v129, s[28:31], s6 offen lds
	s_waitcnt vmcnt(8)
	s_waitcnt lgkmcnt(0)
	s_barrier
; #define LDA(dst, b, h) for (int m = 0; m < 4; ++m) for (int k = 0; k < 2; ++k) \
;     dst[m][k] = *reinterpret_cast<const bf16x8*>((char*)SA(b, h) + lds_byte(wr * 64 + m * 16 + fr, k * 32 + fq * 8))
; #define MMA(ai, bj, At, Bt_) do { __builtin_amdgcn_s_setprio(1); \
;     for (int m = 0; m < 4; ++m) for (int n = 0; n < 2; ++n) for (int k = 0; k < 2; ++k) \
;       acc[ai][bj][m][n] = __builtin_amdgcn_mfma_f32_16x16x32_bf16(Bt_[n][k], At[m][k], acc[ai][bj][m][n], 0, 0, 0); \
;     __builtin_amdgcn_s_setprio(0); } while (0)
; #define WAIT_V(n) asm volatile("s_waitcnt vmcnt(" #n ")" ::: "memory")
; #define WAIT_L(n) asm volatile("s_waitcnt lgkmcnt(" #n ")" ::: "memory")
; #define BAR __builtin_amdgcn_s_barrier()
; #define SCHED __builtin_amdgcn_sched_barrier(0)
; template <int MODE>
; DI void gemm_phase(const bf16_t* __restrict__ A, const bf16_t* __restrict__ Bt, int M, int N, int K, const Epi& ep) {
;     ...
;             WAIT_V(8); WAIT_L(0); BAR; MMA(0, 0, At, B0); MMA(0, 1, At, B1); BAR; SCHED;
;             LDA(At, 0, 1);
;             WAIT_V(2); WAIT_L(0); BAR; MMA(1, 0, At, B0); MMA(1, 1, At, B1); BAR; SCHED;
	s_setprio 1
	s_waitcnt lgkmcnt(7)
	v_mfma_f32_16x16x32_bf16 v[124:127], v[156:159], v[188:191], v[124:127]
	v_mfma_f32_16x16x32_bf16 v[120:123], v[164:167], v[188:191], v[120:123]
	s_waitcnt lgkmcnt(5)
	v_mfma_f32_16x16x32_bf16 v[116:119], v[156:159], v[196:199], v[116:119]
	v_mfma_f32_16x16x32_bf16 v[112:115], v[164:167], v[196:199], v[112:115]
	s_waitcnt lgkmcnt(3)
	v_mfma_f32_16x16x32_bf16 v[108:111], v[156:159], v[204:207], v[108:111]
	v_mfma_f32_16x16x32_bf16 v[124:127], v[160:163], v[192:195], v[124:127]
	v_mfma_f32_16x16x32_bf16 v[120:123], v[168:171], v[192:195], v[120:123]
	v_mfma_f32_16x16x32_bf16 v[116:119], v[160:163], v[200:203], v[116:119]
	v_mfma_f32_16x16x32_bf16 v[112:115], v[168:171], v[200:203], v[112:115]
	s_waitcnt lgkmcnt(2)
	v_mfma_f32_16x16x32_bf16 v[222:225], v[160:163], v[208:211], v[108:111]
	v_mfma_f32_16x16x32_bf16 v[104:107], v[164:167], v[204:207], v[104:107]
	s_waitcnt lgkmcnt(1)
	v_mfma_f32_16x16x32_bf16 v[100:103], v[156:159], v[214:217], v[100:103]
	v_mfma_f32_16x16x32_bf16 v[96:99], v[164:167], v[214:217], v[96:99]
	v_mfma_f32_16x16x32_bf16 v[226:229], v[168:171], v[208:211], v[104:107]
	s_waitcnt lgkmcnt(0)
	v_mfma_f32_16x16x32_bf16 v[230:233], v[160:163], v[218:221], v[100:103]
	v_mfma_f32_16x16x32_bf16 v[234:237], v[168:171], v[218:221], v[96:99]
	s_setprio 0
	s_setprio 1
	v_mfma_f32_16x16x32_bf16 v[92:95], v[172:175], v[188:191], v[92:95]
	v_mfma_f32_16x16x32_bf16 v[88:91], v[180:183], v[188:191], v[88:91]
	v_mfma_f32_16x16x32_bf16 v[84:87], v[172:175], v[196:199], v[84:87]
	v_mfma_f32_16x16x32_bf16 v[80:83], v[180:183], v[196:199], v[80:83]
	v_mfma_f32_16x16x32_bf16 v[92:95], v[176:179], v[192:195], v[92:95]
	v_mfma_f32_16x16x32_bf16 v[88:91], v[184:187], v[192:195], v[88:91]
	v_mfma_f32_16x16x32_bf16 v[84:87], v[176:179], v[200:203], v[84:87]
	v_mfma_f32_16x16x32_bf16 v[80:83], v[184:187], v[200:203], v[80:83]
	v_mfma_f32_16x16x32_bf16 v[76:79], v[172:175], v[204:207], v[76:79]
	v_mfma_f32_16x16x32_bf16 v[72:75], v[180:183], v[204:207], v[72:75]
	v_mfma_f32_16x16x32_bf16 v[68:71], v[172:175], v[214:217], v[68:71]
	v_mfma_f32_16x16x32_bf16 v[64:67], v[180:183], v[214:217], v[64:67]
	v_mfma_f32_16x16x32_bf16 v[188:191], v[176:179], v[208:211], v[76:79]
	v_mfma_f32_16x16x32_bf16 v[192:195], v[184:187], v[208:211], v[72:75]
	v_mfma_f32_16x16x32_bf16 v[196:199], v[176:179], v[218:221], v[68:71]
	v_mfma_f32_16x16x32_bf16 v[200:203], v[184:187], v[218:221], v[64:67]
	s_setprio 0
	s_barrier
	s_nop 1
	ds_read_b128 v[64:67], v149 offset:16384
	ds_read_b128 v[68:71], v149 offset:17408
	ds_read_b128 v[72:75], v150 offset:16384
	ds_read_b128 v[76:79], v150 offset:17408
	ds_read_b128 v[96:99], v151 offset:16384
	ds_read_b128 v[100:103], v151 offset:17408
	ds_read_b128 v[104:107], v152 offset:16384
	ds_read_b128 v[108:111], v152 offset:17408
	s_waitcnt vmcnt(2)
	s_waitcnt lgkmcnt(0)
	s_barrier
	s_setprio 1
	s_waitcnt lgkmcnt(7)
	v_mfma_f32_16x16x32_bf16 v[60:63], v[156:159], v[64:67], v[60:63]
	v_mfma_f32_16x16x32_bf16 v[56:59], v[164:167], v[64:67], v[56:59]
	s_waitcnt lgkmcnt(5)
	v_mfma_f32_16x16x32_bf16 v[52:55], v[156:159], v[72:75], v[52:55]
	v_mfma_f32_16x16x32_bf16 v[48:51], v[164:167], v[72:75], v[48:51]
	v_mfma_f32_16x16x32_bf16 v[60:63], v[160:163], v[68:71], v[60:63]
	v_mfma_f32_16x16x32_bf16 v[56:59], v[168:171], v[68:71], v[56:59]
	s_waitcnt lgkmcnt(4)
	v_mfma_f32_16x16x32_bf16 v[52:55], v[160:163], v[76:79], v[52:55]
	v_mfma_f32_16x16x32_bf16 v[48:51], v[168:171], v[76:79], v[48:51]
	s_waitcnt lgkmcnt(3)
	v_mfma_f32_16x16x32_bf16 v[44:47], v[156:159], v[96:99], v[44:47]
	v_mfma_f32_16x16x32_bf16 v[40:43], v[164:167], v[96:99], v[40:43]
	s_waitcnt lgkmcnt(1)
	v_mfma_f32_16x16x32_bf16 v[36:39], v[156:159], v[104:107], v[36:39]
	v_mfma_f32_16x16x32_bf16 v[32:35], v[164:167], v[104:107], v[32:35]
	v_mfma_f32_16x16x32_bf16 v[204:207], v[160:163], v[100:103], v[44:47]
	v_mfma_f32_16x16x32_bf16 v[208:211], v[168:171], v[100:103], v[40:43]
	s_waitcnt lgkmcnt(0)
	v_mfma_f32_16x16x32_bf16 v[156:159], v[160:163], v[108:111], v[36:39]
	v_mfma_f32_16x16x32_bf16 v[160:163], v[168:171], v[108:111], v[32:35]
	s_setprio 0
	s_setprio 1
	v_mfma_f32_16x16x32_bf16 v[28:31], v[172:175], v[64:67], v[28:31]
	v_mfma_f32_16x16x32_bf16 v[24:27], v[180:183], v[64:67], v[24:27]
	v_mfma_f32_16x16x32_bf16 v[20:23], v[172:175], v[72:75], v[20:23]
	v_mfma_f32_16x16x32_bf16 v[16:19], v[180:183], v[72:75], v[16:19]
	v_mfma_f32_16x16x32_bf16 v[28:31], v[176:179], v[68:71], v[28:31]
	v_mfma_f32_16x16x32_bf16 v[24:27], v[184:187], v[68:71], v[24:27]
	v_mfma_f32_16x16x32_bf16 v[20:23], v[176:179], v[76:79], v[20:23]
	v_mfma_f32_16x16x32_bf16 v[16:19], v[184:187], v[76:79], v[16:19]
	v_mfma_f32_16x16x32_bf16 v[12:15], v[172:175], v[96:99], v[12:15]
	v_mfma_f32_16x16x32_bf16 v[8:11], v[180:183], v[96:99], v[8:11]
	v_mfma_f32_16x16x32_bf16 v[4:7], v[172:175], v[104:107], v[4:7]
	v_mfma_f32_16x16x32_bf16 v[0:3], v[180:183], v[104:107], v[0:3]
	v_mfma_f32_16x16x32_bf16 v[164:167], v[176:179], v[100:103], v[12:15]
	v_mfma_f32_16x16x32_bf16 v[168:171], v[184:187], v[100:103], v[8:11]
	v_mfma_f32_16x16x32_bf16 v[172:175], v[176:179], v[108:111], v[4:7]
	v_mfma_f32_16x16x32_bf16 v[176:179], v[184:187], v[108:111], v[0:3]
	s_setprio 0
	s_barrier
; #define LDA(dst, b, h) for (int m = 0; m < 4; ++m) for (int k = 0; k < 2; ++k) \
;     dst[m][k] = *reinterpret_cast<const bf16x8*>((char*)SA(b, h) + lds_byte(wr * 64 + m * 16 + fr, k * 32 + fq * 8))
; #define LDB(dst, b, h) for (int n = 0; n < 2; ++n) for (int k = 0; k < 2; ++k) \
;     dst[n][k] = *reinterpret_cast<const bf16x8*>((char*)SB(b, h) + lds_byte(wc * 32 + n * 16 + fr, k * 32 + fq * 8))
; #define MMA(ai, bj, At, Bt_) do { __builtin_amdgcn_s_setprio(1); \
;     for (int m = 0; m < 4; ++m) for (int n = 0; n < 2; ++n) for (int k = 0; k < 2; ++k) \
;       acc[ai][bj][m][n] = __builtin_amdgcn_mfma_f32_16x16x32_bf16(Bt_[n][k], At[m][k], acc[ai][bj][m][n], 0, 0, 0); \
;     __builtin_amdgcn_s_setprio(0); } while (0)
; #define WAIT_V(n) asm volatile("s_waitcnt vmcnt(" #n ")" ::: "memory")
; #define WAIT_L(n) asm volatile("s_waitcnt lgkmcnt(" #n ")" ::: "memory")
; #define BAR __builtin_amdgcn_s_barrier()
; #define SCHED __builtin_amdgcn_sched_barrier(0)
; template <int MODE>
; DI void gemm_phase(const bf16_t* __restrict__ A, const bf16_t* __restrict__ Bt, int M, int N, int K, const Epi& ep) {
;     ...
;             LDB(B0, 1, 0); LDB(B1, 1, 1); SCHED; LDA(At, 1, 0);
;             WAIT_V(0); WAIT_L(0); BAR; MMA(0, 0, At, B0); MMA(0, 1, At, B1); BAR; SCHED;
;             LDA(At, 1, 1);
;             WAIT_L(0); BAR; MMA(1, 0, At, B0); MMA(1, 1, At, B1); BAR; SCHED;
;         }
;         if (wr == 0) BAR;
	s_nop 1
	ds_read_b128 v[0:3], v153
	ds_read_b128 v[4:7], v153 offset:1024
	ds_read_b128 v[8:11], v153 offset:2048
	ds_read_b128 v[12:15], v153 offset:3072
	ds_read_b128 v[180:183], v154
	ds_read_b128 v[184:187], v154 offset:1024
	ds_read_b128 v[214:217], v154 offset:2048
	ds_read_b128 v[218:221], v154 offset:3072
	ds_read_b128 v[32:35], v149 offset:32768
	ds_read_b128 v[36:39], v149 offset:33792
	ds_read_b128 v[40:43], v150 offset:32768
	ds_read_b128 v[44:47], v150 offset:33792
	ds_read_b128 v[238:241], v151 offset:32768
	ds_read_b128 v[242:245], v151 offset:33792
	ds_read_b128 v[246:249], v152 offset:32768
	ds_read_b128 v[64:67], v152 offset:33792
	s_waitcnt vmcnt(0)
	s_waitcnt lgkmcnt(0)
	s_barrier
	s_setprio 1
	s_waitcnt lgkmcnt(7)
	v_mfma_f32_16x16x32_bf16 v[68:71], v[0:3], v[32:35], v[124:127]
	s_waitcnt lgkmcnt(6)
	v_mfma_f32_16x16x32_bf16 v[96:99], v[4:7], v[36:39], v[68:71]
	v_mfma_f32_16x16x32_bf16 v[68:71], v[8:11], v[32:35], v[120:123]
	v_mfma_f32_16x16x32_bf16 v[100:103], v[12:15], v[36:39], v[68:71]
	s_waitcnt lgkmcnt(5)
	v_mfma_f32_16x16x32_bf16 v[68:71], v[0:3], v[40:43], v[116:119]
	s_waitcnt lgkmcnt(4)
	v_mfma_f32_16x16x32_bf16 v[104:107], v[4:7], v[44:47], v[68:71]
	v_mfma_f32_16x16x32_bf16 v[68:71], v[8:11], v[40:43], v[112:115]
	v_mfma_f32_16x16x32_bf16 v[108:111], v[12:15], v[44:47], v[68:71]
	s_waitcnt lgkmcnt(3)
	v_mfma_f32_16x16x32_bf16 v[68:71], v[0:3], v[238:241], v[222:225]
	s_waitcnt lgkmcnt(2)
	v_mfma_f32_16x16x32_bf16 v[112:115], v[4:7], v[242:245], v[68:71]
	v_mfma_f32_16x16x32_bf16 v[68:71], v[8:11], v[238:241], v[226:229]
	v_mfma_f32_16x16x32_bf16 v[116:119], v[12:15], v[242:245], v[68:71]
	s_waitcnt lgkmcnt(1)
	v_mfma_f32_16x16x32_bf16 v[68:71], v[0:3], v[246:249], v[230:233]
	s_waitcnt lgkmcnt(0)
	v_mfma_f32_16x16x32_bf16 v[120:123], v[4:7], v[64:67], v[68:71]
	v_mfma_f32_16x16x32_bf16 v[68:71], v[8:11], v[246:249], v[234:237]
	v_mfma_f32_16x16x32_bf16 v[124:127], v[12:15], v[64:67], v[68:71]
	s_setprio 0
	s_setprio 1
	v_mfma_f32_16x16x32_bf16 v[68:71], v[180:183], v[32:35], v[92:95]
	v_mfma_f32_16x16x32_bf16 v[32:35], v[214:217], v[32:35], v[88:91]
	v_mfma_f32_16x16x32_bf16 v[222:225], v[184:187], v[36:39], v[68:71]
	v_mfma_f32_16x16x32_bf16 v[68:71], v[218:221], v[36:39], v[32:35]
	v_mfma_f32_16x16x32_bf16 v[32:35], v[180:183], v[40:43], v[84:87]
	v_mfma_f32_16x16x32_bf16 v[72:75], v[184:187], v[44:47], v[32:35]
	v_mfma_f32_16x16x32_bf16 v[32:35], v[214:217], v[40:43], v[80:83]
	v_mfma_f32_16x16x32_bf16 v[76:79], v[218:221], v[44:47], v[32:35]
	v_mfma_f32_16x16x32_bf16 v[32:35], v[180:183], v[238:241], v[188:191]
	v_mfma_f32_16x16x32_bf16 v[80:83], v[184:187], v[242:245], v[32:35]
	v_mfma_f32_16x16x32_bf16 v[32:35], v[214:217], v[238:241], v[192:195]
	v_mfma_f32_16x16x32_bf16 v[84:87], v[218:221], v[242:245], v[32:35]
	v_mfma_f32_16x16x32_bf16 v[32:35], v[180:183], v[246:249], v[196:199]
	v_mfma_f32_16x16x32_bf16 v[88:91], v[184:187], v[64:67], v[32:35]
	v_mfma_f32_16x16x32_bf16 v[32:35], v[214:217], v[246:249], v[200:203]
	v_mfma_f32_16x16x32_bf16 v[92:95], v[218:221], v[64:67], v[32:35]
	s_setprio 0
	s_barrier
	ds_read_b128 v[64:67], v149 offset:49152
	ds_read_b128 v[188:191], v149 offset:50176
	ds_read_b128 v[192:195], v150 offset:49152
	ds_read_b128 v[196:199], v150 offset:50176
	ds_read_b128 v[200:203], v151 offset:49152
	ds_read_b128 v[226:229], v151 offset:50176
	ds_read_b128 v[230:233], v152 offset:49152
	ds_read_b128 v[234:237], v152 offset:50176
	s_waitcnt lgkmcnt(0)
	s_barrier
	s_setprio 1
	s_waitcnt lgkmcnt(7)
	v_mfma_f32_16x16x32_bf16 v[32:35], v[0:3], v[64:67], v[60:63]
	s_waitcnt lgkmcnt(5)
	v_mfma_f32_16x16x32_bf16 v[40:43], v[0:3], v[192:195], v[52:55]
	v_mfma_f32_16x16x32_bf16 v[44:47], v[8:11], v[192:195], v[48:51]
	s_waitcnt lgkmcnt(3)
	v_mfma_f32_16x16x32_bf16 v[48:51], v[0:3], v[200:203], v[204:207]
	s_waitcnt lgkmcnt(1)
	v_mfma_f32_16x16x32_bf16 v[0:3], v[0:3], v[230:233], v[156:159]
	v_mfma_f32_16x16x32_bf16 v[36:39], v[8:11], v[64:67], v[56:59]
	v_mfma_f32_16x16x32_bf16 v[52:55], v[8:11], v[200:203], v[208:211]
	s_waitcnt lgkmcnt(0)
	v_mfma_f32_16x16x32_bf16 v[56:59], v[4:7], v[234:237], v[0:3]
	v_mfma_f32_16x16x32_bf16 v[0:3], v[8:11], v[230:233], v[160:163]
	v_mfma_f32_16x16x32_bf16 v[32:35], v[4:7], v[188:191], v[32:35]
	v_mfma_f32_16x16x32_bf16 v[36:39], v[12:15], v[188:191], v[36:39]
	v_mfma_f32_16x16x32_bf16 v[40:43], v[4:7], v[196:199], v[40:43]
	v_mfma_f32_16x16x32_bf16 v[44:47], v[12:15], v[196:199], v[44:47]
	v_mfma_f32_16x16x32_bf16 v[48:51], v[4:7], v[226:229], v[48:51]
	v_mfma_f32_16x16x32_bf16 v[52:55], v[12:15], v[226:229], v[52:55]
	v_mfma_f32_16x16x32_bf16 v[60:63], v[12:15], v[234:237], v[0:3]
	s_setprio 0
	s_setprio 1
	v_mfma_f32_16x16x32_bf16 v[0:3], v[180:183], v[64:67], v[28:31]
	v_mfma_f32_16x16x32_bf16 v[4:7], v[214:217], v[64:67], v[24:27]
	v_mfma_f32_16x16x32_bf16 v[8:11], v[180:183], v[192:195], v[20:23]
	v_mfma_f32_16x16x32_bf16 v[12:15], v[214:217], v[192:195], v[16:19]
	v_mfma_f32_16x16x32_bf16 v[16:19], v[180:183], v[200:203], v[164:167]
	v_mfma_f32_16x16x32_bf16 v[20:23], v[214:217], v[200:203], v[168:171]
	v_mfma_f32_16x16x32_bf16 v[24:27], v[180:183], v[230:233], v[172:175]
	v_mfma_f32_16x16x32_bf16 v[28:31], v[214:217], v[230:233], v[176:179]
	v_mfma_f32_16x16x32_bf16 v[0:3], v[184:187], v[188:191], v[0:3]
	v_mfma_f32_16x16x32_bf16 v[4:7], v[218:221], v[188:191], v[4:7]
	v_mfma_f32_16x16x32_bf16 v[8:11], v[184:187], v[196:199], v[8:11]
	v_mfma_f32_16x16x32_bf16 v[12:15], v[218:221], v[196:199], v[12:15]
	v_mfma_f32_16x16x32_bf16 v[16:19], v[184:187], v[226:229], v[16:19]
	v_mfma_f32_16x16x32_bf16 v[20:23], v[218:221], v[226:229], v[20:23]
	v_mfma_f32_16x16x32_bf16 v[24:27], v[184:187], v[234:237], v[24:27]
	v_mfma_f32_16x16x32_bf16 v[28:31], v[218:221], v[234:237], v[28:31]
	s_setprio 0
	s_barrier
	s_and_saveexec_b64 s[6:7], s[38:39]
	s_cbranch_execz .LBB0_1444
	s_barrier
	s_branch .LBB0_1444
